# GEMM K-loops: loop counter / pointer SALU and exit compare hoisted above the loop-back barrier (only the branch stays behind it), all 8 instances
# speedup vs baseline: 1.0102x; 1.0020x over previous
; #define PG8_STAGE(bufoff, gbase, voff) do { _Pragma("unroll") for (int _i = 0; _i < 2; ++_i) \
;         __builtin_amdgcn_global_load_lds((const unsigned*)((const char*)(gbase) + (voff)[_i]), (PG8_LAS unsigned*)(lds + (bufoff) + ldsw + _i * 8192), 16, 0, 0); } while (0)
; #define PG8_LDA(dst, b, h) do { _Pragma("unroll") for (int m = 0; m < 4; ++m) _Pragma("unroll") for (int k = 0; k < 2; ++k) dst[m][k] = *(const PG8_LAS bf16x8*)(lds + PG8_SA(b, h) + aoff + m * 2048 + k * 1024); } while (0)
; #define PG8_LDB(dst, b, h) do { _Pragma("unroll") for (int n = 0; n < 2; ++n) _Pragma("unroll") for (int k = 0; k < 2; ++k) dst[n][k] = *(const PG8_LAS bf16x8*)(lds + PG8_SB(b, h) + boff + n * 2048 + k * 1024); } while (0)
; #define PG8_MMA(ai, bj, At, Bt) do { __builtin_amdgcn_s_setprio(1); _Pragma("unroll") for (int m = 0; m < 4; ++m) _Pragma("unroll") for (int n = 0; n < 2; ++n) _Pragma("unroll") for (int k = 0; k < 2; ++k) \
;         acc[ai][bj][m][n] = __builtin_amdgcn_mfma_f32_16x16x32_bf16(Bt[n][k], At[m][k], acc[ai][bj][m][n], 0, 0, 0); __builtin_amdgcn_s_setprio(0); } while (0)
; #define PG8_WAIT_V(n) asm volatile("s_waitcnt vmcnt(" #n ")" ::: "memory")
; #define PG8_BAR __builtin_amdgcn_s_barrier()
; template <class Epi, class Sched, bool ALIGN_EPI = false, bool SP2 = false>
; __device__ __forceinline__ void gemm_phase(PG8_LAS unsigned char* lds, const Gemm g, const Sched& S, const Epi& E, int wave_s) {
;     ...
;         for (int t = 0; t < nt; t += 2) {
;             const bool last = (t == nt - 2);
;             const char* a1 = cA + (size_t)(t + 1) * kstep;
;             const char* a2 = last ? nA : cA + (size_t)(t + 2) * kstep; const char* b2 = last ? nB : cB + (size_t)(t + 2) * kstep;
;             const char* a3 = a2 + kstep; const char* b3 = b2 + kstep;
;             if (last && has_next) S.a_ready(nxt);
;             if constexpr (SP2) {
;             PG8_LDB(B0, 0, 0); PG8_LDB(B1, 0, 1); PG8_SCHED; PG8_LDA(At, 0, 0); PG8_STAGE(PG8_SA(1, 1), a1 + hstep, voffA);
;             PG8_WAIT_V(8); PG8_WAIT_L(0); PG8_BAR; PG8_MMA(0, 0, At, B0); PG8_MMA(0, 1, At, B1); PG8_BAR; PG8_SCHED;
;             PG8_LDA(At, 0, 1); PG8_STAGE(PG8_SB(0, 0), b2, voffB); PG8_STAGE(PG8_SB(0, 1), b2 + hstep, voffB); PG8_STAGE(PG8_SA(0, 0), a2, voffA);
;             PG8_WAIT_V(8); PG8_WAIT_L(0); PG8_BAR; PG8_MMA(1, 0, At, B0); PG8_MMA(1, 1, At, B1); PG8_BAR; PG8_SCHED;
.LBB0_160:
	ds_read_b128 v[128:131], v193
	ds_read_b128 v[132:135], v193 offset:1024
	ds_read_b128 v[164:167], v193 offset:2048
	ds_read_b128 v[168:171], v193 offset:3072
	ds_read_b128 v[198:201], v194
	ds_read_b128 v[202:205], v194 offset:1024
	ds_read_b128 v[206:209], v194 offset:2048
	ds_read_b128 v[210:213], v194 offset:3072
	s_add_u32 s34, s10, 0xfff80080
	s_addc_u32 s35, s11, -1
	s_cmp_eq_u32 s37, 28
	s_cselect_b32 vcc_hi, s5, s35
	s_cselect_b32 vcc_lo, s12, s34
	s_cselect_b32 s35, s9, s36
	s_cselect_b32 s34, s39, s91
	v_lshl_add_u64 v[172:173], s[10:11], 0, v[154:155]
	s_add_i32 m0, s20, 0xc000
	ds_read_b128 v[214:217], v195
	ds_read_b128 v[218:221], v195 offset:1024
	ds_read_b128 v[222:225], v195 offset:2048
	ds_read_b128 v[226:229], v195 offset:3072
	ds_read_b128 v[230:233], v195 offset:4096
	ds_read_b128 v[234:237], v195 offset:5120
	ds_read_b128 v[238:241], v195 offset:6144
	ds_read_b128 v[242:245], v195 offset:7168
	global_load_lds_dwordx4 v[172:173], off
	v_lshl_add_u64 v[172:173], s[10:11], 0, v[156:157]
	s_add_i32 m0, s20, 0xe000
	s_nop 0
	global_load_lds_dwordx4 v[172:173], off
	s_waitcnt vmcnt(8)
	s_waitcnt lgkmcnt(0)
	s_barrier
	s_setprio 1
	s_waitcnt lgkmcnt(0)
	v_mfma_f32_16x16x32_bf16 v[124:127], v[128:131], v[214:217], v[124:127]
	v_mfma_f32_16x16x32_bf16 v[120:123], v[164:167], v[214:217], v[120:123]
	v_mfma_f32_16x16x32_bf16 v[108:111], v[128:131], v[222:225], v[108:111]
	v_mfma_f32_16x16x32_bf16 v[104:107], v[164:167], v[222:225], v[104:107]
	v_mfma_f32_16x16x32_bf16 v[92:95], v[128:131], v[230:233], v[92:95]
	v_mfma_f32_16x16x32_bf16 v[88:91], v[164:167], v[230:233], v[88:91]
	v_mfma_f32_16x16x32_bf16 v[76:79], v[128:131], v[238:241], v[76:79]
	v_mfma_f32_16x16x32_bf16 v[72:75], v[164:167], v[238:241], v[72:75]
	v_mfma_f32_16x16x32_bf16 v[124:127], v[132:135], v[218:221], v[124:127]
	v_mfma_f32_16x16x32_bf16 v[120:123], v[168:171], v[218:221], v[120:123]
	v_mfma_f32_16x16x32_bf16 v[108:111], v[132:135], v[226:229], v[108:111]
	v_mfma_f32_16x16x32_bf16 v[104:107], v[168:171], v[226:229], v[104:107]
	v_mfma_f32_16x16x32_bf16 v[92:95], v[132:135], v[234:237], v[92:95]
	v_mfma_f32_16x16x32_bf16 v[88:91], v[168:171], v[234:237], v[88:91]
	v_mfma_f32_16x16x32_bf16 v[76:79], v[132:135], v[242:245], v[76:79]
	v_mfma_f32_16x16x32_bf16 v[72:75], v[168:171], v[242:245], v[72:75]
	s_setprio 0
	s_setprio 1
	v_mfma_f32_16x16x32_bf16 v[116:119], v[198:201], v[214:217], v[116:119]
	v_mfma_f32_16x16x32_bf16 v[112:115], v[206:209], v[214:217], v[112:115]
	v_mfma_f32_16x16x32_bf16 v[100:103], v[198:201], v[222:225], v[100:103]
	v_mfma_f32_16x16x32_bf16 v[96:99], v[206:209], v[222:225], v[96:99]
	v_mfma_f32_16x16x32_bf16 v[84:87], v[198:201], v[230:233], v[84:87]
	v_mfma_f32_16x16x32_bf16 v[80:83], v[206:209], v[230:233], v[80:83]
	v_mfma_f32_16x16x32_bf16 v[68:71], v[198:201], v[238:241], v[68:71]
	v_mfma_f32_16x16x32_bf16 v[64:67], v[206:209], v[238:241], v[64:67]
	v_mfma_f32_16x16x32_bf16 v[116:119], v[202:205], v[218:221], v[116:119]
	v_mfma_f32_16x16x32_bf16 v[112:115], v[210:213], v[218:221], v[112:115]
	v_mfma_f32_16x16x32_bf16 v[100:103], v[202:205], v[226:229], v[100:103]
	v_mfma_f32_16x16x32_bf16 v[96:99], v[210:213], v[226:229], v[96:99]
	v_mfma_f32_16x16x32_bf16 v[84:87], v[202:205], v[234:237], v[84:87]
	v_mfma_f32_16x16x32_bf16 v[80:83], v[210:213], v[234:237], v[80:83]
	v_mfma_f32_16x16x32_bf16 v[68:71], v[202:205], v[242:245], v[68:71]
	v_mfma_f32_16x16x32_bf16 v[64:67], v[210:213], v[242:245], v[64:67]
	s_setprio 0
	s_barrier
	s_add_i32 s40, s26, s19
	v_lshl_add_u64 v[172:173], s[34:35], 0, v[138:139]
	s_mov_b32 m0, s40
	ds_read_b128 v[214:217], v195 offset:16384
	ds_read_b128 v[218:221], v195 offset:17408
	ds_read_b128 v[222:225], v195 offset:18432
	ds_read_b128 v[226:229], v195 offset:19456
	ds_read_b128 v[230:233], v195 offset:20480
	ds_read_b128 v[234:237], v195 offset:21504
	ds_read_b128 v[238:241], v195 offset:22528
	ds_read_b128 v[242:245], v195 offset:23552
	global_load_lds_dwordx4 v[172:173], off
	s_add_i32 m0, s40, 0x2000
	s_add_u32 s40, s34, 0x80000
	v_lshl_add_u64 v[246:247], s[34:35], 0, v[142:143]
	s_addc_u32 s41, s35, 0
	s_add_i32 s42, s27, s19
	global_load_lds_dwordx4 v[246:247], off
	v_lshl_add_u64 v[248:249], s[40:41], 0, v[138:139]
	s_mov_b32 m0, s42
	v_lshl_add_u64 v[250:251], vcc, 0, v[140:141]
	global_load_lds_dwordx4 v[248:249], off
	v_lshl_add_u64 v[248:249], s[40:41], 0, v[142:143]
	s_add_i32 m0, s42, 0x2000
	s_nop 0
	global_load_lds_dwordx4 v[248:249], off
	v_lshl_add_u64 v[248:249], vcc, 0, v[136:137]
	s_mov_b32 m0, s20
	s_nop 0
	global_load_lds_dwordx4 v[248:249], off
	s_mov_b32 m0, s21
	s_nop 0
	global_load_lds_dwordx4 v[250:251], off
	s_waitcnt vmcnt(8)
	s_waitcnt lgkmcnt(0)
	s_barrier
; #define PG8_STAGE(bufoff, gbase, voff) do { _Pragma("unroll") for (int _i = 0; _i < 2; ++_i) \
;         __builtin_amdgcn_global_load_lds((const unsigned*)((const char*)(gbase) + (voff)[_i]), (PG8_LAS unsigned*)(lds + (bufoff) + ldsw + _i * 8192), 16, 0, 0); } while (0)
; #define PG8_LDA(dst, b, h) do { _Pragma("unroll") for (int m = 0; m < 4; ++m) _Pragma("unroll") for (int k = 0; k < 2; ++k) dst[m][k] = *(const PG8_LAS bf16x8*)(lds + PG8_SA(b, h) + aoff + m * 2048 + k * 1024); } while (0)
; #define PG8_LDB(dst, b, h) do { _Pragma("unroll") for (int n = 0; n < 2; ++n) _Pragma("unroll") for (int k = 0; k < 2; ++k) dst[n][k] = *(const PG8_LAS bf16x8*)(lds + PG8_SB(b, h) + boff + n * 2048 + k * 1024); } while (0)
; #define PG8_MMA(ai, bj, At, Bt) do { __builtin_amdgcn_s_setprio(1); _Pragma("unroll") for (int m = 0; m < 4; ++m) _Pragma("unroll") for (int n = 0; n < 2; ++n) _Pragma("unroll") for (int k = 0; k < 2; ++k) \
;         acc[ai][bj][m][n] = __builtin_amdgcn_mfma_f32_16x16x32_bf16(Bt[n][k], At[m][k], acc[ai][bj][m][n], 0, 0, 0); __builtin_amdgcn_s_setprio(0); } while (0)
; #define PG8_WAIT_V(n) asm volatile("s_waitcnt vmcnt(" #n ")" ::: "memory")
; #define PG8_WAIT_L(n) asm volatile("s_waitcnt lgkmcnt(" #n ")" ::: "memory")
; #define PG8_BAR __builtin_amdgcn_s_barrier()
; #define PG8_SCHED __builtin_amdgcn_sched_barrier(0)
; template <class Epi, class Sched, bool ALIGN_EPI = false, bool SP2 = false>
; __device__ __forceinline__ void gemm_phase(PG8_LAS unsigned char* lds, const Gemm g, const Sched& S, const Epi& E, int wave_s) {
;     ...
;             PG8_WAIT_V(8); PG8_WAIT_L(0); PG8_BAR; PG8_MMA(1, 0, At, B0); PG8_MMA(1, 1, At, B1); PG8_BAR; PG8_SCHED;
;             PG8_LDB(B0, 1, 0); PG8_LDB(B1, 1, 1); PG8_SCHED; PG8_LDA(At, 1, 0); PG8_STAGE(PG8_SA(0, 1), a2 + hstep, voffA);
;             PG8_WAIT_V(8); PG8_WAIT_L(0); PG8_BAR; PG8_MMA(0, 0, At, B0); PG8_MMA(0, 1, At, B1); PG8_BAR; PG8_SCHED;
	s_setprio 1
	s_waitcnt lgkmcnt(0)
	v_mfma_f32_16x16x32_bf16 v[60:63], v[128:131], v[214:217], v[60:63]
	v_mfma_f32_16x16x32_bf16 v[56:59], v[164:167], v[214:217], v[56:59]
	v_mfma_f32_16x16x32_bf16 v[44:47], v[128:131], v[222:225], v[44:47]
	v_mfma_f32_16x16x32_bf16 v[40:43], v[164:167], v[222:225], v[40:43]
	v_mfma_f32_16x16x32_bf16 v[28:31], v[128:131], v[230:233], v[28:31]
	v_mfma_f32_16x16x32_bf16 v[24:27], v[164:167], v[230:233], v[24:27]
	v_mfma_f32_16x16x32_bf16 v[12:15], v[128:131], v[238:241], v[12:15]
	v_mfma_f32_16x16x32_bf16 v[8:11], v[164:167], v[238:241], v[8:11]
	v_mfma_f32_16x16x32_bf16 v[60:63], v[132:135], v[218:221], v[60:63]
	v_mfma_f32_16x16x32_bf16 v[56:59], v[168:171], v[218:221], v[56:59]
	v_mfma_f32_16x16x32_bf16 v[44:47], v[132:135], v[226:229], v[44:47]
	v_mfma_f32_16x16x32_bf16 v[40:43], v[168:171], v[226:229], v[40:43]
	v_mfma_f32_16x16x32_bf16 v[28:31], v[132:135], v[234:237], v[28:31]
	v_mfma_f32_16x16x32_bf16 v[24:27], v[168:171], v[234:237], v[24:27]
	v_mfma_f32_16x16x32_bf16 v[12:15], v[132:135], v[242:245], v[12:15]
	v_mfma_f32_16x16x32_bf16 v[8:11], v[168:171], v[242:245], v[8:11]
	s_setprio 0
	s_setprio 1
	v_mfma_f32_16x16x32_bf16 v[52:55], v[198:201], v[214:217], v[52:55]
	v_mfma_f32_16x16x32_bf16 v[48:51], v[206:209], v[214:217], v[48:51]
	v_mfma_f32_16x16x32_bf16 v[36:39], v[198:201], v[222:225], v[36:39]
	v_mfma_f32_16x16x32_bf16 v[32:35], v[206:209], v[222:225], v[32:35]
	v_mfma_f32_16x16x32_bf16 v[20:23], v[198:201], v[230:233], v[20:23]
	v_mfma_f32_16x16x32_bf16 v[16:19], v[206:209], v[230:233], v[16:19]
	v_mfma_f32_16x16x32_bf16 v[4:7], v[198:201], v[238:241], v[4:7]
	v_mfma_f32_16x16x32_bf16 v[0:3], v[206:209], v[238:241], v[0:3]
	v_mfma_f32_16x16x32_bf16 v[52:55], v[202:205], v[218:221], v[52:55]
	v_mfma_f32_16x16x32_bf16 v[48:51], v[210:213], v[218:221], v[48:51]
	v_mfma_f32_16x16x32_bf16 v[36:39], v[202:205], v[226:229], v[36:39]
	v_mfma_f32_16x16x32_bf16 v[32:35], v[210:213], v[226:229], v[32:35]
	v_mfma_f32_16x16x32_bf16 v[20:23], v[202:205], v[234:237], v[20:23]
	v_mfma_f32_16x16x32_bf16 v[16:19], v[210:213], v[234:237], v[16:19]
	v_mfma_f32_16x16x32_bf16 v[4:7], v[202:205], v[242:245], v[4:7]
	v_mfma_f32_16x16x32_bf16 v[0:3], v[210:213], v[242:245], v[0:3]
	s_setprio 0
	s_barrier
	s_add_i32 s42, 0, 0x18000
	v_add_u32_e32 v144, s42, v175
	s_add_i32 s43, 0, 0x1c000
	ds_read_b128 v[128:131], v144
	ds_read_b128 v[132:135], v144 offset:1024
	ds_read_b128 v[164:167], v144 offset:2048
	ds_read_b128 v[168:171], v144 offset:3072
	v_add_u32_e32 v144, s43, v175
	ds_read_b128 v[198:201], v144
	ds_read_b128 v[202:205], v144 offset:1024
	ds_read_b128 v[206:209], v144 offset:2048
	ds_read_b128 v[210:213], v144 offset:3072
	s_add_u32 s40, vcc_lo, 0x80000
	s_addc_u32 s41, vcc_hi, 0
	s_mov_b32 m0, s23
	v_lshl_add_u64 v[252:253], s[40:41], 0, v[136:137]
	ds_read_b128 v[214:217], v195 offset:32768
	ds_read_b128 v[218:221], v195 offset:33792
	ds_read_b128 v[222:225], v195 offset:34816
	ds_read_b128 v[226:229], v195 offset:35840
	ds_read_b128 v[230:233], v195 offset:36864
	ds_read_b128 v[234:237], v195 offset:37888
	ds_read_b128 v[238:241], v195 offset:38912
	ds_read_b128 v[242:245], v195 offset:39936
	global_load_lds_dwordx4 v[252:253], off
	v_lshl_add_u64 v[252:253], s[40:41], 0, v[140:141]
	s_mov_b32 m0, s33
	s_nop 0
	global_load_lds_dwordx4 v[252:253], off
	s_waitcnt vmcnt(8)
	s_waitcnt lgkmcnt(0)
	s_barrier
	s_setprio 1
	s_waitcnt lgkmcnt(0)
	v_mfma_f32_16x16x32_bf16 v[124:127], v[128:131], v[214:217], v[124:127]
	v_mfma_f32_16x16x32_bf16 v[120:123], v[164:167], v[214:217], v[120:123]
	v_mfma_f32_16x16x32_bf16 v[108:111], v[128:131], v[222:225], v[108:111]
	v_mfma_f32_16x16x32_bf16 v[104:107], v[164:167], v[222:225], v[104:107]
	v_mfma_f32_16x16x32_bf16 v[92:95], v[128:131], v[230:233], v[92:95]
	v_mfma_f32_16x16x32_bf16 v[88:91], v[164:167], v[230:233], v[88:91]
	v_mfma_f32_16x16x32_bf16 v[76:79], v[128:131], v[238:241], v[76:79]
	v_mfma_f32_16x16x32_bf16 v[72:75], v[164:167], v[238:241], v[72:75]
	v_mfma_f32_16x16x32_bf16 v[124:127], v[132:135], v[218:221], v[124:127]
	v_mfma_f32_16x16x32_bf16 v[120:123], v[168:171], v[218:221], v[120:123]
	v_mfma_f32_16x16x32_bf16 v[108:111], v[132:135], v[226:229], v[108:111]
	v_mfma_f32_16x16x32_bf16 v[104:107], v[168:171], v[226:229], v[104:107]
	v_mfma_f32_16x16x32_bf16 v[92:95], v[132:135], v[234:237], v[92:95]
	v_mfma_f32_16x16x32_bf16 v[88:91], v[168:171], v[234:237], v[88:91]
	v_mfma_f32_16x16x32_bf16 v[76:79], v[132:135], v[242:245], v[76:79]
	v_mfma_f32_16x16x32_bf16 v[72:75], v[168:171], v[242:245], v[72:75]
	s_setprio 0
	s_setprio 1
	v_mfma_f32_16x16x32_bf16 v[116:119], v[198:201], v[214:217], v[116:119]
	v_mfma_f32_16x16x32_bf16 v[112:115], v[206:209], v[214:217], v[112:115]
	v_mfma_f32_16x16x32_bf16 v[100:103], v[198:201], v[222:225], v[100:103]
	v_mfma_f32_16x16x32_bf16 v[96:99], v[206:209], v[222:225], v[96:99]
	v_mfma_f32_16x16x32_bf16 v[84:87], v[198:201], v[230:233], v[84:87]
	v_mfma_f32_16x16x32_bf16 v[80:83], v[206:209], v[230:233], v[80:83]
	v_mfma_f32_16x16x32_bf16 v[68:71], v[198:201], v[238:241], v[68:71]
	v_mfma_f32_16x16x32_bf16 v[64:67], v[206:209], v[238:241], v[64:67]
	v_mfma_f32_16x16x32_bf16 v[116:119], v[202:205], v[218:221], v[116:119]
	v_mfma_f32_16x16x32_bf16 v[112:115], v[210:213], v[218:221], v[112:115]
	v_mfma_f32_16x16x32_bf16 v[100:103], v[202:205], v[226:229], v[100:103]
	v_mfma_f32_16x16x32_bf16 v[96:99], v[210:213], v[226:229], v[96:99]
	v_mfma_f32_16x16x32_bf16 v[84:87], v[202:205], v[234:237], v[84:87]
	v_mfma_f32_16x16x32_bf16 v[80:83], v[210:213], v[234:237], v[80:83]
	v_mfma_f32_16x16x32_bf16 v[68:71], v[202:205], v[242:245], v[68:71]
	v_mfma_f32_16x16x32_bf16 v[64:67], v[210:213], v[242:245], v[64:67]
	s_setprio 0
	s_barrier
; #define PG8_STAGE(bufoff, gbase, voff) do { _Pragma("unroll") for (int _i = 0; _i < 2; ++_i) \
;         __builtin_amdgcn_global_load_lds((const unsigned*)((const char*)(gbase) + (voff)[_i]), (PG8_LAS unsigned*)(lds + (bufoff) + ldsw + _i * 8192), 16, 0, 0); } while (0)
; #define PG8_LDA(dst, b, h) do { _Pragma("unroll") for (int m = 0; m < 4; ++m) _Pragma("unroll") for (int k = 0; k < 2; ++k) dst[m][k] = *(const PG8_LAS bf16x8*)(lds + PG8_SA(b, h) + aoff + m * 2048 + k * 1024); } while (0)
; #define PG8_MMA(ai, bj, At, Bt) do { __builtin_amdgcn_s_setprio(1); _Pragma("unroll") for (int m = 0; m < 4; ++m) _Pragma("unroll") for (int n = 0; n < 2; ++n) _Pragma("unroll") for (int k = 0; k < 2; ++k) \
;         acc[ai][bj][m][n] = __builtin_amdgcn_mfma_f32_16x16x32_bf16(Bt[n][k], At[m][k], acc[ai][bj][m][n], 0, 0, 0); __builtin_amdgcn_s_setprio(0); } while (0)
; #define PG8_WAIT_V(n) asm volatile("s_waitcnt vmcnt(" #n ")" ::: "memory")
; #define PG8_WAIT_L(n) asm volatile("s_waitcnt lgkmcnt(" #n ")" ::: "memory")
; #define PG8_BAR __builtin_amdgcn_s_barrier()
; #define PG8_SCHED __builtin_amdgcn_sched_barrier(0)
; template <class Epi, class Sched, bool ALIGN_EPI = false, bool SP2 = false>
; __device__ __forceinline__ void gemm_phase(PG8_LAS unsigned char* lds, const Gemm g, const Sched& S, const Epi& E, int wave_s) {
;     ...
;         for (int t = 0; t < nt; t += 2) {
;             const bool last = (t == nt - 2);
;             const char* a1 = cA + (size_t)(t + 1) * kstep;
;             const char* a2 = last ? nA : cA + (size_t)(t + 2) * kstep; const char* b2 = last ? nB : cB + (size_t)(t + 2) * kstep;
;     ...
;             PG8_LDA(At, 1, 1); PG8_STAGE(PG8_SB(1, 0), b3, voffB); PG8_STAGE(PG8_SB(1, 1), b3 + hstep, voffB); PG8_STAGE(PG8_SA(1, 0), a3, voffA);
;             PG8_WAIT_V(8); PG8_WAIT_L(0); PG8_BAR; PG8_MMA(1, 0, At, B0); PG8_MMA(1, 1, At, B1); PG8_BAR; PG8_SCHED;
	s_add_i32 s40, s42, s19
	v_lshl_add_u64 v[172:173], v[172:173], 0, s[16:17]
	s_mov_b32 m0, s40
	ds_read_b128 v[214:217], v195 offset:49152
	ds_read_b128 v[218:221], v195 offset:50176
	ds_read_b128 v[222:225], v195 offset:51200
	ds_read_b128 v[226:229], v195 offset:52224
	ds_read_b128 v[230:233], v195 offset:53248
	ds_read_b128 v[234:237], v195 offset:54272
	ds_read_b128 v[238:241], v195 offset:55296
	ds_read_b128 v[242:245], v195 offset:56320
	global_load_lds_dwordx4 v[172:173], off
	s_add_i32 m0, s40, 0x2000
	s_add_u32 s34, s34, 0x80080
	v_lshl_add_u64 v[172:173], v[246:247], 0, s[16:17]
	s_addc_u32 s35, s35, 0
	s_add_i32 s40, s43, s19
	global_load_lds_dwordx4 v[172:173], off
	v_lshl_add_u64 v[172:173], s[34:35], 0, v[138:139]
	s_mov_b32 m0, s40
	s_nop 0
	global_load_lds_dwordx4 v[172:173], off
	v_lshl_add_u64 v[172:173], s[34:35], 0, v[142:143]
	s_add_i32 m0, s40, 0x2000
	s_nop 0
	global_load_lds_dwordx4 v[172:173], off
	v_lshl_add_u64 v[172:173], v[248:249], 0, s[16:17]
	s_mov_b32 m0, s85
	s_nop 0
	global_load_lds_dwordx4 v[172:173], off
	v_lshl_add_u64 v[172:173], v[250:251], 0, s[16:17]
	s_mov_b32 m0, s87
	s_nop 0
	global_load_lds_dwordx4 v[172:173], off
	s_waitcnt vmcnt(8)
	s_waitcnt lgkmcnt(0)
	s_barrier
	s_setprio 1
	s_waitcnt lgkmcnt(0)
	v_mfma_f32_16x16x32_bf16 v[60:63], v[128:131], v[214:217], v[60:63]
	v_mfma_f32_16x16x32_bf16 v[56:59], v[164:167], v[214:217], v[56:59]
	v_mfma_f32_16x16x32_bf16 v[44:47], v[128:131], v[222:225], v[44:47]
	v_mfma_f32_16x16x32_bf16 v[40:43], v[164:167], v[222:225], v[40:43]
	v_mfma_f32_16x16x32_bf16 v[28:31], v[128:131], v[230:233], v[28:31]
	v_mfma_f32_16x16x32_bf16 v[24:27], v[164:167], v[230:233], v[24:27]
	v_mfma_f32_16x16x32_bf16 v[12:15], v[128:131], v[238:241], v[12:15]
	v_mfma_f32_16x16x32_bf16 v[8:11], v[164:167], v[238:241], v[8:11]
	v_mfma_f32_16x16x32_bf16 v[60:63], v[132:135], v[218:221], v[60:63]
	v_mfma_f32_16x16x32_bf16 v[56:59], v[168:171], v[218:221], v[56:59]
	v_mfma_f32_16x16x32_bf16 v[44:47], v[132:135], v[226:229], v[44:47]
	v_mfma_f32_16x16x32_bf16 v[40:43], v[168:171], v[226:229], v[40:43]
	v_mfma_f32_16x16x32_bf16 v[28:31], v[132:135], v[234:237], v[28:31]
	v_mfma_f32_16x16x32_bf16 v[24:27], v[168:171], v[234:237], v[24:27]
	v_mfma_f32_16x16x32_bf16 v[12:15], v[132:135], v[242:245], v[12:15]
	v_mfma_f32_16x16x32_bf16 v[8:11], v[168:171], v[242:245], v[8:11]
	s_setprio 0
	s_setprio 1
	v_mfma_f32_16x16x32_bf16 v[52:55], v[198:201], v[214:217], v[52:55]
	v_mfma_f32_16x16x32_bf16 v[48:51], v[206:209], v[214:217], v[48:51]
	v_mfma_f32_16x16x32_bf16 v[36:39], v[198:201], v[222:225], v[36:39]
	v_mfma_f32_16x16x32_bf16 v[32:35], v[206:209], v[222:225], v[32:35]
	v_mfma_f32_16x16x32_bf16 v[20:23], v[198:201], v[230:233], v[20:23]
	v_mfma_f32_16x16x32_bf16 v[16:19], v[206:209], v[230:233], v[16:19]
	v_mfma_f32_16x16x32_bf16 v[4:7], v[198:201], v[238:241], v[4:7]
	v_mfma_f32_16x16x32_bf16 v[0:3], v[206:209], v[238:241], v[0:3]
	v_mfma_f32_16x16x32_bf16 v[52:55], v[202:205], v[218:221], v[52:55]
	v_mfma_f32_16x16x32_bf16 v[48:51], v[210:213], v[218:221], v[48:51]
	v_mfma_f32_16x16x32_bf16 v[36:39], v[202:205], v[226:229], v[36:39]
	v_mfma_f32_16x16x32_bf16 v[32:35], v[210:213], v[226:229], v[32:35]
	v_mfma_f32_16x16x32_bf16 v[20:23], v[202:205], v[234:237], v[20:23]
	v_mfma_f32_16x16x32_bf16 v[16:19], v[210:213], v[234:237], v[16:19]
	v_mfma_f32_16x16x32_bf16 v[4:7], v[202:205], v[242:245], v[4:7]
	v_mfma_f32_16x16x32_bf16 v[0:3], v[210:213], v[242:245], v[0:3]
	s_add_i32 s37, s37, 2
	s_add_u32 s10, s10, 0x100
	s_addc_u32 s11, s11, 0
	s_add_u32 s91, s91, 0x100
	s_addc_u32 s36, s36, 0
	s_cmp_gt_u32 s37, 29
	s_setprio 0
	s_barrier
	s_cbranch_scc0 .LBB0_160
	s_and_b64 vcc, exec, s[28:29]
	s_cbranch_vccz .LBB0_163
	s_barrier

; #define PG8_STAGE(bufoff, gbase, voff) do { _Pragma("unroll") for (int _i = 0; _i < 2; ++_i) \
;         __builtin_amdgcn_global_load_lds((const unsigned*)((const char*)(gbase) + (voff)[_i]), (PG8_LAS unsigned*)(lds + (bufoff) + ldsw + _i * 8192), 16, 0, 0); } while (0)
; #define PG8_LDA(dst, b, h) do { _Pragma("unroll") for (int m = 0; m < 4; ++m) _Pragma("unroll") for (int k = 0; k < 2; ++k) dst[m][k] = *(const PG8_LAS bf16x8*)(lds + PG8_SA(b, h) + aoff + m * 2048 + k * 1024); } while (0)
; #define PG8_LDB(dst, b, h) do { _Pragma("unroll") for (int n = 0; n < 2; ++n) _Pragma("unroll") for (int k = 0; k < 2; ++k) dst[n][k] = *(const PG8_LAS bf16x8*)(lds + PG8_SB(b, h) + boff + n * 2048 + k * 1024); } while (0)
; #define PG8_MMA(ai, bj, At, Bt) do { __builtin_amdgcn_s_setprio(1); _Pragma("unroll") for (int m = 0; m < 4; ++m) _Pragma("unroll") for (int n = 0; n < 2; ++n) _Pragma("unroll") for (int k = 0; k < 2; ++k) \
;         acc[ai][bj][m][n] = __builtin_amdgcn_mfma_f32_16x16x32_bf16(Bt[n][k], At[m][k], acc[ai][bj][m][n], 0, 0, 0); __builtin_amdgcn_s_setprio(0); } while (0)
; #define PG8_WAIT_V(n) asm volatile("s_waitcnt vmcnt(" #n ")" ::: "memory")
; #define PG8_WAIT_L(n) asm volatile("s_waitcnt lgkmcnt(" #n ")" ::: "memory")
; #define PG8_BAR __builtin_amdgcn_s_barrier()
; #define PG8_SCHED __builtin_amdgcn_sched_barrier(0)
; template <class Epi, class Sched, bool ALIGN_EPI = false, bool SP2 = false>
; __device__ __forceinline__ void gemm_phase(PG8_LAS unsigned char* lds, const Gemm g, const Sched& S, const Epi& E, int wave_s) {
;     ...
;         for (int t = 0; t < nt; t += 2) {
;             const bool last = (t == nt - 2);
;             const char* a1 = cA + (size_t)(t + 1) * kstep;
;             const char* a2 = last ? nA : cA + (size_t)(t + 2) * kstep; const char* b2 = last ? nB : cB + (size_t)(t + 2) * kstep;
;             const char* a3 = a2 + kstep; const char* b3 = b2 + kstep;
;             if (last && has_next) S.a_ready(nxt);
;             if constexpr (SP2) {
;             PG8_LDB(B0, 0, 0); PG8_LDB(B1, 0, 1); PG8_SCHED; PG8_LDA(At, 0, 0); PG8_STAGE(PG8_SA(1, 1), a1 + hstep, voffA);
;             PG8_WAIT_V(8); PG8_WAIT_L(0); PG8_BAR; PG8_MMA(0, 0, At, B0); PG8_MMA(0, 1, At, B1); PG8_BAR; PG8_SCHED;
;             PG8_LDA(At, 0, 1); PG8_STAGE(PG8_SB(0, 0), b2, voffB); PG8_STAGE(PG8_SB(0, 1), b2 + hstep, voffB); PG8_STAGE(PG8_SA(0, 0), a2, voffA);
.LBB0_710:
	ds_read_b128 v[144:147], v151
	ds_read_b128 v[154:157], v151 offset:1024
	ds_read_b128 v[158:161], v151 offset:2048
	ds_read_b128 v[162:165], v151 offset:3072
	ds_read_b128 v[166:169], v152
	ds_read_b128 v[170:173], v152 offset:1024
	ds_read_b128 v[174:177], v152 offset:2048
	ds_read_b128 v[178:181], v152 offset:3072
	s_add_u32 s0, s40, 0xfff80080
	s_addc_u32 s1, s41, -1
	s_cmp_eq_u32 s61, 28
	s_cselect_b32 s45, s29, s1
	s_cselect_b32 s44, s39, s0
	s_cselect_b32 s43, s17, s60
	s_cselect_b32 s42, s54, s55
	v_lshl_add_u64 v[198:199], s[40:41], 0, v[136:137]
	s_add_i32 m0, s20, 0xc000
	ds_read_b128 v[182:185], v153
	ds_read_b128 v[186:189], v153 offset:1024
	ds_read_b128 v[190:193], v153 offset:2048
	ds_read_b128 v[194:197], v153 offset:3072
	ds_read_b128 v[202:205], v153 offset:4096
	ds_read_b128 v[208:211], v153 offset:5120
	ds_read_b128 v[212:215], v153 offset:6144
	ds_read_b128 v[216:219], v153 offset:7168
	global_load_lds_dwordx4 v[198:199], off
	v_lshl_add_u64 v[198:199], s[40:41], 0, v[138:139]
	s_add_i32 m0, s20, 0xe000
	s_nop 0
	global_load_lds_dwordx4 v[198:199], off
	s_waitcnt vmcnt(8)
	s_waitcnt lgkmcnt(0)
	s_barrier
	s_setprio 1
	s_waitcnt lgkmcnt(0)
	v_mfma_f32_16x16x32_bf16 v[124:127], v[144:147], v[182:185], v[124:127]
	v_mfma_f32_16x16x32_bf16 v[120:123], v[158:161], v[182:185], v[120:123]
	v_mfma_f32_16x16x32_bf16 v[108:111], v[144:147], v[190:193], v[108:111]
	v_mfma_f32_16x16x32_bf16 v[104:107], v[158:161], v[190:193], v[104:107]
	v_mfma_f32_16x16x32_bf16 v[92:95], v[144:147], v[202:205], v[92:95]
	v_mfma_f32_16x16x32_bf16 v[88:91], v[158:161], v[202:205], v[88:91]
	v_mfma_f32_16x16x32_bf16 v[76:79], v[144:147], v[212:215], v[76:79]
	v_mfma_f32_16x16x32_bf16 v[72:75], v[158:161], v[212:215], v[72:75]
	v_mfma_f32_16x16x32_bf16 v[124:127], v[154:157], v[186:189], v[124:127]
	v_mfma_f32_16x16x32_bf16 v[120:123], v[162:165], v[186:189], v[120:123]
	v_mfma_f32_16x16x32_bf16 v[108:111], v[154:157], v[194:197], v[108:111]
	v_mfma_f32_16x16x32_bf16 v[104:107], v[162:165], v[194:197], v[104:107]
	v_mfma_f32_16x16x32_bf16 v[92:95], v[154:157], v[208:211], v[92:95]
	v_mfma_f32_16x16x32_bf16 v[88:91], v[162:165], v[208:211], v[88:91]
	v_mfma_f32_16x16x32_bf16 v[76:79], v[154:157], v[216:219], v[76:79]
	v_mfma_f32_16x16x32_bf16 v[72:75], v[162:165], v[216:219], v[72:75]
	s_setprio 0
	s_setprio 1
	v_mfma_f32_16x16x32_bf16 v[116:119], v[166:169], v[182:185], v[116:119]
	v_mfma_f32_16x16x32_bf16 v[112:115], v[174:177], v[182:185], v[112:115]
	v_mfma_f32_16x16x32_bf16 v[100:103], v[166:169], v[190:193], v[100:103]
	v_mfma_f32_16x16x32_bf16 v[96:99], v[174:177], v[190:193], v[96:99]
	v_mfma_f32_16x16x32_bf16 v[84:87], v[166:169], v[202:205], v[84:87]
	v_mfma_f32_16x16x32_bf16 v[80:83], v[174:177], v[202:205], v[80:83]
	v_mfma_f32_16x16x32_bf16 v[68:71], v[166:169], v[212:215], v[68:71]
	v_mfma_f32_16x16x32_bf16 v[64:67], v[174:177], v[212:215], v[64:67]
	v_mfma_f32_16x16x32_bf16 v[116:119], v[170:173], v[186:189], v[116:119]
	v_mfma_f32_16x16x32_bf16 v[112:115], v[178:181], v[186:189], v[112:115]
	v_mfma_f32_16x16x32_bf16 v[100:103], v[170:173], v[194:197], v[100:103]
	v_mfma_f32_16x16x32_bf16 v[96:99], v[178:181], v[194:197], v[96:99]
	v_mfma_f32_16x16x32_bf16 v[84:87], v[170:173], v[208:211], v[84:87]
	v_mfma_f32_16x16x32_bf16 v[80:83], v[178:181], v[208:211], v[80:83]
	v_mfma_f32_16x16x32_bf16 v[68:71], v[170:173], v[216:219], v[68:71]
	v_mfma_f32_16x16x32_bf16 v[64:67], v[178:181], v[216:219], v[64:67]
	s_setprio 0
	s_barrier
	s_add_i32 s0, s33, s19
	v_lshl_add_u64 v[198:199], s[42:43], 0, v[130:131]
	s_mov_b32 m0, s0
	ds_read_b128 v[182:185], v153 offset:16384
	ds_read_b128 v[186:189], v153 offset:17408
	ds_read_b128 v[190:193], v153 offset:18432
	ds_read_b128 v[194:197], v153 offset:19456
	ds_read_b128 v[202:205], v153 offset:20480
	ds_read_b128 v[208:211], v153 offset:21504
	ds_read_b128 v[212:215], v153 offset:22528
	ds_read_b128 v[216:219], v153 offset:23552
	global_load_lds_dwordx4 v[198:199], off
	s_add_i32 m0, s0, 0x2000
	s_add_u32 s66, s42, 0x80000
	v_lshl_add_u64 v[220:221], s[42:43], 0, v[134:135]
	s_addc_u32 s67, s43, 0
	s_add_i32 s0, s46, s19
	global_load_lds_dwordx4 v[220:221], off
	v_lshl_add_u64 v[222:223], s[66:67], 0, v[130:131]
	s_mov_b32 m0, s0
	v_lshl_add_u64 v[224:225], s[44:45], 0, v[132:133]
	global_load_lds_dwordx4 v[222:223], off
	v_lshl_add_u64 v[222:223], s[66:67], 0, v[134:135]
	s_add_i32 m0, s0, 0x2000
	s_nop 0
	global_load_lds_dwordx4 v[222:223], off
	v_lshl_add_u64 v[222:223], s[44:45], 0, v[128:129]
	s_mov_b32 m0, s20
	s_nop 0
	global_load_lds_dwordx4 v[222:223], off
	s_mov_b32 m0, s21
	s_nop 0
	global_load_lds_dwordx4 v[224:225], off
	s_waitcnt vmcnt(8)
	s_waitcnt lgkmcnt(0)
	s_barrier
; #define PG8_STAGE(bufoff, gbase, voff) do { _Pragma("unroll") for (int _i = 0; _i < 2; ++_i) \
;         __builtin_amdgcn_global_load_lds((const unsigned*)((const char*)(gbase) + (voff)[_i]), (PG8_LAS unsigned*)(lds + (bufoff) + ldsw + _i * 8192), 16, 0, 0); } while (0)
; #define PG8_LDA(dst, b, h) do { _Pragma("unroll") for (int m = 0; m < 4; ++m) _Pragma("unroll") for (int k = 0; k < 2; ++k) dst[m][k] = *(const PG8_LAS bf16x8*)(lds + PG8_SA(b, h) + aoff + m * 2048 + k * 1024); } while (0)
; #define PG8_LDB(dst, b, h) do { _Pragma("unroll") for (int n = 0; n < 2; ++n) _Pragma("unroll") for (int k = 0; k < 2; ++k) dst[n][k] = *(const PG8_LAS bf16x8*)(lds + PG8_SB(b, h) + boff + n * 2048 + k * 1024); } while (0)
; #define PG8_MMA(ai, bj, At, Bt) do { __builtin_amdgcn_s_setprio(1); _Pragma("unroll") for (int m = 0; m < 4; ++m) _Pragma("unroll") for (int n = 0; n < 2; ++n) _Pragma("unroll") for (int k = 0; k < 2; ++k) \
;         acc[ai][bj][m][n] = __builtin_amdgcn_mfma_f32_16x16x32_bf16(Bt[n][k], At[m][k], acc[ai][bj][m][n], 0, 0, 0); __builtin_amdgcn_s_setprio(0); } while (0)
; #define PG8_WAIT_V(n) asm volatile("s_waitcnt vmcnt(" #n ")" ::: "memory")
; #define PG8_WAIT_L(n) asm volatile("s_waitcnt lgkmcnt(" #n ")" ::: "memory")
; #define PG8_BAR __builtin_amdgcn_s_barrier()
; #define PG8_SCHED __builtin_amdgcn_sched_barrier(0)
; template <class Epi, class Sched, bool ALIGN_EPI = false, bool SP2 = false>
; __device__ __forceinline__ void gemm_phase(PG8_LAS unsigned char* lds, const Gemm g, const Sched& S, const Epi& E, int wave_s) {
;     ...
;             PG8_WAIT_V(8); PG8_WAIT_L(0); PG8_BAR; PG8_MMA(1, 0, At, B0); PG8_MMA(1, 1, At, B1); PG8_BAR; PG8_SCHED;
;             PG8_LDB(B0, 1, 0); PG8_LDB(B1, 1, 1); PG8_SCHED; PG8_LDA(At, 1, 0); PG8_STAGE(PG8_SA(0, 1), a2 + hstep, voffA);
;             PG8_WAIT_V(8); PG8_WAIT_L(0); PG8_BAR; PG8_MMA(0, 0, At, B0); PG8_MMA(0, 1, At, B1); PG8_BAR; PG8_SCHED;
	s_setprio 1
	s_waitcnt lgkmcnt(0)
	v_mfma_f32_16x16x32_bf16 v[60:63], v[144:147], v[182:185], v[60:63]
	v_mfma_f32_16x16x32_bf16 v[56:59], v[158:161], v[182:185], v[56:59]
	v_mfma_f32_16x16x32_bf16 v[44:47], v[144:147], v[190:193], v[44:47]
	v_mfma_f32_16x16x32_bf16 v[40:43], v[158:161], v[190:193], v[40:43]
	v_mfma_f32_16x16x32_bf16 v[28:31], v[144:147], v[202:205], v[28:31]
	v_mfma_f32_16x16x32_bf16 v[24:27], v[158:161], v[202:205], v[24:27]
	v_mfma_f32_16x16x32_bf16 v[12:15], v[144:147], v[212:215], v[12:15]
	v_mfma_f32_16x16x32_bf16 v[8:11], v[158:161], v[212:215], v[8:11]
	v_mfma_f32_16x16x32_bf16 v[60:63], v[154:157], v[186:189], v[60:63]
	v_mfma_f32_16x16x32_bf16 v[56:59], v[162:165], v[186:189], v[56:59]
	v_mfma_f32_16x16x32_bf16 v[44:47], v[154:157], v[194:197], v[44:47]
	v_mfma_f32_16x16x32_bf16 v[40:43], v[162:165], v[194:197], v[40:43]
	v_mfma_f32_16x16x32_bf16 v[28:31], v[154:157], v[208:211], v[28:31]
	v_mfma_f32_16x16x32_bf16 v[24:27], v[162:165], v[208:211], v[24:27]
	v_mfma_f32_16x16x32_bf16 v[12:15], v[154:157], v[216:219], v[12:15]
	v_mfma_f32_16x16x32_bf16 v[8:11], v[162:165], v[216:219], v[8:11]
	s_setprio 0
	s_setprio 1
	v_mfma_f32_16x16x32_bf16 v[52:55], v[166:169], v[182:185], v[52:55]
	v_mfma_f32_16x16x32_bf16 v[48:51], v[174:177], v[182:185], v[48:51]
	v_mfma_f32_16x16x32_bf16 v[36:39], v[166:169], v[190:193], v[36:39]
	v_mfma_f32_16x16x32_bf16 v[32:35], v[174:177], v[190:193], v[32:35]
	v_mfma_f32_16x16x32_bf16 v[20:23], v[166:169], v[202:205], v[20:23]
	v_mfma_f32_16x16x32_bf16 v[16:19], v[174:177], v[202:205], v[16:19]
	v_mfma_f32_16x16x32_bf16 v[4:7], v[166:169], v[212:215], v[4:7]
	v_mfma_f32_16x16x32_bf16 v[0:3], v[174:177], v[212:215], v[0:3]
	v_mfma_f32_16x16x32_bf16 v[52:55], v[170:173], v[186:189], v[52:55]
	v_mfma_f32_16x16x32_bf16 v[48:51], v[178:181], v[186:189], v[48:51]
	v_mfma_f32_16x16x32_bf16 v[36:39], v[170:173], v[194:197], v[36:39]
	v_mfma_f32_16x16x32_bf16 v[32:35], v[178:181], v[194:197], v[32:35]
	v_mfma_f32_16x16x32_bf16 v[20:23], v[170:173], v[208:211], v[20:23]
	v_mfma_f32_16x16x32_bf16 v[16:19], v[178:181], v[208:211], v[16:19]
	v_mfma_f32_16x16x32_bf16 v[4:7], v[170:173], v[216:219], v[4:7]
	v_mfma_f32_16x16x32_bf16 v[0:3], v[178:181], v[216:219], v[0:3]
	s_setprio 0
	s_barrier
	s_add_i32 s0, 0, 0x18000
	s_add_i32 s1, 0, 0x1c000
	v_add_u32_e32 v162, s0, v149
	v_add_u32_e32 v178, s1, v149
	ds_read_b128 v[144:147], v162
	ds_read_b128 v[154:157], v162 offset:1024
	ds_read_b128 v[158:161], v162 offset:2048
	ds_read_b128 v[162:165], v162 offset:3072
	ds_read_b128 v[166:169], v178
	ds_read_b128 v[170:173], v178 offset:1024
	ds_read_b128 v[174:177], v178 offset:2048
	ds_read_b128 v[178:181], v178 offset:3072
	s_add_u32 s44, s44, 0x80000
	s_addc_u32 s45, s45, 0
	s_mov_b32 m0, s22
	v_lshl_add_u64 v[226:227], s[44:45], 0, v[128:129]
	ds_read_b128 v[182:185], v153 offset:32768
	ds_read_b128 v[186:189], v153 offset:33792
	ds_read_b128 v[190:193], v153 offset:34816
	ds_read_b128 v[194:197], v153 offset:35840
	ds_read_b128 v[202:205], v153 offset:36864
	ds_read_b128 v[208:211], v153 offset:37888
	ds_read_b128 v[212:215], v153 offset:38912
	ds_read_b128 v[216:219], v153 offset:39936
	global_load_lds_dwordx4 v[226:227], off
	v_lshl_add_u64 v[226:227], s[44:45], 0, v[132:133]
	s_mov_b32 m0, s23
	s_nop 0
	global_load_lds_dwordx4 v[226:227], off
	s_waitcnt vmcnt(8)
	s_waitcnt lgkmcnt(0)
	s_barrier
	s_setprio 1
	s_waitcnt lgkmcnt(0)
	v_mfma_f32_16x16x32_bf16 v[124:127], v[144:147], v[182:185], v[124:127]
	v_mfma_f32_16x16x32_bf16 v[120:123], v[158:161], v[182:185], v[120:123]
	v_mfma_f32_16x16x32_bf16 v[108:111], v[144:147], v[190:193], v[108:111]
	v_mfma_f32_16x16x32_bf16 v[104:107], v[158:161], v[190:193], v[104:107]
	v_mfma_f32_16x16x32_bf16 v[92:95], v[144:147], v[202:205], v[92:95]
	v_mfma_f32_16x16x32_bf16 v[88:91], v[158:161], v[202:205], v[88:91]
	v_mfma_f32_16x16x32_bf16 v[76:79], v[144:147], v[212:215], v[76:79]
	v_mfma_f32_16x16x32_bf16 v[72:75], v[158:161], v[212:215], v[72:75]
	v_mfma_f32_16x16x32_bf16 v[124:127], v[154:157], v[186:189], v[124:127]
	v_mfma_f32_16x16x32_bf16 v[120:123], v[162:165], v[186:189], v[120:123]
	v_mfma_f32_16x16x32_bf16 v[108:111], v[154:157], v[194:197], v[108:111]
	v_mfma_f32_16x16x32_bf16 v[104:107], v[162:165], v[194:197], v[104:107]
	v_mfma_f32_16x16x32_bf16 v[92:95], v[154:157], v[208:211], v[92:95]
	v_mfma_f32_16x16x32_bf16 v[88:91], v[162:165], v[208:211], v[88:91]
	v_mfma_f32_16x16x32_bf16 v[76:79], v[154:157], v[216:219], v[76:79]
	v_mfma_f32_16x16x32_bf16 v[72:75], v[162:165], v[216:219], v[72:75]
	s_setprio 0
	s_setprio 1
	v_mfma_f32_16x16x32_bf16 v[116:119], v[166:169], v[182:185], v[116:119]
	v_mfma_f32_16x16x32_bf16 v[112:115], v[174:177], v[182:185], v[112:115]
	v_mfma_f32_16x16x32_bf16 v[100:103], v[166:169], v[190:193], v[100:103]
	v_mfma_f32_16x16x32_bf16 v[96:99], v[174:177], v[190:193], v[96:99]
	v_mfma_f32_16x16x32_bf16 v[84:87], v[166:169], v[202:205], v[84:87]
	v_mfma_f32_16x16x32_bf16 v[80:83], v[174:177], v[202:205], v[80:83]
	v_mfma_f32_16x16x32_bf16 v[68:71], v[166:169], v[212:215], v[68:71]
	v_mfma_f32_16x16x32_bf16 v[64:67], v[174:177], v[212:215], v[64:67]
	v_mfma_f32_16x16x32_bf16 v[116:119], v[170:173], v[186:189], v[116:119]
	v_mfma_f32_16x16x32_bf16 v[112:115], v[178:181], v[186:189], v[112:115]
	v_mfma_f32_16x16x32_bf16 v[100:103], v[170:173], v[194:197], v[100:103]
	v_mfma_f32_16x16x32_bf16 v[96:99], v[178:181], v[194:197], v[96:99]
	v_mfma_f32_16x16x32_bf16 v[84:87], v[170:173], v[208:211], v[84:87]
	v_mfma_f32_16x16x32_bf16 v[80:83], v[178:181], v[208:211], v[80:83]
	v_mfma_f32_16x16x32_bf16 v[68:71], v[170:173], v[216:219], v[68:71]
	v_mfma_f32_16x16x32_bf16 v[64:67], v[178:181], v[216:219], v[64:67]
	s_setprio 0
	s_barrier
; #define PG8_STAGE(bufoff, gbase, voff) do { _Pragma("unroll") for (int _i = 0; _i < 2; ++_i) \
;         __builtin_amdgcn_global_load_lds((const unsigned*)((const char*)(gbase) + (voff)[_i]), (PG8_LAS unsigned*)(lds + (bufoff) + ldsw + _i * 8192), 16, 0, 0); } while (0)
; #define PG8_LDA(dst, b, h) do { _Pragma("unroll") for (int m = 0; m < 4; ++m) _Pragma("unroll") for (int k = 0; k < 2; ++k) dst[m][k] = *(const PG8_LAS bf16x8*)(lds + PG8_SA(b, h) + aoff + m * 2048 + k * 1024); } while (0)
; #define PG8_MMA(ai, bj, At, Bt) do { __builtin_amdgcn_s_setprio(1); _Pragma("unroll") for (int m = 0; m < 4; ++m) _Pragma("unroll") for (int n = 0; n < 2; ++n) _Pragma("unroll") for (int k = 0; k < 2; ++k) \
;         acc[ai][bj][m][n] = __builtin_amdgcn_mfma_f32_16x16x32_bf16(Bt[n][k], At[m][k], acc[ai][bj][m][n], 0, 0, 0); __builtin_amdgcn_s_setprio(0); } while (0)
; #define PG8_WAIT_V(n) asm volatile("s_waitcnt vmcnt(" #n ")" ::: "memory")
; #define PG8_WAIT_L(n) asm volatile("s_waitcnt lgkmcnt(" #n ")" ::: "memory")
; #define PG8_BAR __builtin_amdgcn_s_barrier()
; #define PG8_SCHED __builtin_amdgcn_sched_barrier(0)
; template <class Epi, class Sched, bool ALIGN_EPI = false, bool SP2 = false>
; __device__ __forceinline__ void gemm_phase(PG8_LAS unsigned char* lds, const Gemm g, const Sched& S, const Epi& E, int wave_s) {
;     ...
;         for (int t = 0; t < nt; t += 2) {
;             const bool last = (t == nt - 2);
;     ...
;             PG8_LDA(At, 1, 1); PG8_STAGE(PG8_SB(1, 0), b3, voffB); PG8_STAGE(PG8_SB(1, 1), b3 + hstep, voffB); PG8_STAGE(PG8_SA(1, 0), a3, voffA);
;             PG8_WAIT_V(8); PG8_WAIT_L(0); PG8_BAR; PG8_MMA(1, 0, At, B0); PG8_MMA(1, 1, At, B1); PG8_BAR; PG8_SCHED;
	s_add_i32 s0, s0, s19
	v_lshl_add_u64 v[198:199], v[198:199], 0, s[10:11]
	s_mov_b32 m0, s0
	ds_read_b128 v[182:185], v153 offset:49152
	ds_read_b128 v[186:189], v153 offset:50176
	ds_read_b128 v[190:193], v153 offset:51200
	ds_read_b128 v[194:197], v153 offset:52224
	ds_read_b128 v[202:205], v153 offset:53248
	ds_read_b128 v[208:211], v153 offset:54272
	ds_read_b128 v[212:215], v153 offset:55296
	ds_read_b128 v[216:219], v153 offset:56320
	global_load_lds_dwordx4 v[198:199], off
	s_add_i32 m0, s0, 0x2000
	s_add_u32 s42, s42, 0x80080
	v_lshl_add_u64 v[198:199], v[220:221], 0, s[10:11]
	s_addc_u32 s43, s43, 0
	s_add_i32 s0, s1, s19
	global_load_lds_dwordx4 v[198:199], off
	v_lshl_add_u64 v[198:199], s[42:43], 0, v[130:131]
	s_mov_b32 m0, s0
	s_nop 0
	global_load_lds_dwordx4 v[198:199], off
	v_lshl_add_u64 v[198:199], s[42:43], 0, v[134:135]
	s_add_i32 m0, s0, 0x2000
	s_nop 0
	global_load_lds_dwordx4 v[198:199], off
	v_lshl_add_u64 v[198:199], v[222:223], 0, s[10:11]
	s_mov_b32 m0, s25
	s_nop 0
	global_load_lds_dwordx4 v[198:199], off
	v_lshl_add_u64 v[198:199], v[224:225], 0, s[10:11]
	s_mov_b32 m0, s26
	s_nop 0
	global_load_lds_dwordx4 v[198:199], off
	s_waitcnt vmcnt(8)
	s_waitcnt lgkmcnt(0)
	s_barrier
	s_setprio 1
	s_waitcnt lgkmcnt(0)
	v_mfma_f32_16x16x32_bf16 v[60:63], v[144:147], v[182:185], v[60:63]
	v_mfma_f32_16x16x32_bf16 v[56:59], v[158:161], v[182:185], v[56:59]
	v_mfma_f32_16x16x32_bf16 v[44:47], v[144:147], v[190:193], v[44:47]
	v_mfma_f32_16x16x32_bf16 v[40:43], v[158:161], v[190:193], v[40:43]
	v_mfma_f32_16x16x32_bf16 v[28:31], v[144:147], v[202:205], v[28:31]
	v_mfma_f32_16x16x32_bf16 v[24:27], v[158:161], v[202:205], v[24:27]
	v_mfma_f32_16x16x32_bf16 v[12:15], v[144:147], v[212:215], v[12:15]
	v_mfma_f32_16x16x32_bf16 v[8:11], v[158:161], v[212:215], v[8:11]
	v_mfma_f32_16x16x32_bf16 v[60:63], v[154:157], v[186:189], v[60:63]
	v_mfma_f32_16x16x32_bf16 v[56:59], v[162:165], v[186:189], v[56:59]
	v_mfma_f32_16x16x32_bf16 v[44:47], v[154:157], v[194:197], v[44:47]
	v_mfma_f32_16x16x32_bf16 v[40:43], v[162:165], v[194:197], v[40:43]
	v_mfma_f32_16x16x32_bf16 v[28:31], v[154:157], v[208:211], v[28:31]
	v_mfma_f32_16x16x32_bf16 v[24:27], v[162:165], v[208:211], v[24:27]
	v_mfma_f32_16x16x32_bf16 v[12:15], v[154:157], v[216:219], v[12:15]
	v_mfma_f32_16x16x32_bf16 v[8:11], v[162:165], v[216:219], v[8:11]
	s_setprio 0
	s_setprio 1
	v_mfma_f32_16x16x32_bf16 v[52:55], v[166:169], v[182:185], v[52:55]
	v_mfma_f32_16x16x32_bf16 v[48:51], v[174:177], v[182:185], v[48:51]
	v_mfma_f32_16x16x32_bf16 v[36:39], v[166:169], v[190:193], v[36:39]
	v_mfma_f32_16x16x32_bf16 v[32:35], v[174:177], v[190:193], v[32:35]
	v_mfma_f32_16x16x32_bf16 v[20:23], v[166:169], v[202:205], v[20:23]
	v_mfma_f32_16x16x32_bf16 v[16:19], v[174:177], v[202:205], v[16:19]
	v_mfma_f32_16x16x32_bf16 v[4:7], v[166:169], v[212:215], v[4:7]
	v_mfma_f32_16x16x32_bf16 v[0:3], v[174:177], v[212:215], v[0:3]
	v_mfma_f32_16x16x32_bf16 v[52:55], v[170:173], v[186:189], v[52:55]
	v_mfma_f32_16x16x32_bf16 v[48:51], v[178:181], v[186:189], v[48:51]
	v_mfma_f32_16x16x32_bf16 v[36:39], v[170:173], v[194:197], v[36:39]
	v_mfma_f32_16x16x32_bf16 v[32:35], v[178:181], v[194:197], v[32:35]
	v_mfma_f32_16x16x32_bf16 v[20:23], v[170:173], v[208:211], v[20:23]
	v_mfma_f32_16x16x32_bf16 v[16:19], v[178:181], v[208:211], v[16:19]
	v_mfma_f32_16x16x32_bf16 v[4:7], v[170:173], v[216:219], v[4:7]
	v_mfma_f32_16x16x32_bf16 v[0:3], v[178:181], v[216:219], v[0:3]
	s_add_i32 s61, s61, 2
	s_add_u32 s40, s40, 0x100
	s_addc_u32 s41, s41, 0
	s_add_u32 s55, s55, 0x100
	s_addc_u32 s60, s60, 0
	s_cmp_gt_u32 s61, 29
	s_setprio 0
	s_barrier
	s_cbranch_scc0 .LBB0_710
	s_and_b64 vcc, exec, s[14:15]
	s_cbranch_vccz .LBB0_713
	s_barrier

; #define PG8_STAGE(bufoff, gbase, voff) do { _Pragma("unroll") for (int _i = 0; _i < 2; ++_i) \
;         __builtin_amdgcn_global_load_lds((const unsigned*)((const char*)(gbase) + (voff)[_i]), (PG8_LAS unsigned*)(lds + (bufoff) + ldsw + _i * 8192), 16, 0, 0); } while (0)
; #define PG8_LDA(dst, b, h) do { _Pragma("unroll") for (int m = 0; m < 4; ++m) _Pragma("unroll") for (int k = 0; k < 2; ++k) dst[m][k] = *(const PG8_LAS bf16x8*)(lds + PG8_SA(b, h) + aoff + m * 2048 + k * 1024); } while (0)
; #define PG8_LDB(dst, b, h) do { _Pragma("unroll") for (int n = 0; n < 2; ++n) _Pragma("unroll") for (int k = 0; k < 2; ++k) dst[n][k] = *(const PG8_LAS bf16x8*)(lds + PG8_SB(b, h) + boff + n * 2048 + k * 1024); } while (0)
; #define PG8_MMA(ai, bj, At, Bt) do { __builtin_amdgcn_s_setprio(1); _Pragma("unroll") for (int m = 0; m < 4; ++m) _Pragma("unroll") for (int n = 0; n < 2; ++n) _Pragma("unroll") for (int k = 0; k < 2; ++k) \
;         acc[ai][bj][m][n] = __builtin_amdgcn_mfma_f32_16x16x32_bf16(Bt[n][k], At[m][k], acc[ai][bj][m][n], 0, 0, 0); __builtin_amdgcn_s_setprio(0); } while (0)
; #define PG8_WAIT_V(n) asm volatile("s_waitcnt vmcnt(" #n ")" ::: "memory")
; #define PG8_WAIT_L(n) asm volatile("s_waitcnt lgkmcnt(" #n ")" ::: "memory")
; #define PG8_BAR __builtin_amdgcn_s_barrier()
; #define PG8_SCHED __builtin_amdgcn_sched_barrier(0)
; template <class Epi, class Sched, bool ALIGN_EPI = false, bool SP2 = false>
; __device__ __forceinline__ void gemm_phase(PG8_LAS unsigned char* lds, const Gemm g, const Sched& S, const Epi& E, int wave_s) {
;     ...
;         for (int t = 0; t < nt; t += 2) {
;             const bool last = (t == nt - 2);
;             const char* a1 = cA + (size_t)(t + 1) * kstep;
;             const char* a2 = last ? nA : cA + (size_t)(t + 2) * kstep; const char* b2 = last ? nB : cB + (size_t)(t + 2) * kstep;
;             const char* a3 = a2 + kstep; const char* b3 = b2 + kstep;
;             if (last && has_next) S.a_ready(nxt);
;             if constexpr (SP2) {
;             PG8_LDB(B0, 0, 0); PG8_LDB(B1, 0, 1); PG8_SCHED; PG8_LDA(At, 0, 0); PG8_STAGE(PG8_SA(1, 1), a1 + hstep, voffA);
;             PG8_WAIT_V(8); PG8_WAIT_L(0); PG8_BAR; PG8_MMA(0, 0, At, B0); PG8_MMA(0, 1, At, B1); PG8_BAR; PG8_SCHED;
;             PG8_LDA(At, 0, 1); PG8_STAGE(PG8_SB(0, 0), b2, voffB); PG8_STAGE(PG8_SB(0, 1), b2 + hstep, voffB); PG8_STAGE(PG8_SA(0, 0), a2, voffA);
.LBB0_755:
	ds_read_b128 v[150:153], v147
	ds_read_b128 v[154:157], v147 offset:1024
	ds_read_b128 v[158:161], v147 offset:2048
	ds_read_b128 v[162:165], v147 offset:3072
	ds_read_b128 v[166:169], v148
	ds_read_b128 v[170:173], v148 offset:1024
	ds_read_b128 v[174:177], v148 offset:2048
	ds_read_b128 v[178:181], v148 offset:3072
	s_add_i32 s66, s36, 2
	s_add_u32 s0, s34, 0x80
	s_addc_u32 s1, s35, 0
	s_cmp_eq_u32 s40, s36
	s_cselect_b32 s36, s4, s0
	s_cselect_b32 s37, s5, s1
	s_cselect_b32 s71, s31, s61
	s_cselect_b32 s70, s30, s60
	v_lshl_add_u64 v[198:199], s[34:35], 0, v[136:137]
	s_add_i32 m0, s23, 0xc000
	ds_read_b128 v[182:185], v149
	ds_read_b128 v[186:189], v149 offset:1024
	ds_read_b128 v[190:193], v149 offset:2048
	ds_read_b128 v[194:197], v149 offset:3072
	ds_read_b128 v[202:205], v149 offset:4096
	ds_read_b128 v[208:211], v149 offset:5120
	ds_read_b128 v[212:215], v149 offset:6144
	ds_read_b128 v[216:219], v149 offset:7168
	global_load_lds_dwordx4 v[198:199], off
	v_lshl_add_u64 v[198:199], s[34:35], 0, v[138:139]
	s_add_i32 m0, s23, 0xe000
	s_nop 0
	global_load_lds_dwordx4 v[198:199], off
	s_waitcnt vmcnt(8)
	s_waitcnt lgkmcnt(0)
	s_barrier
	s_setprio 1
	s_waitcnt lgkmcnt(0)
	v_mfma_f32_16x16x32_bf16 v[120:123], v[150:153], v[182:185], v[120:123]
	v_mfma_f32_16x16x32_bf16 v[124:127], v[158:161], v[182:185], v[124:127]
	v_mfma_f32_16x16x32_bf16 v[108:111], v[150:153], v[190:193], v[108:111]
	v_mfma_f32_16x16x32_bf16 v[104:107], v[158:161], v[190:193], v[104:107]
	v_mfma_f32_16x16x32_bf16 v[92:95], v[150:153], v[202:205], v[92:95]
	v_mfma_f32_16x16x32_bf16 v[88:91], v[158:161], v[202:205], v[88:91]
	v_mfma_f32_16x16x32_bf16 v[76:79], v[150:153], v[212:215], v[76:79]
	v_mfma_f32_16x16x32_bf16 v[72:75], v[158:161], v[212:215], v[72:75]
	v_mfma_f32_16x16x32_bf16 v[120:123], v[154:157], v[186:189], v[120:123]
	v_mfma_f32_16x16x32_bf16 v[124:127], v[162:165], v[186:189], v[124:127]
	v_mfma_f32_16x16x32_bf16 v[108:111], v[154:157], v[194:197], v[108:111]
	v_mfma_f32_16x16x32_bf16 v[104:107], v[162:165], v[194:197], v[104:107]
	v_mfma_f32_16x16x32_bf16 v[92:95], v[154:157], v[208:211], v[92:95]
	v_mfma_f32_16x16x32_bf16 v[88:91], v[162:165], v[208:211], v[88:91]
	v_mfma_f32_16x16x32_bf16 v[76:79], v[154:157], v[216:219], v[76:79]
	v_mfma_f32_16x16x32_bf16 v[72:75], v[162:165], v[216:219], v[72:75]
	s_setprio 0
	s_setprio 1
	v_mfma_f32_16x16x32_bf16 v[116:119], v[166:169], v[182:185], v[116:119]
	v_mfma_f32_16x16x32_bf16 v[112:115], v[174:177], v[182:185], v[112:115]
	v_mfma_f32_16x16x32_bf16 v[100:103], v[166:169], v[190:193], v[100:103]
	v_mfma_f32_16x16x32_bf16 v[96:99], v[174:177], v[190:193], v[96:99]
	v_mfma_f32_16x16x32_bf16 v[84:87], v[166:169], v[202:205], v[84:87]
	v_mfma_f32_16x16x32_bf16 v[80:83], v[174:177], v[202:205], v[80:83]
	v_mfma_f32_16x16x32_bf16 v[68:71], v[166:169], v[212:215], v[68:71]
	v_mfma_f32_16x16x32_bf16 v[64:67], v[174:177], v[212:215], v[64:67]
	v_mfma_f32_16x16x32_bf16 v[116:119], v[170:173], v[186:189], v[116:119]
	v_mfma_f32_16x16x32_bf16 v[112:115], v[178:181], v[186:189], v[112:115]
	v_mfma_f32_16x16x32_bf16 v[100:103], v[170:173], v[194:197], v[100:103]
	v_mfma_f32_16x16x32_bf16 v[96:99], v[178:181], v[194:197], v[96:99]
	v_mfma_f32_16x16x32_bf16 v[84:87], v[170:173], v[208:211], v[84:87]
	v_mfma_f32_16x16x32_bf16 v[80:83], v[178:181], v[208:211], v[80:83]
	v_mfma_f32_16x16x32_bf16 v[68:71], v[170:173], v[216:219], v[68:71]
	v_mfma_f32_16x16x32_bf16 v[64:67], v[178:181], v[216:219], v[64:67]
	s_setprio 0
	s_barrier
	s_add_i32 s0, s43, s20
	v_lshl_add_u64 v[198:199], s[70:71], 0, v[130:131]
	s_mov_b32 m0, s0
	ds_read_b128 v[182:185], v149 offset:16384
	ds_read_b128 v[186:189], v149 offset:17408
	ds_read_b128 v[190:193], v149 offset:18432
	ds_read_b128 v[194:197], v149 offset:19456
	ds_read_b128 v[202:205], v149 offset:20480
	ds_read_b128 v[208:211], v149 offset:21504
	ds_read_b128 v[212:215], v149 offset:22528
	ds_read_b128 v[216:219], v149 offset:23552
	global_load_lds_dwordx4 v[198:199], off
	s_add_i32 m0, s0, 0x2000
	v_lshl_add_u64 v[220:221], s[70:71], 0, v[134:135]
	s_add_u32 s70, s70, s6
	s_addc_u32 s71, s71, s7
	s_add_i32 s0, s44, s20
	global_load_lds_dwordx4 v[220:221], off
	v_lshl_add_u64 v[222:223], s[70:71], 0, v[130:131]
	s_mov_b32 m0, s0
	v_lshl_add_u64 v[224:225], s[70:71], 0, v[134:135]
	global_load_lds_dwordx4 v[222:223], off
	s_add_i32 m0, s0, 0x2000
	v_lshl_add_u64 v[226:227], s[36:37], 0, v[128:129]
	global_load_lds_dwordx4 v[224:225], off
	s_mov_b32 m0, s23
	v_lshl_add_u64 v[228:229], s[36:37], 0, v[132:133]
	global_load_lds_dwordx4 v[226:227], off
	s_mov_b32 m0, s24
	s_nop 0
	global_load_lds_dwordx4 v[228:229], off
	s_waitcnt vmcnt(8)
	s_waitcnt lgkmcnt(0)
	s_barrier
; #define PG8_STAGE(bufoff, gbase, voff) do { _Pragma("unroll") for (int _i = 0; _i < 2; ++_i) \
;         __builtin_amdgcn_global_load_lds((const unsigned*)((const char*)(gbase) + (voff)[_i]), (PG8_LAS unsigned*)(lds + (bufoff) + ldsw + _i * 8192), 16, 0, 0); } while (0)
; #define PG8_LDA(dst, b, h) do { _Pragma("unroll") for (int m = 0; m < 4; ++m) _Pragma("unroll") for (int k = 0; k < 2; ++k) dst[m][k] = *(const PG8_LAS bf16x8*)(lds + PG8_SA(b, h) + aoff + m * 2048 + k * 1024); } while (0)
; #define PG8_LDB(dst, b, h) do { _Pragma("unroll") for (int n = 0; n < 2; ++n) _Pragma("unroll") for (int k = 0; k < 2; ++k) dst[n][k] = *(const PG8_LAS bf16x8*)(lds + PG8_SB(b, h) + boff + n * 2048 + k * 1024); } while (0)
; #define PG8_MMA(ai, bj, At, Bt) do { __builtin_amdgcn_s_setprio(1); _Pragma("unroll") for (int m = 0; m < 4; ++m) _Pragma("unroll") for (int n = 0; n < 2; ++n) _Pragma("unroll") for (int k = 0; k < 2; ++k) \
;         acc[ai][bj][m][n] = __builtin_amdgcn_mfma_f32_16x16x32_bf16(Bt[n][k], At[m][k], acc[ai][bj][m][n], 0, 0, 0); __builtin_amdgcn_s_setprio(0); } while (0)
; #define PG8_WAIT_V(n) asm volatile("s_waitcnt vmcnt(" #n ")" ::: "memory")
; #define PG8_WAIT_L(n) asm volatile("s_waitcnt lgkmcnt(" #n ")" ::: "memory")
; #define PG8_BAR __builtin_amdgcn_s_barrier()
; #define PG8_SCHED __builtin_amdgcn_sched_barrier(0)
; template <class Epi, class Sched, bool ALIGN_EPI = false, bool SP2 = false>
; __device__ __forceinline__ void gemm_phase(PG8_LAS unsigned char* lds, const Gemm g, const Sched& S, const Epi& E, int wave_s) {
;     ...
;             PG8_WAIT_V(8); PG8_WAIT_L(0); PG8_BAR; PG8_MMA(1, 0, At, B0); PG8_MMA(1, 1, At, B1); PG8_BAR; PG8_SCHED;
;             PG8_LDB(B0, 1, 0); PG8_LDB(B1, 1, 1); PG8_SCHED; PG8_LDA(At, 1, 0); PG8_STAGE(PG8_SA(0, 1), a2 + hstep, voffA);
;             PG8_WAIT_V(8); PG8_WAIT_L(0); PG8_BAR; PG8_MMA(0, 0, At, B0); PG8_MMA(0, 1, At, B1); PG8_BAR; PG8_SCHED;
	s_setprio 1
	s_waitcnt lgkmcnt(0)
	v_mfma_f32_16x16x32_bf16 v[60:63], v[150:153], v[182:185], v[60:63]
	v_mfma_f32_16x16x32_bf16 v[56:59], v[158:161], v[182:185], v[56:59]
	v_mfma_f32_16x16x32_bf16 v[44:47], v[150:153], v[190:193], v[44:47]
	v_mfma_f32_16x16x32_bf16 v[40:43], v[158:161], v[190:193], v[40:43]
	v_mfma_f32_16x16x32_bf16 v[28:31], v[150:153], v[202:205], v[28:31]
	v_mfma_f32_16x16x32_bf16 v[24:27], v[158:161], v[202:205], v[24:27]
	v_mfma_f32_16x16x32_bf16 v[12:15], v[150:153], v[212:215], v[12:15]
	v_mfma_f32_16x16x32_bf16 v[8:11], v[158:161], v[212:215], v[8:11]
	v_mfma_f32_16x16x32_bf16 v[60:63], v[154:157], v[186:189], v[60:63]
	v_mfma_f32_16x16x32_bf16 v[56:59], v[162:165], v[186:189], v[56:59]
	v_mfma_f32_16x16x32_bf16 v[44:47], v[154:157], v[194:197], v[44:47]
	v_mfma_f32_16x16x32_bf16 v[40:43], v[162:165], v[194:197], v[40:43]
	v_mfma_f32_16x16x32_bf16 v[28:31], v[154:157], v[208:211], v[28:31]
	v_mfma_f32_16x16x32_bf16 v[24:27], v[162:165], v[208:211], v[24:27]
	v_mfma_f32_16x16x32_bf16 v[12:15], v[154:157], v[216:219], v[12:15]
	v_mfma_f32_16x16x32_bf16 v[8:11], v[162:165], v[216:219], v[8:11]
	s_setprio 0
	s_setprio 1
	v_mfma_f32_16x16x32_bf16 v[52:55], v[166:169], v[182:185], v[52:55]
	v_mfma_f32_16x16x32_bf16 v[48:51], v[174:177], v[182:185], v[48:51]
	v_mfma_f32_16x16x32_bf16 v[36:39], v[166:169], v[190:193], v[36:39]
	v_mfma_f32_16x16x32_bf16 v[32:35], v[174:177], v[190:193], v[32:35]
	v_mfma_f32_16x16x32_bf16 v[20:23], v[166:169], v[202:205], v[20:23]
	v_mfma_f32_16x16x32_bf16 v[16:19], v[174:177], v[202:205], v[16:19]
	v_mfma_f32_16x16x32_bf16 v[4:7], v[166:169], v[212:215], v[4:7]
	v_mfma_f32_16x16x32_bf16 v[0:3], v[174:177], v[212:215], v[0:3]
	v_mfma_f32_16x16x32_bf16 v[52:55], v[170:173], v[186:189], v[52:55]
	v_mfma_f32_16x16x32_bf16 v[48:51], v[178:181], v[186:189], v[48:51]
	v_mfma_f32_16x16x32_bf16 v[36:39], v[170:173], v[194:197], v[36:39]
	v_mfma_f32_16x16x32_bf16 v[32:35], v[178:181], v[194:197], v[32:35]
	v_mfma_f32_16x16x32_bf16 v[20:23], v[170:173], v[208:211], v[20:23]
	v_mfma_f32_16x16x32_bf16 v[16:19], v[178:181], v[208:211], v[16:19]
	v_mfma_f32_16x16x32_bf16 v[4:7], v[170:173], v[216:219], v[4:7]
	v_mfma_f32_16x16x32_bf16 v[0:3], v[178:181], v[216:219], v[0:3]
	s_setprio 0
	s_barrier
	s_add_i32 s0, 0, 0x18000
	s_add_i32 s1, 0, 0x1c000
	v_add_u32_e32 v162, s0, v145
	v_add_u32_e32 v178, s1, v145
	ds_read_b128 v[150:153], v162
	ds_read_b128 v[154:157], v162 offset:1024
	ds_read_b128 v[158:161], v162 offset:2048
	ds_read_b128 v[162:165], v162 offset:3072
	ds_read_b128 v[166:169], v178
	ds_read_b128 v[170:173], v178 offset:1024
	ds_read_b128 v[174:177], v178 offset:2048
	ds_read_b128 v[178:181], v178 offset:3072
	s_add_u32 s36, s36, s6
	s_addc_u32 s37, s37, s7
	s_mov_b32 m0, s25
	v_lshl_add_u64 v[230:231], s[36:37], 0, v[128:129]
	ds_read_b128 v[182:185], v149 offset:32768
	ds_read_b128 v[186:189], v149 offset:33792
	ds_read_b128 v[190:193], v149 offset:34816
	ds_read_b128 v[194:197], v149 offset:35840
	ds_read_b128 v[202:205], v149 offset:36864
	ds_read_b128 v[208:211], v149 offset:37888
	ds_read_b128 v[212:215], v149 offset:38912
	ds_read_b128 v[216:219], v149 offset:39936
	global_load_lds_dwordx4 v[230:231], off
	v_lshl_add_u64 v[230:231], s[36:37], 0, v[132:133]
	s_mov_b32 m0, s26
	s_nop 0
	global_load_lds_dwordx4 v[230:231], off
	s_waitcnt vmcnt(8)
	s_waitcnt lgkmcnt(0)
	s_barrier
	s_setprio 1
	s_waitcnt lgkmcnt(0)
	v_mfma_f32_16x16x32_bf16 v[120:123], v[150:153], v[182:185], v[120:123]
	v_mfma_f32_16x16x32_bf16 v[124:127], v[158:161], v[182:185], v[124:127]
	v_mfma_f32_16x16x32_bf16 v[108:111], v[150:153], v[190:193], v[108:111]
	v_mfma_f32_16x16x32_bf16 v[104:107], v[158:161], v[190:193], v[104:107]
	v_mfma_f32_16x16x32_bf16 v[92:95], v[150:153], v[202:205], v[92:95]
	v_mfma_f32_16x16x32_bf16 v[88:91], v[158:161], v[202:205], v[88:91]
	v_mfma_f32_16x16x32_bf16 v[76:79], v[150:153], v[212:215], v[76:79]
	v_mfma_f32_16x16x32_bf16 v[72:75], v[158:161], v[212:215], v[72:75]
	v_mfma_f32_16x16x32_bf16 v[120:123], v[154:157], v[186:189], v[120:123]
	v_mfma_f32_16x16x32_bf16 v[124:127], v[162:165], v[186:189], v[124:127]
	v_mfma_f32_16x16x32_bf16 v[108:111], v[154:157], v[194:197], v[108:111]
	v_mfma_f32_16x16x32_bf16 v[104:107], v[162:165], v[194:197], v[104:107]
	v_mfma_f32_16x16x32_bf16 v[92:95], v[154:157], v[208:211], v[92:95]
	v_mfma_f32_16x16x32_bf16 v[88:91], v[162:165], v[208:211], v[88:91]
	v_mfma_f32_16x16x32_bf16 v[76:79], v[154:157], v[216:219], v[76:79]
	v_mfma_f32_16x16x32_bf16 v[72:75], v[162:165], v[216:219], v[72:75]
	s_setprio 0
	s_setprio 1
	v_mfma_f32_16x16x32_bf16 v[116:119], v[166:169], v[182:185], v[116:119]
	v_mfma_f32_16x16x32_bf16 v[112:115], v[174:177], v[182:185], v[112:115]
	v_mfma_f32_16x16x32_bf16 v[100:103], v[166:169], v[190:193], v[100:103]
	v_mfma_f32_16x16x32_bf16 v[96:99], v[174:177], v[190:193], v[96:99]
	v_mfma_f32_16x16x32_bf16 v[84:87], v[166:169], v[202:205], v[84:87]
	v_mfma_f32_16x16x32_bf16 v[80:83], v[174:177], v[202:205], v[80:83]
	v_mfma_f32_16x16x32_bf16 v[68:71], v[166:169], v[212:215], v[68:71]
	v_mfma_f32_16x16x32_bf16 v[64:67], v[174:177], v[212:215], v[64:67]
	v_mfma_f32_16x16x32_bf16 v[116:119], v[170:173], v[186:189], v[116:119]
	v_mfma_f32_16x16x32_bf16 v[112:115], v[178:181], v[186:189], v[112:115]
	v_mfma_f32_16x16x32_bf16 v[100:103], v[170:173], v[194:197], v[100:103]
	v_mfma_f32_16x16x32_bf16 v[96:99], v[178:181], v[194:197], v[96:99]
	v_mfma_f32_16x16x32_bf16 v[84:87], v[170:173], v[208:211], v[84:87]
	v_mfma_f32_16x16x32_bf16 v[80:83], v[178:181], v[208:211], v[80:83]
	v_mfma_f32_16x16x32_bf16 v[68:71], v[170:173], v[216:219], v[68:71]
	v_mfma_f32_16x16x32_bf16 v[64:67], v[178:181], v[216:219], v[64:67]
	s_setprio 0
	s_barrier
; #define PG8_STAGE(bufoff, gbase, voff) do { _Pragma("unroll") for (int _i = 0; _i < 2; ++_i) \
;         __builtin_amdgcn_global_load_lds((const unsigned*)((const char*)(gbase) + (voff)[_i]), (PG8_LAS unsigned*)(lds + (bufoff) + ldsw + _i * 8192), 16, 0, 0); } while (0)
; #define PG8_LDA(dst, b, h) do { _Pragma("unroll") for (int m = 0; m < 4; ++m) _Pragma("unroll") for (int k = 0; k < 2; ++k) dst[m][k] = *(const PG8_LAS bf16x8*)(lds + PG8_SA(b, h) + aoff + m * 2048 + k * 1024); } while (0)
; #define PG8_MMA(ai, bj, At, Bt) do { __builtin_amdgcn_s_setprio(1); _Pragma("unroll") for (int m = 0; m < 4; ++m) _Pragma("unroll") for (int n = 0; n < 2; ++n) _Pragma("unroll") for (int k = 0; k < 2; ++k) \
;         acc[ai][bj][m][n] = __builtin_amdgcn_mfma_f32_16x16x32_bf16(Bt[n][k], At[m][k], acc[ai][bj][m][n], 0, 0, 0); __builtin_amdgcn_s_setprio(0); } while (0)
; #define PG8_WAIT_V(n) asm volatile("s_waitcnt vmcnt(" #n ")" ::: "memory")
; #define PG8_WAIT_L(n) asm volatile("s_waitcnt lgkmcnt(" #n ")" ::: "memory")
; #define PG8_BAR __builtin_amdgcn_s_barrier()
; #define PG8_SCHED __builtin_amdgcn_sched_barrier(0)
; template <class Epi, class Sched, bool ALIGN_EPI = false, bool SP2 = false>
; __device__ __forceinline__ void gemm_phase(PG8_LAS unsigned char* lds, const Gemm g, const Sched& S, const Epi& E, int wave_s) {
;     ...
;         for (int t = 0; t < nt; t += 2) {
;             const bool last = (t == nt - 2);
;     ...
;             PG8_LDA(At, 1, 1); PG8_STAGE(PG8_SB(1, 0), b3, voffB); PG8_STAGE(PG8_SB(1, 1), b3 + hstep, voffB); PG8_STAGE(PG8_SA(1, 0), a3, voffA);
;             PG8_WAIT_V(8); PG8_WAIT_L(0); PG8_BAR; PG8_MMA(1, 0, At, B0); PG8_MMA(1, 1, At, B1); PG8_BAR; PG8_SCHED;
	s_add_i32 s0, s0, s20
	v_lshl_add_u64 v[198:199], v[198:199], 0, s[14:15]
	s_mov_b32 m0, s0
	ds_read_b128 v[182:185], v149 offset:49152
	ds_read_b128 v[186:189], v149 offset:50176
	ds_read_b128 v[190:193], v149 offset:51200
	ds_read_b128 v[194:197], v149 offset:52224
	ds_read_b128 v[202:205], v149 offset:53248
	ds_read_b128 v[208:211], v149 offset:54272
	ds_read_b128 v[212:215], v149 offset:55296
	ds_read_b128 v[216:219], v149 offset:56320
	global_load_lds_dwordx4 v[198:199], off
	v_lshl_add_u64 v[198:199], v[220:221], 0, s[14:15]
	s_add_i32 m0, s0, 0x2000
	s_add_i32 s0, s1, s20
	global_load_lds_dwordx4 v[198:199], off
	v_lshl_add_u64 v[198:199], v[222:223], 0, s[14:15]
	s_mov_b32 m0, s0
	s_nop 0
	global_load_lds_dwordx4 v[198:199], off
	v_lshl_add_u64 v[198:199], v[224:225], 0, s[14:15]
	s_add_i32 m0, s0, 0x2000
	s_nop 0
	global_load_lds_dwordx4 v[198:199], off
	v_lshl_add_u64 v[198:199], v[226:227], 0, s[14:15]
	s_mov_b32 m0, s33
	s_nop 0
	global_load_lds_dwordx4 v[198:199], off
	v_lshl_add_u64 v[198:199], v[228:229], 0, s[14:15]
	s_mov_b32 m0, s38
	s_nop 0
	global_load_lds_dwordx4 v[198:199], off
	s_waitcnt vmcnt(8)
	s_waitcnt lgkmcnt(0)
	s_barrier
	s_setprio 1
	s_waitcnt lgkmcnt(0)
	v_mfma_f32_16x16x32_bf16 v[60:63], v[150:153], v[182:185], v[60:63]
	v_mfma_f32_16x16x32_bf16 v[56:59], v[158:161], v[182:185], v[56:59]
	v_mfma_f32_16x16x32_bf16 v[44:47], v[150:153], v[190:193], v[44:47]
	v_mfma_f32_16x16x32_bf16 v[40:43], v[158:161], v[190:193], v[40:43]
	v_mfma_f32_16x16x32_bf16 v[28:31], v[150:153], v[202:205], v[28:31]
	v_mfma_f32_16x16x32_bf16 v[24:27], v[158:161], v[202:205], v[24:27]
	v_mfma_f32_16x16x32_bf16 v[12:15], v[150:153], v[212:215], v[12:15]
	v_mfma_f32_16x16x32_bf16 v[8:11], v[158:161], v[212:215], v[8:11]
	v_mfma_f32_16x16x32_bf16 v[60:63], v[154:157], v[186:189], v[60:63]
	v_mfma_f32_16x16x32_bf16 v[56:59], v[162:165], v[186:189], v[56:59]
	v_mfma_f32_16x16x32_bf16 v[44:47], v[154:157], v[194:197], v[44:47]
	v_mfma_f32_16x16x32_bf16 v[40:43], v[162:165], v[194:197], v[40:43]
	v_mfma_f32_16x16x32_bf16 v[28:31], v[154:157], v[208:211], v[28:31]
	v_mfma_f32_16x16x32_bf16 v[24:27], v[162:165], v[208:211], v[24:27]
	v_mfma_f32_16x16x32_bf16 v[12:15], v[154:157], v[216:219], v[12:15]
	v_mfma_f32_16x16x32_bf16 v[8:11], v[162:165], v[216:219], v[8:11]
	s_setprio 0
	s_setprio 1
	v_mfma_f32_16x16x32_bf16 v[52:55], v[166:169], v[182:185], v[52:55]
	v_mfma_f32_16x16x32_bf16 v[48:51], v[174:177], v[182:185], v[48:51]
	v_mfma_f32_16x16x32_bf16 v[36:39], v[166:169], v[190:193], v[36:39]
	v_mfma_f32_16x16x32_bf16 v[32:35], v[174:177], v[190:193], v[32:35]
	v_mfma_f32_16x16x32_bf16 v[20:23], v[166:169], v[202:205], v[20:23]
	v_mfma_f32_16x16x32_bf16 v[16:19], v[174:177], v[202:205], v[16:19]
	v_mfma_f32_16x16x32_bf16 v[4:7], v[166:169], v[212:215], v[4:7]
	v_mfma_f32_16x16x32_bf16 v[0:3], v[174:177], v[212:215], v[0:3]
	v_mfma_f32_16x16x32_bf16 v[52:55], v[170:173], v[186:189], v[52:55]
	v_mfma_f32_16x16x32_bf16 v[48:51], v[178:181], v[186:189], v[48:51]
	v_mfma_f32_16x16x32_bf16 v[36:39], v[170:173], v[194:197], v[36:39]
	v_mfma_f32_16x16x32_bf16 v[32:35], v[178:181], v[194:197], v[32:35]
	v_mfma_f32_16x16x32_bf16 v[20:23], v[170:173], v[208:211], v[20:23]
	v_mfma_f32_16x16x32_bf16 v[16:19], v[178:181], v[208:211], v[16:19]
	v_mfma_f32_16x16x32_bf16 v[4:7], v[170:173], v[216:219], v[4:7]
	v_mfma_f32_16x16x32_bf16 v[0:3], v[178:181], v[216:219], v[0:3]
	s_add_u32 s34, s34, 0x100
	s_addc_u32 s35, s35, 0
	s_add_u32 s60, s60, 0x100
	s_addc_u32 s61, s61, 0
	s_cmp_ge_i32 s66, s39
	s_mov_b32 s36, s66
	s_setprio 0
	s_barrier
	s_cbranch_scc0 .LBB0_755

; #define PG8_STAGE(bufoff, gbase, voff) do { _Pragma("unroll") for (int _i = 0; _i < 2; ++_i) \
;         __builtin_amdgcn_global_load_lds((const unsigned*)((const char*)(gbase) + (voff)[_i]), (PG8_LAS unsigned*)(lds + (bufoff) + ldsw + _i * 8192), 16, 0, 0); } while (0)
; #define PG8_LDA(dst, b, h) do { _Pragma("unroll") for (int m = 0; m < 4; ++m) _Pragma("unroll") for (int k = 0; k < 2; ++k) dst[m][k] = *(const PG8_LAS bf16x8*)(lds + PG8_SA(b, h) + aoff + m * 2048 + k * 1024); } while (0)
; #define PG8_LDB(dst, b, h) do { _Pragma("unroll") for (int n = 0; n < 2; ++n) _Pragma("unroll") for (int k = 0; k < 2; ++k) dst[n][k] = *(const PG8_LAS bf16x8*)(lds + PG8_SB(b, h) + boff + n * 2048 + k * 1024); } while (0)
; #define PG8_MMA(ai, bj, At, Bt) do { __builtin_amdgcn_s_setprio(1); _Pragma("unroll") for (int m = 0; m < 4; ++m) _Pragma("unroll") for (int n = 0; n < 2; ++n) _Pragma("unroll") for (int k = 0; k < 2; ++k) \
;         acc[ai][bj][m][n] = __builtin_amdgcn_mfma_f32_16x16x32_bf16(Bt[n][k], At[m][k], acc[ai][bj][m][n], 0, 0, 0); __builtin_amdgcn_s_setprio(0); } while (0)
; #define PG8_WAIT_V(n) asm volatile("s_waitcnt vmcnt(" #n ")" ::: "memory")
; #define PG8_WAIT_L(n) asm volatile("s_waitcnt lgkmcnt(" #n ")" ::: "memory")
; #define PG8_BAR __builtin_amdgcn_s_barrier()
; #define PG8_SCHED __builtin_amdgcn_sched_barrier(0)
; template <class Epi, class Sched, bool ALIGN_EPI = false, bool SP2 = false>
; __device__ __forceinline__ void gemm_phase(PG8_LAS unsigned char* lds, const Gemm g, const Sched& S, const Epi& E, int wave_s) {
;     ...
;         for (int t = 0; t < nt; t += 2) {
;             const bool last = (t == nt - 2);
;             const char* a1 = cA + (size_t)(t + 1) * kstep;
;             const char* a2 = last ? nA : cA + (size_t)(t + 2) * kstep; const char* b2 = last ? nB : cB + (size_t)(t + 2) * kstep;
;             const char* a3 = a2 + kstep; const char* b3 = b2 + kstep;
;             if (last && has_next) S.a_ready(nxt);
;             if constexpr (SP2) {
;             PG8_LDB(B0, 0, 0); PG8_LDB(B1, 0, 1); PG8_SCHED; PG8_LDA(At, 0, 0); PG8_STAGE(PG8_SA(1, 1), a1 + hstep, voffA);
;             PG8_WAIT_V(8); PG8_WAIT_L(0); PG8_BAR; PG8_MMA(0, 0, At, B0); PG8_MMA(0, 1, At, B1); PG8_BAR; PG8_SCHED;
;             PG8_LDA(At, 0, 1); PG8_STAGE(PG8_SB(0, 0), b2, voffB); PG8_STAGE(PG8_SB(0, 1), b2 + hstep, voffB); PG8_STAGE(PG8_SA(0, 0), a2, voffA);
.LBB0_893:
	ds_read_b128 v[32:35], v195
	ds_read_b128 v[36:39], v195 offset:1024
	ds_read_b128 v[48:51], v195 offset:2048
	ds_read_b128 v[52:55], v195 offset:3072
	ds_read_b128 v[160:163], v196
	ds_read_b128 v[164:167], v196 offset:1024
	ds_read_b128 v[168:171], v196 offset:2048
	ds_read_b128 v[172:175], v196 offset:3072
	s_add_u32 s0, s40, 0xfff80080
	s_addc_u32 s1, s41, -1
	s_cmp_eq_u32 s67, 28
	s_cselect_b32 s45, s2, s1
	s_cselect_b32 s44, s3, s0
	s_cselect_b32 s43, s9, s66
	s_cselect_b32 s42, s31, s35
	v_lshl_add_u64 v[198:199], s[40:41], 0, v[152:153]
	s_add_i32 m0, s20, 0xc000
	ds_read_b128 v[176:179], v197
	ds_read_b128 v[180:183], v197 offset:1024
	ds_read_b128 v[184:187], v197 offset:2048
	ds_read_b128 v[188:191], v197 offset:3072
	ds_read_b128 v[202:205], v197 offset:4096
	ds_read_b128 v[208:211], v197 offset:5120
	ds_read_b128 v[212:215], v197 offset:6144
	ds_read_b128 v[216:219], v197 offset:7168
	global_load_lds_dwordx4 v[198:199], off
	v_lshl_add_u64 v[198:199], s[40:41], 0, v[154:155]
	s_add_i32 m0, s20, 0xe000
	s_nop 0
	global_load_lds_dwordx4 v[198:199], off
	s_waitcnt vmcnt(8)
	s_waitcnt lgkmcnt(0)
	s_barrier
	s_setprio 1
	s_waitcnt lgkmcnt(0)
	v_mfma_f32_16x16x32_bf16 v[140:143], v[32:35], v[176:179], v[140:143]
	v_mfma_f32_16x16x32_bf16 v[136:139], v[48:51], v[176:179], v[136:139]
	v_mfma_f32_16x16x32_bf16 v[124:127], v[32:35], v[184:187], v[124:127]
	v_mfma_f32_16x16x32_bf16 v[120:123], v[48:51], v[184:187], v[120:123]
	v_mfma_f32_16x16x32_bf16 v[108:111], v[32:35], v[202:205], v[108:111]
	v_mfma_f32_16x16x32_bf16 v[104:107], v[48:51], v[202:205], v[104:107]
	v_mfma_f32_16x16x32_bf16 v[92:95], v[32:35], v[212:215], v[92:95]
	v_mfma_f32_16x16x32_bf16 v[88:91], v[48:51], v[212:215], v[88:91]
	v_mfma_f32_16x16x32_bf16 v[140:143], v[36:39], v[180:183], v[140:143]
	v_mfma_f32_16x16x32_bf16 v[136:139], v[52:55], v[180:183], v[136:139]
	v_mfma_f32_16x16x32_bf16 v[124:127], v[36:39], v[188:191], v[124:127]
	v_mfma_f32_16x16x32_bf16 v[120:123], v[52:55], v[188:191], v[120:123]
	v_mfma_f32_16x16x32_bf16 v[108:111], v[36:39], v[208:211], v[108:111]
	v_mfma_f32_16x16x32_bf16 v[104:107], v[52:55], v[208:211], v[104:107]
	v_mfma_f32_16x16x32_bf16 v[92:95], v[36:39], v[216:219], v[92:95]
	v_mfma_f32_16x16x32_bf16 v[88:91], v[52:55], v[216:219], v[88:91]
	s_setprio 0
	s_setprio 1
	v_mfma_f32_16x16x32_bf16 v[132:135], v[160:163], v[176:179], v[132:135]
	v_mfma_f32_16x16x32_bf16 v[128:131], v[168:171], v[176:179], v[128:131]
	v_mfma_f32_16x16x32_bf16 v[116:119], v[160:163], v[184:187], v[116:119]
	v_mfma_f32_16x16x32_bf16 v[112:115], v[168:171], v[184:187], v[112:115]
	v_mfma_f32_16x16x32_bf16 v[100:103], v[160:163], v[202:205], v[100:103]
	v_mfma_f32_16x16x32_bf16 v[96:99], v[168:171], v[202:205], v[96:99]
	v_mfma_f32_16x16x32_bf16 v[84:87], v[160:163], v[212:215], v[84:87]
	v_mfma_f32_16x16x32_bf16 v[80:83], v[168:171], v[212:215], v[80:83]
	v_mfma_f32_16x16x32_bf16 v[132:135], v[164:167], v[180:183], v[132:135]
	v_mfma_f32_16x16x32_bf16 v[128:131], v[172:175], v[180:183], v[128:131]
	v_mfma_f32_16x16x32_bf16 v[116:119], v[164:167], v[188:191], v[116:119]
	v_mfma_f32_16x16x32_bf16 v[112:115], v[172:175], v[188:191], v[112:115]
	v_mfma_f32_16x16x32_bf16 v[100:103], v[164:167], v[208:211], v[100:103]
	v_mfma_f32_16x16x32_bf16 v[96:99], v[172:175], v[208:211], v[96:99]
	v_mfma_f32_16x16x32_bf16 v[84:87], v[164:167], v[216:219], v[84:87]
	v_mfma_f32_16x16x32_bf16 v[80:83], v[172:175], v[216:219], v[80:83]
	s_setprio 0
	s_barrier
	s_add_i32 s0, s47, s19
	v_lshl_add_u64 v[198:199], s[42:43], 0, v[146:147]
	s_mov_b32 m0, s0
	ds_read_b128 v[176:179], v197 offset:16384
	ds_read_b128 v[180:183], v197 offset:17408
	ds_read_b128 v[184:187], v197 offset:18432
	ds_read_b128 v[188:191], v197 offset:19456
	ds_read_b128 v[202:205], v197 offset:20480
	ds_read_b128 v[208:211], v197 offset:21504
	ds_read_b128 v[212:215], v197 offset:22528
	ds_read_b128 v[216:219], v197 offset:23552
	global_load_lds_dwordx4 v[198:199], off
	s_add_i32 m0, s0, 0x2000
	s_add_u32 s70, s42, 0x80000
	v_lshl_add_u64 v[220:221], s[42:43], 0, v[150:151]
	s_addc_u32 s71, s43, 0
	s_add_i32 s0, s60, s19
	global_load_lds_dwordx4 v[220:221], off
	v_lshl_add_u64 v[222:223], s[70:71], 0, v[146:147]
	s_mov_b32 m0, s0
	v_lshl_add_u64 v[224:225], s[44:45], 0, v[148:149]
	global_load_lds_dwordx4 v[222:223], off
	v_lshl_add_u64 v[222:223], s[70:71], 0, v[150:151]
	s_add_i32 m0, s0, 0x2000
	s_nop 0
	global_load_lds_dwordx4 v[222:223], off
	v_lshl_add_u64 v[222:223], s[44:45], 0, v[144:145]
	s_mov_b32 m0, s20
	s_nop 0
	global_load_lds_dwordx4 v[222:223], off
	s_mov_b32 m0, s21
	s_nop 0
	global_load_lds_dwordx4 v[224:225], off
	s_waitcnt vmcnt(8)
	s_waitcnt lgkmcnt(0)
	s_barrier
; #define PG8_STAGE(bufoff, gbase, voff) do { _Pragma("unroll") for (int _i = 0; _i < 2; ++_i) \
;         __builtin_amdgcn_global_load_lds((const unsigned*)((const char*)(gbase) + (voff)[_i]), (PG8_LAS unsigned*)(lds + (bufoff) + ldsw + _i * 8192), 16, 0, 0); } while (0)
; #define PG8_LDA(dst, b, h) do { _Pragma("unroll") for (int m = 0; m < 4; ++m) _Pragma("unroll") for (int k = 0; k < 2; ++k) dst[m][k] = *(const PG8_LAS bf16x8*)(lds + PG8_SA(b, h) + aoff + m * 2048 + k * 1024); } while (0)
; #define PG8_LDB(dst, b, h) do { _Pragma("unroll") for (int n = 0; n < 2; ++n) _Pragma("unroll") for (int k = 0; k < 2; ++k) dst[n][k] = *(const PG8_LAS bf16x8*)(lds + PG8_SB(b, h) + boff + n * 2048 + k * 1024); } while (0)
; #define PG8_MMA(ai, bj, At, Bt) do { __builtin_amdgcn_s_setprio(1); _Pragma("unroll") for (int m = 0; m < 4; ++m) _Pragma("unroll") for (int n = 0; n < 2; ++n) _Pragma("unroll") for (int k = 0; k < 2; ++k) \
;         acc[ai][bj][m][n] = __builtin_amdgcn_mfma_f32_16x16x32_bf16(Bt[n][k], At[m][k], acc[ai][bj][m][n], 0, 0, 0); __builtin_amdgcn_s_setprio(0); } while (0)
; #define PG8_WAIT_V(n) asm volatile("s_waitcnt vmcnt(" #n ")" ::: "memory")
; #define PG8_WAIT_L(n) asm volatile("s_waitcnt lgkmcnt(" #n ")" ::: "memory")
; #define PG8_BAR __builtin_amdgcn_s_barrier()
; #define PG8_SCHED __builtin_amdgcn_sched_barrier(0)
; template <class Epi, class Sched, bool ALIGN_EPI = false, bool SP2 = false>
; __device__ __forceinline__ void gemm_phase(PG8_LAS unsigned char* lds, const Gemm g, const Sched& S, const Epi& E, int wave_s) {
;     ...
;             PG8_WAIT_V(8); PG8_WAIT_L(0); PG8_BAR; PG8_MMA(1, 0, At, B0); PG8_MMA(1, 1, At, B1); PG8_BAR; PG8_SCHED;
;             PG8_LDB(B0, 1, 0); PG8_LDB(B1, 1, 1); PG8_SCHED; PG8_LDA(At, 1, 0); PG8_STAGE(PG8_SA(0, 1), a2 + hstep, voffA);
;             PG8_WAIT_V(8); PG8_WAIT_L(0); PG8_BAR; PG8_MMA(0, 0, At, B0); PG8_MMA(0, 1, At, B1); PG8_BAR; PG8_SCHED;
	s_setprio 1
	s_waitcnt lgkmcnt(0)
	v_mfma_f32_16x16x32_bf16 v[76:79], v[32:35], v[176:179], v[76:79]
	v_mfma_f32_16x16x32_bf16 v[72:75], v[48:51], v[176:179], v[72:75]
	v_mfma_f32_16x16x32_bf16 v[60:63], v[32:35], v[184:187], v[60:63]
	v_mfma_f32_16x16x32_bf16 v[56:59], v[48:51], v[184:187], v[56:59]
	v_mfma_f32_16x16x32_bf16 v[28:31], v[32:35], v[202:205], v[28:31]
	v_mfma_f32_16x16x32_bf16 v[24:27], v[48:51], v[202:205], v[24:27]
	v_mfma_f32_16x16x32_bf16 v[12:15], v[32:35], v[212:215], v[12:15]
	v_mfma_f32_16x16x32_bf16 v[8:11], v[48:51], v[212:215], v[8:11]
	v_mfma_f32_16x16x32_bf16 v[76:79], v[36:39], v[180:183], v[76:79]
	v_mfma_f32_16x16x32_bf16 v[72:75], v[52:55], v[180:183], v[72:75]
	v_mfma_f32_16x16x32_bf16 v[60:63], v[36:39], v[188:191], v[60:63]
	v_mfma_f32_16x16x32_bf16 v[56:59], v[52:55], v[188:191], v[56:59]
	v_mfma_f32_16x16x32_bf16 v[28:31], v[36:39], v[208:211], v[28:31]
	v_mfma_f32_16x16x32_bf16 v[24:27], v[52:55], v[208:211], v[24:27]
	v_mfma_f32_16x16x32_bf16 v[12:15], v[36:39], v[216:219], v[12:15]
	v_mfma_f32_16x16x32_bf16 v[8:11], v[52:55], v[216:219], v[8:11]
	s_setprio 0
	s_setprio 1
	v_mfma_f32_16x16x32_bf16 v[44:47], v[160:163], v[184:187], v[44:47]
	v_mfma_f32_16x16x32_bf16 v[40:43], v[168:171], v[184:187], v[40:43]
	v_mfma_f32_16x16x32_bf16 v[20:23], v[160:163], v[202:205], v[20:23]
	v_mfma_f32_16x16x32_bf16 v[16:19], v[168:171], v[202:205], v[16:19]
	v_mfma_f32_16x16x32_bf16 v[4:7], v[160:163], v[212:215], v[4:7]
	v_mfma_f32_16x16x32_bf16 v[0:3], v[168:171], v[212:215], v[0:3]
	v_mfma_f32_16x16x32_bf16 v[32:35], v[160:163], v[176:179], v[68:71]
	v_mfma_f32_16x16x32_bf16 v[36:39], v[168:171], v[176:179], v[64:67]
	v_mfma_f32_16x16x32_bf16 v[44:47], v[164:167], v[188:191], v[44:47]
	v_mfma_f32_16x16x32_bf16 v[40:43], v[172:175], v[188:191], v[40:43]
	v_mfma_f32_16x16x32_bf16 v[20:23], v[164:167], v[208:211], v[20:23]
	v_mfma_f32_16x16x32_bf16 v[16:19], v[172:175], v[208:211], v[16:19]
	v_mfma_f32_16x16x32_bf16 v[4:7], v[164:167], v[216:219], v[4:7]
	v_mfma_f32_16x16x32_bf16 v[0:3], v[172:175], v[216:219], v[0:3]
	v_mfma_f32_16x16x32_bf16 v[32:35], v[164:167], v[180:183], v[32:35]
	v_mfma_f32_16x16x32_bf16 v[36:39], v[172:175], v[180:183], v[36:39]
	s_setprio 0
	s_barrier
	s_add_i32 s0, 0, 0x18000
	s_add_i32 s1, 0, 0x1c000
	v_add_u32_e32 v68, s0, v193
	v_add_u32_e32 v172, s1, v193
	ds_read_b128 v[48:51], v68
	ds_read_b128 v[52:55], v68 offset:1024
	ds_read_b128 v[64:67], v68 offset:2048
	ds_read_b128 v[68:71], v68 offset:3072
	ds_read_b128 v[160:163], v172
	ds_read_b128 v[164:167], v172 offset:1024
	ds_read_b128 v[168:171], v172 offset:2048
	ds_read_b128 v[172:175], v172 offset:3072
	s_add_u32 s44, s44, 0x80000
	s_addc_u32 s45, s45, 0
	s_mov_b32 m0, s22
	v_lshl_add_u64 v[226:227], s[44:45], 0, v[144:145]
	ds_read_b128 v[176:179], v197 offset:32768
	ds_read_b128 v[180:183], v197 offset:33792
	ds_read_b128 v[184:187], v197 offset:34816
	ds_read_b128 v[188:191], v197 offset:35840
	ds_read_b128 v[202:205], v197 offset:36864
	ds_read_b128 v[208:211], v197 offset:37888
	ds_read_b128 v[212:215], v197 offset:38912
	ds_read_b128 v[216:219], v197 offset:39936
	global_load_lds_dwordx4 v[226:227], off
	v_lshl_add_u64 v[226:227], s[44:45], 0, v[148:149]
	s_mov_b32 m0, s23
	s_nop 0
	global_load_lds_dwordx4 v[226:227], off
	s_waitcnt vmcnt(8)
	s_waitcnt lgkmcnt(0)
	s_barrier
	s_setprio 1
	s_waitcnt lgkmcnt(0)
	v_mfma_f32_16x16x32_bf16 v[140:143], v[48:51], v[176:179], v[140:143]
	v_mfma_f32_16x16x32_bf16 v[136:139], v[64:67], v[176:179], v[136:139]
	v_mfma_f32_16x16x32_bf16 v[124:127], v[48:51], v[184:187], v[124:127]
	v_mfma_f32_16x16x32_bf16 v[120:123], v[64:67], v[184:187], v[120:123]
	v_mfma_f32_16x16x32_bf16 v[108:111], v[48:51], v[202:205], v[108:111]
	v_mfma_f32_16x16x32_bf16 v[104:107], v[64:67], v[202:205], v[104:107]
	v_mfma_f32_16x16x32_bf16 v[92:95], v[48:51], v[212:215], v[92:95]
	v_mfma_f32_16x16x32_bf16 v[88:91], v[64:67], v[212:215], v[88:91]
	v_mfma_f32_16x16x32_bf16 v[140:143], v[52:55], v[180:183], v[140:143]
	v_mfma_f32_16x16x32_bf16 v[136:139], v[68:71], v[180:183], v[136:139]
	v_mfma_f32_16x16x32_bf16 v[124:127], v[52:55], v[188:191], v[124:127]
	v_mfma_f32_16x16x32_bf16 v[120:123], v[68:71], v[188:191], v[120:123]
	v_mfma_f32_16x16x32_bf16 v[108:111], v[52:55], v[208:211], v[108:111]
	v_mfma_f32_16x16x32_bf16 v[104:107], v[68:71], v[208:211], v[104:107]
	v_mfma_f32_16x16x32_bf16 v[92:95], v[52:55], v[216:219], v[92:95]
	v_mfma_f32_16x16x32_bf16 v[88:91], v[68:71], v[216:219], v[88:91]
	s_setprio 0
	s_setprio 1
	v_mfma_f32_16x16x32_bf16 v[132:135], v[160:163], v[176:179], v[132:135]
	v_mfma_f32_16x16x32_bf16 v[128:131], v[168:171], v[176:179], v[128:131]
	v_mfma_f32_16x16x32_bf16 v[116:119], v[160:163], v[184:187], v[116:119]
	v_mfma_f32_16x16x32_bf16 v[112:115], v[168:171], v[184:187], v[112:115]
	v_mfma_f32_16x16x32_bf16 v[100:103], v[160:163], v[202:205], v[100:103]
	v_mfma_f32_16x16x32_bf16 v[96:99], v[168:171], v[202:205], v[96:99]
	v_mfma_f32_16x16x32_bf16 v[84:87], v[160:163], v[212:215], v[84:87]
	v_mfma_f32_16x16x32_bf16 v[80:83], v[168:171], v[212:215], v[80:83]
	v_mfma_f32_16x16x32_bf16 v[132:135], v[164:167], v[180:183], v[132:135]
	v_mfma_f32_16x16x32_bf16 v[128:131], v[172:175], v[180:183], v[128:131]
	v_mfma_f32_16x16x32_bf16 v[116:119], v[164:167], v[188:191], v[116:119]
	v_mfma_f32_16x16x32_bf16 v[112:115], v[172:175], v[188:191], v[112:115]
	v_mfma_f32_16x16x32_bf16 v[100:103], v[164:167], v[208:211], v[100:103]
	v_mfma_f32_16x16x32_bf16 v[96:99], v[172:175], v[208:211], v[96:99]
	v_mfma_f32_16x16x32_bf16 v[84:87], v[164:167], v[216:219], v[84:87]
	v_mfma_f32_16x16x32_bf16 v[80:83], v[172:175], v[216:219], v[80:83]
	s_setprio 0
	s_barrier
; #define PG8_STAGE(bufoff, gbase, voff) do { _Pragma("unroll") for (int _i = 0; _i < 2; ++_i) \
;         __builtin_amdgcn_global_load_lds((const unsigned*)((const char*)(gbase) + (voff)[_i]), (PG8_LAS unsigned*)(lds + (bufoff) + ldsw + _i * 8192), 16, 0, 0); } while (0)
; #define PG8_LDA(dst, b, h) do { _Pragma("unroll") for (int m = 0; m < 4; ++m) _Pragma("unroll") for (int k = 0; k < 2; ++k) dst[m][k] = *(const PG8_LAS bf16x8*)(lds + PG8_SA(b, h) + aoff + m * 2048 + k * 1024); } while (0)
; #define PG8_MMA(ai, bj, At, Bt) do { __builtin_amdgcn_s_setprio(1); _Pragma("unroll") for (int m = 0; m < 4; ++m) _Pragma("unroll") for (int n = 0; n < 2; ++n) _Pragma("unroll") for (int k = 0; k < 2; ++k) \
;         acc[ai][bj][m][n] = __builtin_amdgcn_mfma_f32_16x16x32_bf16(Bt[n][k], At[m][k], acc[ai][bj][m][n], 0, 0, 0); __builtin_amdgcn_s_setprio(0); } while (0)
; #define PG8_WAIT_V(n) asm volatile("s_waitcnt vmcnt(" #n ")" ::: "memory")
; #define PG8_WAIT_L(n) asm volatile("s_waitcnt lgkmcnt(" #n ")" ::: "memory")
; #define PG8_BAR __builtin_amdgcn_s_barrier()
; #define PG8_SCHED __builtin_amdgcn_sched_barrier(0)
; template <class Epi, class Sched, bool ALIGN_EPI = false, bool SP2 = false>
; __device__ __forceinline__ void gemm_phase(PG8_LAS unsigned char* lds, const Gemm g, const Sched& S, const Epi& E, int wave_s) {
;     ...
;         for (int t = 0; t < nt; t += 2) {
;             const bool last = (t == nt - 2);
;     ...
;             PG8_LDA(At, 1, 1); PG8_STAGE(PG8_SB(1, 0), b3, voffB); PG8_STAGE(PG8_SB(1, 1), b3 + hstep, voffB); PG8_STAGE(PG8_SA(1, 0), a3, voffA);
;             PG8_WAIT_V(8); PG8_WAIT_L(0); PG8_BAR; PG8_MMA(1, 0, At, B0); PG8_MMA(1, 1, At, B1); PG8_BAR; PG8_SCHED;
	s_add_i32 s0, s0, s19
	v_lshl_add_u64 v[198:199], v[198:199], 0, s[16:17]
	s_mov_b32 m0, s0
	ds_read_b128 v[176:179], v197 offset:49152
	ds_read_b128 v[180:183], v197 offset:50176
	ds_read_b128 v[184:187], v197 offset:51200
	ds_read_b128 v[188:191], v197 offset:52224
	ds_read_b128 v[202:205], v197 offset:53248
	ds_read_b128 v[208:211], v197 offset:54272
	ds_read_b128 v[212:215], v197 offset:55296
	ds_read_b128 v[216:219], v197 offset:56320
	global_load_lds_dwordx4 v[198:199], off
	s_add_i32 m0, s0, 0x2000
	s_add_u32 s42, s42, 0x80080
	v_lshl_add_u64 v[198:199], v[220:221], 0, s[16:17]
	s_addc_u32 s43, s43, 0
	s_add_i32 s0, s1, s19
	global_load_lds_dwordx4 v[198:199], off
	v_lshl_add_u64 v[198:199], s[42:43], 0, v[146:147]
	s_mov_b32 m0, s0
	s_nop 0
	global_load_lds_dwordx4 v[198:199], off
	v_lshl_add_u64 v[198:199], s[42:43], 0, v[150:151]
	s_add_i32 m0, s0, 0x2000
	s_nop 0
	global_load_lds_dwordx4 v[198:199], off
	v_lshl_add_u64 v[198:199], v[222:223], 0, s[16:17]
	s_mov_b32 m0, s25
	s_nop 0
	global_load_lds_dwordx4 v[198:199], off
	v_lshl_add_u64 v[198:199], v[224:225], 0, s[16:17]
	s_mov_b32 m0, s26
	s_nop 0
	global_load_lds_dwordx4 v[198:199], off
	s_waitcnt vmcnt(8)
	s_waitcnt lgkmcnt(0)
	s_barrier
	s_setprio 1
	s_waitcnt lgkmcnt(0)
	v_mfma_f32_16x16x32_bf16 v[76:79], v[48:51], v[176:179], v[76:79]
	v_mfma_f32_16x16x32_bf16 v[72:75], v[64:67], v[176:179], v[72:75]
	v_mfma_f32_16x16x32_bf16 v[60:63], v[48:51], v[184:187], v[60:63]
	v_mfma_f32_16x16x32_bf16 v[56:59], v[64:67], v[184:187], v[56:59]
	v_mfma_f32_16x16x32_bf16 v[28:31], v[48:51], v[202:205], v[28:31]
	v_mfma_f32_16x16x32_bf16 v[24:27], v[64:67], v[202:205], v[24:27]
	v_mfma_f32_16x16x32_bf16 v[12:15], v[48:51], v[212:215], v[12:15]
	v_mfma_f32_16x16x32_bf16 v[8:11], v[64:67], v[212:215], v[8:11]
	v_mfma_f32_16x16x32_bf16 v[76:79], v[52:55], v[180:183], v[76:79]
	v_mfma_f32_16x16x32_bf16 v[72:75], v[68:71], v[180:183], v[72:75]
	v_mfma_f32_16x16x32_bf16 v[60:63], v[52:55], v[188:191], v[60:63]
	v_mfma_f32_16x16x32_bf16 v[56:59], v[68:71], v[188:191], v[56:59]
	v_mfma_f32_16x16x32_bf16 v[28:31], v[52:55], v[208:211], v[28:31]
	v_mfma_f32_16x16x32_bf16 v[24:27], v[68:71], v[208:211], v[24:27]
	v_mfma_f32_16x16x32_bf16 v[12:15], v[52:55], v[216:219], v[12:15]
	v_mfma_f32_16x16x32_bf16 v[8:11], v[68:71], v[216:219], v[8:11]
	s_setprio 0
	s_setprio 1
	v_mfma_f32_16x16x32_bf16 v[32:35], v[160:163], v[176:179], v[32:35]
	v_mfma_f32_16x16x32_bf16 v[68:71], v[164:167], v[180:183], v[32:35]
	v_mfma_f32_16x16x32_bf16 v[32:35], v[168:171], v[176:179], v[36:39]
	v_mfma_f32_16x16x32_bf16 v[64:67], v[172:175], v[180:183], v[32:35]
	v_mfma_f32_16x16x32_bf16 v[32:35], v[160:163], v[184:187], v[44:47]
	v_mfma_f32_16x16x32_bf16 v[44:47], v[164:167], v[188:191], v[32:35]
	v_mfma_f32_16x16x32_bf16 v[32:35], v[168:171], v[184:187], v[40:43]
	v_mfma_f32_16x16x32_bf16 v[20:23], v[160:163], v[202:205], v[20:23]
	v_mfma_f32_16x16x32_bf16 v[16:19], v[168:171], v[202:205], v[16:19]
	v_mfma_f32_16x16x32_bf16 v[4:7], v[160:163], v[212:215], v[4:7]
	v_mfma_f32_16x16x32_bf16 v[0:3], v[168:171], v[212:215], v[0:3]
	v_mfma_f32_16x16x32_bf16 v[40:43], v[172:175], v[188:191], v[32:35]
	v_mfma_f32_16x16x32_bf16 v[20:23], v[164:167], v[208:211], v[20:23]
	v_mfma_f32_16x16x32_bf16 v[16:19], v[172:175], v[208:211], v[16:19]
	v_mfma_f32_16x16x32_bf16 v[4:7], v[164:167], v[216:219], v[4:7]
	v_mfma_f32_16x16x32_bf16 v[0:3], v[172:175], v[216:219], v[0:3]
	s_add_i32 s67, s67, 2
	s_add_u32 s40, s40, 0x100
	s_addc_u32 s41, s41, 0
	s_add_u32 s35, s35, 0x100
	s_addc_u32 s66, s66, 0
	s_cmp_gt_u32 s67, 29
	s_setprio 0
	s_barrier
	s_cbranch_scc0 .LBB0_893
	s_and_b64 vcc, exec, s[28:29]
	s_cbranch_vccz .LBB0_896
	s_barrier

; #define PG8_STAGE(bufoff, gbase, voff) do { _Pragma("unroll") for (int _i = 0; _i < 2; ++_i) \
;         __builtin_amdgcn_global_load_lds((const unsigned*)((const char*)(gbase) + (voff)[_i]), (PG8_LAS unsigned*)(lds + (bufoff) + ldsw + _i * 8192), 16, 0, 0); } while (0)
; #define PG8_LDA(dst, b, h) do { _Pragma("unroll") for (int m = 0; m < 4; ++m) _Pragma("unroll") for (int k = 0; k < 2; ++k) dst[m][k] = *(const PG8_LAS bf16x8*)(lds + PG8_SA(b, h) + aoff + m * 2048 + k * 1024); } while (0)
; #define PG8_LDB(dst, b, h) do { _Pragma("unroll") for (int n = 0; n < 2; ++n) _Pragma("unroll") for (int k = 0; k < 2; ++k) dst[n][k] = *(const PG8_LAS bf16x8*)(lds + PG8_SB(b, h) + boff + n * 2048 + k * 1024); } while (0)
; #define PG8_MMA(ai, bj, At, Bt) do { __builtin_amdgcn_s_setprio(1); _Pragma("unroll") for (int m = 0; m < 4; ++m) _Pragma("unroll") for (int n = 0; n < 2; ++n) _Pragma("unroll") for (int k = 0; k < 2; ++k) \
;         acc[ai][bj][m][n] = __builtin_amdgcn_mfma_f32_16x16x32_bf16(Bt[n][k], At[m][k], acc[ai][bj][m][n], 0, 0, 0); __builtin_amdgcn_s_setprio(0); } while (0)
; #define PG8_WAIT_V(n) asm volatile("s_waitcnt vmcnt(" #n ")" ::: "memory")
; #define PG8_WAIT_L(n) asm volatile("s_waitcnt lgkmcnt(" #n ")" ::: "memory")
; #define PG8_BAR __builtin_amdgcn_s_barrier()
; #define PG8_SCHED __builtin_amdgcn_sched_barrier(0)
; template <class Epi, class Sched, bool ALIGN_EPI = false, bool SP2 = false>
; __device__ __forceinline__ void gemm_phase(PG8_LAS unsigned char* lds, const Gemm g, const Sched& S, const Epi& E, int wave_s) {
;     ...
;         for (int t = 0; t < nt; t += 2) {
;             const bool last = (t == nt - 2);
;             const char* a1 = cA + (size_t)(t + 1) * kstep;
;             const char* a2 = last ? nA : cA + (size_t)(t + 2) * kstep; const char* b2 = last ? nB : cB + (size_t)(t + 2) * kstep;
;             const char* a3 = a2 + kstep; const char* b3 = b2 + kstep;
;             if (last && has_next) S.a_ready(nxt);
;             if constexpr (SP2) {
;             PG8_LDB(B0, 0, 0); PG8_LDB(B1, 0, 1); PG8_SCHED; PG8_LDA(At, 0, 0); PG8_STAGE(PG8_SA(1, 1), a1 + hstep, voffA);
;             PG8_WAIT_V(8); PG8_WAIT_L(0); PG8_BAR; PG8_MMA(0, 0, At, B0); PG8_MMA(0, 1, At, B1); PG8_BAR; PG8_SCHED;
;             PG8_LDA(At, 0, 1); PG8_STAGE(PG8_SB(0, 0), b2, voffB); PG8_STAGE(PG8_SB(0, 1), b2 + hstep, voffB); PG8_STAGE(PG8_SA(0, 0), a2, voffA);
.LBB0_1074:
	s_waitcnt vmcnt(0)
	ds_read_b128 v[146:149], v197
	ds_read_b128 v[150:153], v197 offset:1024
	ds_read_b128 v[154:157], v197 offset:2048
	ds_read_b128 v[158:161], v197 offset:3072
	ds_read_b128 v[162:165], v198
	ds_read_b128 v[166:169], v198 offset:1024
	ds_read_b128 v[170:173], v198 offset:2048
	ds_read_b128 v[174:177], v198 offset:3072
	s_add_u32 s0, s36, 0xfff80080
	s_addc_u32 s1, s37, -1
	s_cmp_eq_u32 s65, 28
	s_cselect_b32 s41, s2, s1
	s_cselect_b32 s40, s3, s0
	s_cselect_b32 s39, s7, s35
	s_cselect_b32 s38, s25, s27
	v_lshl_add_u64 v[220:221], s[36:37], 0, v[138:139]
	s_add_i32 m0, s20, 0xc000
	ds_read_b128 v[178:181], v199
	ds_read_b128 v[182:185], v199 offset:1024
	ds_read_b128 v[186:189], v199 offset:2048
	ds_read_b128 v[190:193], v199 offset:3072
	ds_read_b128 v[202:205], v199 offset:4096
	ds_read_b128 v[208:211], v199 offset:5120
	ds_read_b128 v[212:215], v199 offset:6144
	ds_read_b128 v[216:219], v199 offset:7168
	global_load_lds_dwordx4 v[220:221], off
	v_lshl_add_u64 v[220:221], s[36:37], 0, v[140:141]
	s_add_i32 m0, s20, 0xe000
	s_nop 0
	global_load_lds_dwordx4 v[220:221], off
	s_waitcnt vmcnt(8)
	s_waitcnt lgkmcnt(0)
	s_barrier
	s_setprio 1
	s_waitcnt lgkmcnt(0)
	v_mfma_f32_16x16x32_bf16 v[124:127], v[146:149], v[178:181], v[124:127]
	v_mfma_f32_16x16x32_bf16 v[120:123], v[154:157], v[178:181], v[120:123]
	v_mfma_f32_16x16x32_bf16 v[108:111], v[146:149], v[186:189], v[108:111]
	v_mfma_f32_16x16x32_bf16 v[104:107], v[154:157], v[186:189], v[104:107]
	v_mfma_f32_16x16x32_bf16 v[92:95], v[146:149], v[202:205], v[92:95]
	v_mfma_f32_16x16x32_bf16 v[88:91], v[154:157], v[202:205], v[88:91]
	v_mfma_f32_16x16x32_bf16 v[76:79], v[146:149], v[212:215], v[76:79]
	v_mfma_f32_16x16x32_bf16 v[72:75], v[154:157], v[212:215], v[72:75]
	v_mfma_f32_16x16x32_bf16 v[124:127], v[150:153], v[182:185], v[124:127]
	v_mfma_f32_16x16x32_bf16 v[120:123], v[158:161], v[182:185], v[120:123]
	v_mfma_f32_16x16x32_bf16 v[108:111], v[150:153], v[190:193], v[108:111]
	v_mfma_f32_16x16x32_bf16 v[104:107], v[158:161], v[190:193], v[104:107]
	v_mfma_f32_16x16x32_bf16 v[92:95], v[150:153], v[208:211], v[92:95]
	v_mfma_f32_16x16x32_bf16 v[88:91], v[158:161], v[208:211], v[88:91]
	v_mfma_f32_16x16x32_bf16 v[76:79], v[150:153], v[216:219], v[76:79]
	v_mfma_f32_16x16x32_bf16 v[72:75], v[158:161], v[216:219], v[72:75]
	s_setprio 0
	s_setprio 1
	v_mfma_f32_16x16x32_bf16 v[116:119], v[162:165], v[178:181], v[116:119]
	v_mfma_f32_16x16x32_bf16 v[112:115], v[170:173], v[178:181], v[112:115]
	v_mfma_f32_16x16x32_bf16 v[100:103], v[162:165], v[186:189], v[100:103]
	v_mfma_f32_16x16x32_bf16 v[96:99], v[170:173], v[186:189], v[96:99]
	v_mfma_f32_16x16x32_bf16 v[84:87], v[162:165], v[202:205], v[84:87]
	v_mfma_f32_16x16x32_bf16 v[80:83], v[170:173], v[202:205], v[80:83]
	v_mfma_f32_16x16x32_bf16 v[68:71], v[162:165], v[212:215], v[68:71]
	v_mfma_f32_16x16x32_bf16 v[64:67], v[170:173], v[212:215], v[64:67]
	v_mfma_f32_16x16x32_bf16 v[116:119], v[166:169], v[182:185], v[116:119]
	v_mfma_f32_16x16x32_bf16 v[112:115], v[174:177], v[182:185], v[112:115]
	v_mfma_f32_16x16x32_bf16 v[100:103], v[166:169], v[190:193], v[100:103]
	v_mfma_f32_16x16x32_bf16 v[96:99], v[174:177], v[190:193], v[96:99]
	v_mfma_f32_16x16x32_bf16 v[84:87], v[166:169], v[208:211], v[84:87]
	v_mfma_f32_16x16x32_bf16 v[80:83], v[174:177], v[208:211], v[80:83]
	v_mfma_f32_16x16x32_bf16 v[68:71], v[166:169], v[216:219], v[68:71]
	v_mfma_f32_16x16x32_bf16 v[64:67], v[174:177], v[216:219], v[64:67]
	s_setprio 0
	s_barrier
	s_add_i32 s0, s61, s19
	v_lshl_add_u64 v[220:221], s[38:39], 0, v[130:131]
	s_mov_b32 m0, s0
	ds_read_b128 v[178:181], v199 offset:16384
	ds_read_b128 v[182:185], v199 offset:17408
	ds_read_b128 v[186:189], v199 offset:18432
	ds_read_b128 v[190:193], v199 offset:19456
	ds_read_b128 v[202:205], v199 offset:20480
	ds_read_b128 v[208:211], v199 offset:21504
	ds_read_b128 v[212:215], v199 offset:22528
	ds_read_b128 v[216:219], v199 offset:23552
	global_load_lds_dwordx4 v[220:221], off
	s_add_i32 m0, s0, 0x2000
	s_add_u32 s66, s38, 0x80000
	v_lshl_add_u64 v[222:223], s[38:39], 0, v[134:135]
	s_addc_u32 s67, s39, 0
	s_add_i32 s0, s64, s19
	global_load_lds_dwordx4 v[222:223], off
	v_lshl_add_u64 v[224:225], s[66:67], 0, v[130:131]
	s_mov_b32 m0, s0
	v_lshl_add_u64 v[226:227], s[40:41], 0, v[132:133]
	global_load_lds_dwordx4 v[224:225], off
	v_lshl_add_u64 v[224:225], s[66:67], 0, v[134:135]
	s_add_i32 m0, s0, 0x2000
	s_nop 0
	global_load_lds_dwordx4 v[224:225], off
	v_lshl_add_u64 v[224:225], s[40:41], 0, v[128:129]
	s_mov_b32 m0, s20
	s_nop 0
	global_load_lds_dwordx4 v[224:225], off
	s_mov_b32 m0, s21
	s_nop 0
	global_load_lds_dwordx4 v[226:227], off
	s_waitcnt vmcnt(8)
	s_waitcnt lgkmcnt(0)
	s_barrier
; #define PG8_STAGE(bufoff, gbase, voff) do { _Pragma("unroll") for (int _i = 0; _i < 2; ++_i) \
;         __builtin_amdgcn_global_load_lds((const unsigned*)((const char*)(gbase) + (voff)[_i]), (PG8_LAS unsigned*)(lds + (bufoff) + ldsw + _i * 8192), 16, 0, 0); } while (0)
; #define PG8_LDA(dst, b, h) do { _Pragma("unroll") for (int m = 0; m < 4; ++m) _Pragma("unroll") for (int k = 0; k < 2; ++k) dst[m][k] = *(const PG8_LAS bf16x8*)(lds + PG8_SA(b, h) + aoff + m * 2048 + k * 1024); } while (0)
; #define PG8_LDB(dst, b, h) do { _Pragma("unroll") for (int n = 0; n < 2; ++n) _Pragma("unroll") for (int k = 0; k < 2; ++k) dst[n][k] = *(const PG8_LAS bf16x8*)(lds + PG8_SB(b, h) + boff + n * 2048 + k * 1024); } while (0)
; #define PG8_MMA(ai, bj, At, Bt) do { __builtin_amdgcn_s_setprio(1); _Pragma("unroll") for (int m = 0; m < 4; ++m) _Pragma("unroll") for (int n = 0; n < 2; ++n) _Pragma("unroll") for (int k = 0; k < 2; ++k) \
;         acc[ai][bj][m][n] = __builtin_amdgcn_mfma_f32_16x16x32_bf16(Bt[n][k], At[m][k], acc[ai][bj][m][n], 0, 0, 0); __builtin_amdgcn_s_setprio(0); } while (0)
; #define PG8_WAIT_V(n) asm volatile("s_waitcnt vmcnt(" #n ")" ::: "memory")
; #define PG8_WAIT_L(n) asm volatile("s_waitcnt lgkmcnt(" #n ")" ::: "memory")
; #define PG8_BAR __builtin_amdgcn_s_barrier()
; #define PG8_SCHED __builtin_amdgcn_sched_barrier(0)
; template <class Epi, class Sched, bool ALIGN_EPI = false, bool SP2 = false>
; __device__ __forceinline__ void gemm_phase(PG8_LAS unsigned char* lds, const Gemm g, const Sched& S, const Epi& E, int wave_s) {
;     ...
;             PG8_WAIT_V(8); PG8_WAIT_L(0); PG8_BAR; PG8_MMA(1, 0, At, B0); PG8_MMA(1, 1, At, B1); PG8_BAR; PG8_SCHED;
;             PG8_LDB(B0, 1, 0); PG8_LDB(B1, 1, 1); PG8_SCHED; PG8_LDA(At, 1, 0); PG8_STAGE(PG8_SA(0, 1), a2 + hstep, voffA);
;             PG8_WAIT_V(8); PG8_WAIT_L(0); PG8_BAR; PG8_MMA(0, 0, At, B0); PG8_MMA(0, 1, At, B1); PG8_BAR; PG8_SCHED;
	s_setprio 1
	s_waitcnt lgkmcnt(0)
	v_mfma_f32_16x16x32_bf16 v[60:63], v[146:149], v[178:181], v[60:63]
	v_mfma_f32_16x16x32_bf16 v[56:59], v[154:157], v[178:181], v[56:59]
	v_mfma_f32_16x16x32_bf16 v[44:47], v[146:149], v[186:189], v[44:47]
	v_mfma_f32_16x16x32_bf16 v[40:43], v[154:157], v[186:189], v[40:43]
	v_mfma_f32_16x16x32_bf16 v[28:31], v[146:149], v[202:205], v[28:31]
	v_mfma_f32_16x16x32_bf16 v[24:27], v[154:157], v[202:205], v[24:27]
	v_mfma_f32_16x16x32_bf16 v[12:15], v[146:149], v[212:215], v[12:15]
	v_mfma_f32_16x16x32_bf16 v[8:11], v[154:157], v[212:215], v[8:11]
	v_mfma_f32_16x16x32_bf16 v[60:63], v[150:153], v[182:185], v[60:63]
	v_mfma_f32_16x16x32_bf16 v[56:59], v[158:161], v[182:185], v[56:59]
	v_mfma_f32_16x16x32_bf16 v[44:47], v[150:153], v[190:193], v[44:47]
	v_mfma_f32_16x16x32_bf16 v[40:43], v[158:161], v[190:193], v[40:43]
	v_mfma_f32_16x16x32_bf16 v[28:31], v[150:153], v[208:211], v[28:31]
	v_mfma_f32_16x16x32_bf16 v[24:27], v[158:161], v[208:211], v[24:27]
	v_mfma_f32_16x16x32_bf16 v[12:15], v[150:153], v[216:219], v[12:15]
	v_mfma_f32_16x16x32_bf16 v[8:11], v[158:161], v[216:219], v[8:11]
	s_setprio 0
	s_setprio 1
	v_mfma_f32_16x16x32_bf16 v[52:55], v[162:165], v[178:181], v[52:55]
	v_mfma_f32_16x16x32_bf16 v[48:51], v[170:173], v[178:181], v[48:51]
	v_mfma_f32_16x16x32_bf16 v[36:39], v[162:165], v[186:189], v[36:39]
	v_mfma_f32_16x16x32_bf16 v[32:35], v[170:173], v[186:189], v[32:35]
	v_mfma_f32_16x16x32_bf16 v[20:23], v[162:165], v[202:205], v[20:23]
	v_mfma_f32_16x16x32_bf16 v[16:19], v[170:173], v[202:205], v[16:19]
	v_mfma_f32_16x16x32_bf16 v[4:7], v[162:165], v[212:215], v[4:7]
	v_mfma_f32_16x16x32_bf16 v[0:3], v[170:173], v[212:215], v[0:3]
	v_mfma_f32_16x16x32_bf16 v[52:55], v[166:169], v[182:185], v[52:55]
	v_mfma_f32_16x16x32_bf16 v[48:51], v[174:177], v[182:185], v[48:51]
	v_mfma_f32_16x16x32_bf16 v[36:39], v[166:169], v[190:193], v[36:39]
	v_mfma_f32_16x16x32_bf16 v[32:35], v[174:177], v[190:193], v[32:35]
	v_mfma_f32_16x16x32_bf16 v[20:23], v[166:169], v[208:211], v[20:23]
	v_mfma_f32_16x16x32_bf16 v[16:19], v[174:177], v[208:211], v[16:19]
	v_mfma_f32_16x16x32_bf16 v[4:7], v[166:169], v[216:219], v[4:7]
	v_mfma_f32_16x16x32_bf16 v[0:3], v[174:177], v[216:219], v[0:3]
	s_setprio 0
	s_barrier
	s_add_i32 s0, 0, 0x18000
	v_add_u32_e32 v136, s0, v195
	s_add_i32 s1, 0, 0x1c000
	ds_read_b128 v[146:149], v136
	ds_read_b128 v[150:153], v136 offset:1024
	ds_read_b128 v[154:157], v136 offset:2048
	ds_read_b128 v[158:161], v136 offset:3072
	v_add_u32_e32 v136, s1, v195
	ds_read_b128 v[162:165], v136
	ds_read_b128 v[166:169], v136 offset:1024
	ds_read_b128 v[170:173], v136 offset:2048
	ds_read_b128 v[174:177], v136 offset:3072
	s_add_u32 s40, s40, 0x80000
	s_addc_u32 s41, s41, 0
	s_mov_b32 m0, s33
	v_lshl_add_u64 v[228:229], s[40:41], 0, v[128:129]
	ds_read_b128 v[178:181], v199 offset:32768
	ds_read_b128 v[182:185], v199 offset:33792
	ds_read_b128 v[186:189], v199 offset:34816
	ds_read_b128 v[190:193], v199 offset:35840
	ds_read_b128 v[202:205], v199 offset:36864
	ds_read_b128 v[208:211], v199 offset:37888
	ds_read_b128 v[212:215], v199 offset:38912
	ds_read_b128 v[216:219], v199 offset:39936
	global_load_lds_dwordx4 v[228:229], off
	v_lshl_add_u64 v[228:229], s[40:41], 0, v[132:133]
	s_mov_b32 m0, s42
	s_nop 0
	global_load_lds_dwordx4 v[228:229], off
	s_waitcnt vmcnt(8)
	s_waitcnt lgkmcnt(0)
	s_barrier
	s_setprio 1
	s_waitcnt lgkmcnt(0)
	v_mfma_f32_16x16x32_bf16 v[124:127], v[146:149], v[178:181], v[124:127]
	v_mfma_f32_16x16x32_bf16 v[120:123], v[154:157], v[178:181], v[120:123]
	v_mfma_f32_16x16x32_bf16 v[108:111], v[146:149], v[186:189], v[108:111]
	v_mfma_f32_16x16x32_bf16 v[104:107], v[154:157], v[186:189], v[104:107]
	v_mfma_f32_16x16x32_bf16 v[92:95], v[146:149], v[202:205], v[92:95]
	v_mfma_f32_16x16x32_bf16 v[88:91], v[154:157], v[202:205], v[88:91]
	v_mfma_f32_16x16x32_bf16 v[76:79], v[146:149], v[212:215], v[76:79]
	v_mfma_f32_16x16x32_bf16 v[72:75], v[154:157], v[212:215], v[72:75]
	v_mfma_f32_16x16x32_bf16 v[124:127], v[150:153], v[182:185], v[124:127]
	v_mfma_f32_16x16x32_bf16 v[120:123], v[158:161], v[182:185], v[120:123]
	v_mfma_f32_16x16x32_bf16 v[108:111], v[150:153], v[190:193], v[108:111]
	v_mfma_f32_16x16x32_bf16 v[104:107], v[158:161], v[190:193], v[104:107]
	v_mfma_f32_16x16x32_bf16 v[92:95], v[150:153], v[208:211], v[92:95]
	v_mfma_f32_16x16x32_bf16 v[88:91], v[158:161], v[208:211], v[88:91]
	v_mfma_f32_16x16x32_bf16 v[76:79], v[150:153], v[216:219], v[76:79]
	v_mfma_f32_16x16x32_bf16 v[72:75], v[158:161], v[216:219], v[72:75]
	s_setprio 0
	s_setprio 1
	v_mfma_f32_16x16x32_bf16 v[116:119], v[162:165], v[178:181], v[116:119]
	v_mfma_f32_16x16x32_bf16 v[112:115], v[170:173], v[178:181], v[112:115]
	v_mfma_f32_16x16x32_bf16 v[100:103], v[162:165], v[186:189], v[100:103]
	v_mfma_f32_16x16x32_bf16 v[96:99], v[170:173], v[186:189], v[96:99]
	v_mfma_f32_16x16x32_bf16 v[84:87], v[162:165], v[202:205], v[84:87]
	v_mfma_f32_16x16x32_bf16 v[80:83], v[170:173], v[202:205], v[80:83]
	v_mfma_f32_16x16x32_bf16 v[68:71], v[162:165], v[212:215], v[68:71]
	v_mfma_f32_16x16x32_bf16 v[64:67], v[170:173], v[212:215], v[64:67]
	v_mfma_f32_16x16x32_bf16 v[116:119], v[166:169], v[182:185], v[116:119]
	v_mfma_f32_16x16x32_bf16 v[112:115], v[174:177], v[182:185], v[112:115]
	v_mfma_f32_16x16x32_bf16 v[100:103], v[166:169], v[190:193], v[100:103]
	v_mfma_f32_16x16x32_bf16 v[96:99], v[174:177], v[190:193], v[96:99]
	v_mfma_f32_16x16x32_bf16 v[84:87], v[166:169], v[208:211], v[84:87]
	v_mfma_f32_16x16x32_bf16 v[80:83], v[174:177], v[208:211], v[80:83]
	v_mfma_f32_16x16x32_bf16 v[68:71], v[166:169], v[216:219], v[68:71]
	v_mfma_f32_16x16x32_bf16 v[64:67], v[174:177], v[216:219], v[64:67]
	s_setprio 0
	s_barrier
; #define PG8_STAGE(bufoff, gbase, voff) do { _Pragma("unroll") for (int _i = 0; _i < 2; ++_i) \
;         __builtin_amdgcn_global_load_lds((const unsigned*)((const char*)(gbase) + (voff)[_i]), (PG8_LAS unsigned*)(lds + (bufoff) + ldsw + _i * 8192), 16, 0, 0); } while (0)
; #define PG8_LDA(dst, b, h) do { _Pragma("unroll") for (int m = 0; m < 4; ++m) _Pragma("unroll") for (int k = 0; k < 2; ++k) dst[m][k] = *(const PG8_LAS bf16x8*)(lds + PG8_SA(b, h) + aoff + m * 2048 + k * 1024); } while (0)
; #define PG8_MMA(ai, bj, At, Bt) do { __builtin_amdgcn_s_setprio(1); _Pragma("unroll") for (int m = 0; m < 4; ++m) _Pragma("unroll") for (int n = 0; n < 2; ++n) _Pragma("unroll") for (int k = 0; k < 2; ++k) \
;         acc[ai][bj][m][n] = __builtin_amdgcn_mfma_f32_16x16x32_bf16(Bt[n][k], At[m][k], acc[ai][bj][m][n], 0, 0, 0); __builtin_amdgcn_s_setprio(0); } while (0)
; #define PG8_WAIT_V(n) asm volatile("s_waitcnt vmcnt(" #n ")" ::: "memory")
; #define PG8_WAIT_L(n) asm volatile("s_waitcnt lgkmcnt(" #n ")" ::: "memory")
; #define PG8_BAR __builtin_amdgcn_s_barrier()
; #define PG8_SCHED __builtin_amdgcn_sched_barrier(0)
; template <class Epi, class Sched, bool ALIGN_EPI = false, bool SP2 = false>
; __device__ __forceinline__ void gemm_phase(PG8_LAS unsigned char* lds, const Gemm g, const Sched& S, const Epi& E, int wave_s) {
;     ...
;         for (int t = 0; t < nt; t += 2) {
;             const bool last = (t == nt - 2);
;     ...
;             PG8_LDA(At, 1, 1); PG8_STAGE(PG8_SB(1, 0), b3, voffB); PG8_STAGE(PG8_SB(1, 1), b3 + hstep, voffB); PG8_STAGE(PG8_SA(1, 0), a3, voffA);
;             PG8_WAIT_V(8); PG8_WAIT_L(0); PG8_BAR; PG8_MMA(1, 0, At, B0); PG8_MMA(1, 1, At, B1); PG8_BAR; PG8_SCHED;
	s_add_i32 s0, s0, s19
	v_lshl_add_u64 v[220:221], v[220:221], 0, s[12:13]
	s_mov_b32 m0, s0
	ds_read_b128 v[178:181], v199 offset:49152
	ds_read_b128 v[182:185], v199 offset:50176
	ds_read_b128 v[186:189], v199 offset:51200
	ds_read_b128 v[190:193], v199 offset:52224
	ds_read_b128 v[202:205], v199 offset:53248
	ds_read_b128 v[208:211], v199 offset:54272
	ds_read_b128 v[212:215], v199 offset:55296
	ds_read_b128 v[216:219], v199 offset:56320
	global_load_lds_dwordx4 v[220:221], off
	s_add_i32 m0, s0, 0x2000
	s_add_u32 s38, s38, 0x80080
	v_lshl_add_u64 v[220:221], v[222:223], 0, s[12:13]
	s_addc_u32 s39, s39, 0
	s_add_i32 s0, s1, s19
	global_load_lds_dwordx4 v[220:221], off
	v_lshl_add_u64 v[220:221], s[38:39], 0, v[130:131]
	s_mov_b32 m0, s0
	s_nop 0
	global_load_lds_dwordx4 v[220:221], off
	v_lshl_add_u64 v[220:221], s[38:39], 0, v[134:135]
	s_add_i32 m0, s0, 0x2000
	s_nop 0
	global_load_lds_dwordx4 v[220:221], off
	v_lshl_add_u64 v[220:221], v[224:225], 0, s[12:13]
	s_mov_b32 m0, s44
	s_nop 0
	global_load_lds_dwordx4 v[220:221], off
	v_lshl_add_u64 v[220:221], v[226:227], 0, s[12:13]
	s_mov_b32 m0, s45
	s_nop 0
	global_load_lds_dwordx4 v[220:221], off
	s_waitcnt vmcnt(8)
	s_waitcnt lgkmcnt(0)
	s_barrier
	s_setprio 1
	s_waitcnt lgkmcnt(0)
	v_mfma_f32_16x16x32_bf16 v[60:63], v[146:149], v[178:181], v[60:63]
	v_mfma_f32_16x16x32_bf16 v[56:59], v[154:157], v[178:181], v[56:59]
	v_mfma_f32_16x16x32_bf16 v[44:47], v[146:149], v[186:189], v[44:47]
	v_mfma_f32_16x16x32_bf16 v[40:43], v[154:157], v[186:189], v[40:43]
	v_mfma_f32_16x16x32_bf16 v[28:31], v[146:149], v[202:205], v[28:31]
	v_mfma_f32_16x16x32_bf16 v[24:27], v[154:157], v[202:205], v[24:27]
	v_mfma_f32_16x16x32_bf16 v[12:15], v[146:149], v[212:215], v[12:15]
	v_mfma_f32_16x16x32_bf16 v[8:11], v[154:157], v[212:215], v[8:11]
	v_mfma_f32_16x16x32_bf16 v[60:63], v[150:153], v[182:185], v[60:63]
	v_mfma_f32_16x16x32_bf16 v[56:59], v[158:161], v[182:185], v[56:59]
	v_mfma_f32_16x16x32_bf16 v[44:47], v[150:153], v[190:193], v[44:47]
	v_mfma_f32_16x16x32_bf16 v[40:43], v[158:161], v[190:193], v[40:43]
	v_mfma_f32_16x16x32_bf16 v[28:31], v[150:153], v[208:211], v[28:31]
	v_mfma_f32_16x16x32_bf16 v[24:27], v[158:161], v[208:211], v[24:27]
	v_mfma_f32_16x16x32_bf16 v[12:15], v[150:153], v[216:219], v[12:15]
	v_mfma_f32_16x16x32_bf16 v[8:11], v[158:161], v[216:219], v[8:11]
	s_setprio 0
	s_setprio 1
	v_mfma_f32_16x16x32_bf16 v[52:55], v[162:165], v[178:181], v[52:55]
	v_mfma_f32_16x16x32_bf16 v[48:51], v[170:173], v[178:181], v[48:51]
	v_mfma_f32_16x16x32_bf16 v[36:39], v[162:165], v[186:189], v[36:39]
	v_mfma_f32_16x16x32_bf16 v[32:35], v[170:173], v[186:189], v[32:35]
	v_mfma_f32_16x16x32_bf16 v[20:23], v[162:165], v[202:205], v[20:23]
	v_mfma_f32_16x16x32_bf16 v[16:19], v[170:173], v[202:205], v[16:19]
	v_mfma_f32_16x16x32_bf16 v[4:7], v[162:165], v[212:215], v[4:7]
	v_mfma_f32_16x16x32_bf16 v[0:3], v[170:173], v[212:215], v[0:3]
	v_mfma_f32_16x16x32_bf16 v[52:55], v[166:169], v[182:185], v[52:55]
	v_mfma_f32_16x16x32_bf16 v[48:51], v[174:177], v[182:185], v[48:51]
	v_mfma_f32_16x16x32_bf16 v[36:39], v[166:169], v[190:193], v[36:39]
	v_mfma_f32_16x16x32_bf16 v[32:35], v[174:177], v[190:193], v[32:35]
	v_mfma_f32_16x16x32_bf16 v[20:23], v[166:169], v[208:211], v[20:23]
	v_mfma_f32_16x16x32_bf16 v[16:19], v[174:177], v[208:211], v[16:19]
	v_mfma_f32_16x16x32_bf16 v[4:7], v[166:169], v[216:219], v[4:7]
	v_mfma_f32_16x16x32_bf16 v[0:3], v[174:177], v[216:219], v[0:3]
	s_add_i32 s65, s65, 2
	s_add_u32 s36, s36, 0x100
	s_addc_u32 s37, s37, 0
	s_add_u32 s27, s27, 0x100
	s_addc_u32 s35, s35, 0
	s_cmp_gt_u32 s65, 29
	s_setprio 0
	s_barrier
	s_cbranch_scc0 .LBB0_1074
	s_and_b64 vcc, exec, s[14:15]
	s_cbranch_vccz .LBB0_1077
	s_barrier

; #define PG8_STAGE(bufoff, gbase, voff) do { _Pragma("unroll") for (int _i = 0; _i < 2; ++_i) \
;         __builtin_amdgcn_global_load_lds((const unsigned*)((const char*)(gbase) + (voff)[_i]), (PG8_LAS unsigned*)(lds + (bufoff) + ldsw + _i * 8192), 16, 0, 0); } while (0)
; #define PG8_LDA(dst, b, h) do { _Pragma("unroll") for (int m = 0; m < 4; ++m) _Pragma("unroll") for (int k = 0; k < 2; ++k) dst[m][k] = *(const PG8_LAS bf16x8*)(lds + PG8_SA(b, h) + aoff + m * 2048 + k * 1024); } while (0)
; #define PG8_LDB(dst, b, h) do { _Pragma("unroll") for (int n = 0; n < 2; ++n) _Pragma("unroll") for (int k = 0; k < 2; ++k) dst[n][k] = *(const PG8_LAS bf16x8*)(lds + PG8_SB(b, h) + boff + n * 2048 + k * 1024); } while (0)
; #define PG8_MMA(ai, bj, At, Bt) do { __builtin_amdgcn_s_setprio(1); _Pragma("unroll") for (int m = 0; m < 4; ++m) _Pragma("unroll") for (int n = 0; n < 2; ++n) _Pragma("unroll") for (int k = 0; k < 2; ++k) \
;         acc[ai][bj][m][n] = __builtin_amdgcn_mfma_f32_16x16x32_bf16(Bt[n][k], At[m][k], acc[ai][bj][m][n], 0, 0, 0); __builtin_amdgcn_s_setprio(0); } while (0)
; #define PG8_WAIT_V(n) asm volatile("s_waitcnt vmcnt(" #n ")" ::: "memory")
; #define PG8_WAIT_L(n) asm volatile("s_waitcnt lgkmcnt(" #n ")" ::: "memory")
; #define PG8_BAR __builtin_amdgcn_s_barrier()
; #define PG8_SCHED __builtin_amdgcn_sched_barrier(0)
; template <class Epi, class Sched, bool ALIGN_EPI = false, bool SP2 = false>
; __device__ __forceinline__ void gemm_phase(PG8_LAS unsigned char* lds, const Gemm g, const Sched& S, const Epi& E, int wave_s) {
;     ...
;         for (int t = 0; t < nt; t += 2) {
;             const bool last = (t == nt - 2);
;             const char* a1 = cA + (size_t)(t + 1) * kstep;
;             const char* a2 = last ? nA : cA + (size_t)(t + 2) * kstep; const char* b2 = last ? nB : cB + (size_t)(t + 2) * kstep;
;             const char* a3 = a2 + kstep; const char* b3 = b2 + kstep;
;             if (last && has_next) S.a_ready(nxt);
;             if constexpr (SP2) {
;             PG8_LDB(B0, 0, 0); PG8_LDB(B1, 0, 1); PG8_SCHED; PG8_LDA(At, 0, 0); PG8_STAGE(PG8_SA(1, 1), a1 + hstep, voffA);
;             PG8_WAIT_V(8); PG8_WAIT_L(0); PG8_BAR; PG8_MMA(0, 0, At, B0); PG8_MMA(0, 1, At, B1); PG8_BAR; PG8_SCHED;
;             PG8_LDA(At, 0, 1); PG8_STAGE(PG8_SB(0, 0), b2, voffB); PG8_STAGE(PG8_SB(0, 1), b2 + hstep, voffB); PG8_STAGE(PG8_SA(0, 0), a2, voffA);
.LBB0_1318:
	ds_read_b128 v[144:147], v151
	ds_read_b128 v[154:157], v151 offset:1024
	ds_read_b128 v[158:161], v151 offset:2048
	ds_read_b128 v[162:165], v151 offset:3072
	ds_read_b128 v[166:169], v152
	ds_read_b128 v[170:173], v152 offset:1024
	ds_read_b128 v[174:177], v152 offset:2048
	ds_read_b128 v[178:181], v152 offset:3072
	s_add_u32 s0, s28, 0xfff80080
	s_addc_u32 s1, s29, -1
	s_cmp_eq_u32 s49, 28
	s_cselect_b32 s35, s2, s1
	s_cselect_b32 s34, s3, s0
	s_cselect_b32 s31, s17, s48
	s_cselect_b32 s30, s21, s27
	v_lshl_add_u64 v[198:199], s[28:29], 0, v[136:137]
	s_add_i32 m0, s33, 0xc000
	ds_read_b128 v[182:185], v153
	ds_read_b128 v[186:189], v153 offset:1024
	ds_read_b128 v[190:193], v153 offset:2048
	ds_read_b128 v[194:197], v153 offset:3072
	ds_read_b128 v[202:205], v153 offset:4096
	ds_read_b128 v[208:211], v153 offset:5120
	ds_read_b128 v[212:215], v153 offset:6144
	ds_read_b128 v[216:219], v153 offset:7168
	global_load_lds_dwordx4 v[198:199], off
	v_lshl_add_u64 v[198:199], s[28:29], 0, v[138:139]
	s_add_i32 m0, s33, 0xe000
	s_nop 0
	global_load_lds_dwordx4 v[198:199], off
	s_waitcnt vmcnt(8)
	s_waitcnt lgkmcnt(0)
	s_barrier
	s_setprio 1
	s_waitcnt lgkmcnt(0)
	v_mfma_f32_16x16x32_bf16 v[124:127], v[144:147], v[182:185], v[124:127]
	v_mfma_f32_16x16x32_bf16 v[120:123], v[158:161], v[182:185], v[120:123]
	v_mfma_f32_16x16x32_bf16 v[108:111], v[144:147], v[190:193], v[108:111]
	v_mfma_f32_16x16x32_bf16 v[104:107], v[158:161], v[190:193], v[104:107]
	v_mfma_f32_16x16x32_bf16 v[92:95], v[144:147], v[202:205], v[92:95]
	v_mfma_f32_16x16x32_bf16 v[88:91], v[158:161], v[202:205], v[88:91]
	v_mfma_f32_16x16x32_bf16 v[76:79], v[144:147], v[212:215], v[76:79]
	v_mfma_f32_16x16x32_bf16 v[72:75], v[158:161], v[212:215], v[72:75]
	v_mfma_f32_16x16x32_bf16 v[124:127], v[154:157], v[186:189], v[124:127]
	v_mfma_f32_16x16x32_bf16 v[120:123], v[162:165], v[186:189], v[120:123]
	v_mfma_f32_16x16x32_bf16 v[108:111], v[154:157], v[194:197], v[108:111]
	v_mfma_f32_16x16x32_bf16 v[104:107], v[162:165], v[194:197], v[104:107]
	v_mfma_f32_16x16x32_bf16 v[92:95], v[154:157], v[208:211], v[92:95]
	v_mfma_f32_16x16x32_bf16 v[88:91], v[162:165], v[208:211], v[88:91]
	v_mfma_f32_16x16x32_bf16 v[76:79], v[154:157], v[216:219], v[76:79]
	v_mfma_f32_16x16x32_bf16 v[72:75], v[162:165], v[216:219], v[72:75]
	s_setprio 0
	s_setprio 1
	v_mfma_f32_16x16x32_bf16 v[116:119], v[166:169], v[182:185], v[116:119]
	v_mfma_f32_16x16x32_bf16 v[112:115], v[174:177], v[182:185], v[112:115]
	v_mfma_f32_16x16x32_bf16 v[100:103], v[166:169], v[190:193], v[100:103]
	v_mfma_f32_16x16x32_bf16 v[96:99], v[174:177], v[190:193], v[96:99]
	v_mfma_f32_16x16x32_bf16 v[84:87], v[166:169], v[202:205], v[84:87]
	v_mfma_f32_16x16x32_bf16 v[80:83], v[174:177], v[202:205], v[80:83]
	v_mfma_f32_16x16x32_bf16 v[68:71], v[166:169], v[212:215], v[68:71]
	v_mfma_f32_16x16x32_bf16 v[64:67], v[174:177], v[212:215], v[64:67]
	v_mfma_f32_16x16x32_bf16 v[116:119], v[170:173], v[186:189], v[116:119]
	v_mfma_f32_16x16x32_bf16 v[112:115], v[178:181], v[186:189], v[112:115]
	v_mfma_f32_16x16x32_bf16 v[100:103], v[170:173], v[194:197], v[100:103]
	v_mfma_f32_16x16x32_bf16 v[96:99], v[178:181], v[194:197], v[96:99]
	v_mfma_f32_16x16x32_bf16 v[84:87], v[170:173], v[208:211], v[84:87]
	v_mfma_f32_16x16x32_bf16 v[80:83], v[178:181], v[208:211], v[80:83]
	v_mfma_f32_16x16x32_bf16 v[68:71], v[170:173], v[216:219], v[68:71]
	v_mfma_f32_16x16x32_bf16 v[64:67], v[178:181], v[216:219], v[64:67]
	s_setprio 0
	s_barrier
	s_add_i32 s0, s45, s19
	v_lshl_add_u64 v[198:199], s[30:31], 0, v[130:131]
	s_mov_b32 m0, s0
	ds_read_b128 v[182:185], v153 offset:16384
	ds_read_b128 v[186:189], v153 offset:17408
	ds_read_b128 v[190:193], v153 offset:18432
	ds_read_b128 v[194:197], v153 offset:19456
	ds_read_b128 v[202:205], v153 offset:20480
	ds_read_b128 v[208:211], v153 offset:21504
	ds_read_b128 v[212:215], v153 offset:22528
	ds_read_b128 v[216:219], v153 offset:23552
	global_load_lds_dwordx4 v[198:199], off
	s_add_i32 m0, s0, 0x2000
	s_add_u32 s0, s30, 0x80000
	v_lshl_add_u64 v[220:221], s[30:31], 0, v[134:135]
	s_addc_u32 s1, s31, 0
	s_add_i32 s50, s46, s19
	global_load_lds_dwordx4 v[220:221], off
	v_lshl_add_u64 v[222:223], s[0:1], 0, v[130:131]
	s_mov_b32 m0, s50
	v_lshl_add_u64 v[224:225], s[34:35], 0, v[132:133]
	global_load_lds_dwordx4 v[222:223], off
	v_lshl_add_u64 v[222:223], s[0:1], 0, v[134:135]
	s_add_i32 m0, s50, 0x2000
	s_nop 0
	global_load_lds_dwordx4 v[222:223], off
	v_lshl_add_u64 v[222:223], s[34:35], 0, v[128:129]
	s_mov_b32 m0, s33
	s_nop 0
	global_load_lds_dwordx4 v[222:223], off
	s_mov_b32 m0, s36
	s_nop 0
	global_load_lds_dwordx4 v[224:225], off
	s_waitcnt vmcnt(8)
	s_waitcnt lgkmcnt(0)
	s_barrier
; #define PG8_STAGE(bufoff, gbase, voff) do { _Pragma("unroll") for (int _i = 0; _i < 2; ++_i) \
;         __builtin_amdgcn_global_load_lds((const unsigned*)((const char*)(gbase) + (voff)[_i]), (PG8_LAS unsigned*)(lds + (bufoff) + ldsw + _i * 8192), 16, 0, 0); } while (0)
; #define PG8_LDA(dst, b, h) do { _Pragma("unroll") for (int m = 0; m < 4; ++m) _Pragma("unroll") for (int k = 0; k < 2; ++k) dst[m][k] = *(const PG8_LAS bf16x8*)(lds + PG8_SA(b, h) + aoff + m * 2048 + k * 1024); } while (0)
; #define PG8_LDB(dst, b, h) do { _Pragma("unroll") for (int n = 0; n < 2; ++n) _Pragma("unroll") for (int k = 0; k < 2; ++k) dst[n][k] = *(const PG8_LAS bf16x8*)(lds + PG8_SB(b, h) + boff + n * 2048 + k * 1024); } while (0)
; #define PG8_MMA(ai, bj, At, Bt) do { __builtin_amdgcn_s_setprio(1); _Pragma("unroll") for (int m = 0; m < 4; ++m) _Pragma("unroll") for (int n = 0; n < 2; ++n) _Pragma("unroll") for (int k = 0; k < 2; ++k) \
;         acc[ai][bj][m][n] = __builtin_amdgcn_mfma_f32_16x16x32_bf16(Bt[n][k], At[m][k], acc[ai][bj][m][n], 0, 0, 0); __builtin_amdgcn_s_setprio(0); } while (0)
; #define PG8_WAIT_V(n) asm volatile("s_waitcnt vmcnt(" #n ")" ::: "memory")
; #define PG8_WAIT_L(n) asm volatile("s_waitcnt lgkmcnt(" #n ")" ::: "memory")
; #define PG8_BAR __builtin_amdgcn_s_barrier()
; #define PG8_SCHED __builtin_amdgcn_sched_barrier(0)
; template <class Epi, class Sched, bool ALIGN_EPI = false, bool SP2 = false>
; __device__ __forceinline__ void gemm_phase(PG8_LAS unsigned char* lds, const Gemm g, const Sched& S, const Epi& E, int wave_s) {
;     ...
;             PG8_WAIT_V(8); PG8_WAIT_L(0); PG8_BAR; PG8_MMA(1, 0, At, B0); PG8_MMA(1, 1, At, B1); PG8_BAR; PG8_SCHED;
;             PG8_LDB(B0, 1, 0); PG8_LDB(B1, 1, 1); PG8_SCHED; PG8_LDA(At, 1, 0); PG8_STAGE(PG8_SA(0, 1), a2 + hstep, voffA);
;             PG8_WAIT_V(8); PG8_WAIT_L(0); PG8_BAR; PG8_MMA(0, 0, At, B0); PG8_MMA(0, 1, At, B1); PG8_BAR; PG8_SCHED;
	s_setprio 1
	s_waitcnt lgkmcnt(0)
	v_mfma_f32_16x16x32_bf16 v[60:63], v[144:147], v[182:185], v[60:63]
	v_mfma_f32_16x16x32_bf16 v[56:59], v[158:161], v[182:185], v[56:59]
	v_mfma_f32_16x16x32_bf16 v[44:47], v[144:147], v[190:193], v[44:47]
	v_mfma_f32_16x16x32_bf16 v[40:43], v[158:161], v[190:193], v[40:43]
	v_mfma_f32_16x16x32_bf16 v[28:31], v[144:147], v[202:205], v[28:31]
	v_mfma_f32_16x16x32_bf16 v[24:27], v[158:161], v[202:205], v[24:27]
	v_mfma_f32_16x16x32_bf16 v[12:15], v[144:147], v[212:215], v[12:15]
	v_mfma_f32_16x16x32_bf16 v[8:11], v[158:161], v[212:215], v[8:11]
	v_mfma_f32_16x16x32_bf16 v[60:63], v[154:157], v[186:189], v[60:63]
	v_mfma_f32_16x16x32_bf16 v[56:59], v[162:165], v[186:189], v[56:59]
	v_mfma_f32_16x16x32_bf16 v[44:47], v[154:157], v[194:197], v[44:47]
	v_mfma_f32_16x16x32_bf16 v[40:43], v[162:165], v[194:197], v[40:43]
	v_mfma_f32_16x16x32_bf16 v[28:31], v[154:157], v[208:211], v[28:31]
	v_mfma_f32_16x16x32_bf16 v[24:27], v[162:165], v[208:211], v[24:27]
	v_mfma_f32_16x16x32_bf16 v[12:15], v[154:157], v[216:219], v[12:15]
	v_mfma_f32_16x16x32_bf16 v[8:11], v[162:165], v[216:219], v[8:11]
	s_setprio 0
	s_setprio 1
	v_mfma_f32_16x16x32_bf16 v[52:55], v[166:169], v[182:185], v[52:55]
	v_mfma_f32_16x16x32_bf16 v[48:51], v[174:177], v[182:185], v[48:51]
	v_mfma_f32_16x16x32_bf16 v[36:39], v[166:169], v[190:193], v[36:39]
	v_mfma_f32_16x16x32_bf16 v[32:35], v[174:177], v[190:193], v[32:35]
	v_mfma_f32_16x16x32_bf16 v[20:23], v[166:169], v[202:205], v[20:23]
	v_mfma_f32_16x16x32_bf16 v[16:19], v[174:177], v[202:205], v[16:19]
	v_mfma_f32_16x16x32_bf16 v[4:7], v[166:169], v[212:215], v[4:7]
	v_mfma_f32_16x16x32_bf16 v[0:3], v[174:177], v[212:215], v[0:3]
	v_mfma_f32_16x16x32_bf16 v[52:55], v[170:173], v[186:189], v[52:55]
	v_mfma_f32_16x16x32_bf16 v[48:51], v[178:181], v[186:189], v[48:51]
	v_mfma_f32_16x16x32_bf16 v[36:39], v[170:173], v[194:197], v[36:39]
	v_mfma_f32_16x16x32_bf16 v[32:35], v[178:181], v[194:197], v[32:35]
	v_mfma_f32_16x16x32_bf16 v[20:23], v[170:173], v[208:211], v[20:23]
	v_mfma_f32_16x16x32_bf16 v[16:19], v[178:181], v[208:211], v[16:19]
	v_mfma_f32_16x16x32_bf16 v[4:7], v[170:173], v[216:219], v[4:7]
	v_mfma_f32_16x16x32_bf16 v[0:3], v[178:181], v[216:219], v[0:3]
	s_setprio 0
	s_barrier
	s_add_i32 s50, 0, 0x18000
	s_add_i32 s51, 0, 0x1c000
	v_add_u32_e32 v162, s50, v149
	v_add_u32_e32 v178, s51, v149
	ds_read_b128 v[144:147], v162
	ds_read_b128 v[154:157], v162 offset:1024
	ds_read_b128 v[158:161], v162 offset:2048
	ds_read_b128 v[162:165], v162 offset:3072
	ds_read_b128 v[166:169], v178
	ds_read_b128 v[170:173], v178 offset:1024
	ds_read_b128 v[174:177], v178 offset:2048
	ds_read_b128 v[178:181], v178 offset:3072
	s_add_u32 s0, s34, 0x80000
	s_addc_u32 s1, s35, 0
	s_mov_b32 m0, s37
	v_lshl_add_u64 v[226:227], s[0:1], 0, v[128:129]
	ds_read_b128 v[182:185], v153 offset:32768
	ds_read_b128 v[186:189], v153 offset:33792
	ds_read_b128 v[190:193], v153 offset:34816
	ds_read_b128 v[194:197], v153 offset:35840
	ds_read_b128 v[202:205], v153 offset:36864
	ds_read_b128 v[208:211], v153 offset:37888
	ds_read_b128 v[212:215], v153 offset:38912
	ds_read_b128 v[216:219], v153 offset:39936
	global_load_lds_dwordx4 v[226:227], off
	v_lshl_add_u64 v[226:227], s[0:1], 0, v[132:133]
	s_mov_b32 m0, s38
	s_nop 0
	global_load_lds_dwordx4 v[226:227], off
	s_waitcnt vmcnt(8)
	s_waitcnt lgkmcnt(0)
	s_barrier
	s_setprio 1
	s_waitcnt lgkmcnt(0)
	v_mfma_f32_16x16x32_bf16 v[124:127], v[144:147], v[182:185], v[124:127]
	v_mfma_f32_16x16x32_bf16 v[120:123], v[158:161], v[182:185], v[120:123]
	v_mfma_f32_16x16x32_bf16 v[108:111], v[144:147], v[190:193], v[108:111]
	v_mfma_f32_16x16x32_bf16 v[104:107], v[158:161], v[190:193], v[104:107]
	v_mfma_f32_16x16x32_bf16 v[92:95], v[144:147], v[202:205], v[92:95]
	v_mfma_f32_16x16x32_bf16 v[88:91], v[158:161], v[202:205], v[88:91]
	v_mfma_f32_16x16x32_bf16 v[76:79], v[144:147], v[212:215], v[76:79]
	v_mfma_f32_16x16x32_bf16 v[72:75], v[158:161], v[212:215], v[72:75]
	v_mfma_f32_16x16x32_bf16 v[124:127], v[154:157], v[186:189], v[124:127]
	v_mfma_f32_16x16x32_bf16 v[120:123], v[162:165], v[186:189], v[120:123]
	v_mfma_f32_16x16x32_bf16 v[108:111], v[154:157], v[194:197], v[108:111]
	v_mfma_f32_16x16x32_bf16 v[104:107], v[162:165], v[194:197], v[104:107]
	v_mfma_f32_16x16x32_bf16 v[92:95], v[154:157], v[208:211], v[92:95]
	v_mfma_f32_16x16x32_bf16 v[88:91], v[162:165], v[208:211], v[88:91]
	v_mfma_f32_16x16x32_bf16 v[76:79], v[154:157], v[216:219], v[76:79]
	v_mfma_f32_16x16x32_bf16 v[72:75], v[162:165], v[216:219], v[72:75]
	s_setprio 0
	s_setprio 1
	v_mfma_f32_16x16x32_bf16 v[116:119], v[166:169], v[182:185], v[116:119]
	v_mfma_f32_16x16x32_bf16 v[112:115], v[174:177], v[182:185], v[112:115]
	v_mfma_f32_16x16x32_bf16 v[100:103], v[166:169], v[190:193], v[100:103]
	v_mfma_f32_16x16x32_bf16 v[96:99], v[174:177], v[190:193], v[96:99]
	v_mfma_f32_16x16x32_bf16 v[84:87], v[166:169], v[202:205], v[84:87]
	v_mfma_f32_16x16x32_bf16 v[80:83], v[174:177], v[202:205], v[80:83]
	v_mfma_f32_16x16x32_bf16 v[68:71], v[166:169], v[212:215], v[68:71]
	v_mfma_f32_16x16x32_bf16 v[64:67], v[174:177], v[212:215], v[64:67]
	v_mfma_f32_16x16x32_bf16 v[116:119], v[170:173], v[186:189], v[116:119]
	v_mfma_f32_16x16x32_bf16 v[112:115], v[178:181], v[186:189], v[112:115]
	v_mfma_f32_16x16x32_bf16 v[100:103], v[170:173], v[194:197], v[100:103]
	v_mfma_f32_16x16x32_bf16 v[96:99], v[178:181], v[194:197], v[96:99]
	v_mfma_f32_16x16x32_bf16 v[84:87], v[170:173], v[208:211], v[84:87]
	v_mfma_f32_16x16x32_bf16 v[80:83], v[178:181], v[208:211], v[80:83]
	v_mfma_f32_16x16x32_bf16 v[68:71], v[170:173], v[216:219], v[68:71]
	v_mfma_f32_16x16x32_bf16 v[64:67], v[178:181], v[216:219], v[64:67]
	s_setprio 0
	s_barrier
; #define PG8_STAGE(bufoff, gbase, voff) do { _Pragma("unroll") for (int _i = 0; _i < 2; ++_i) \
;         __builtin_amdgcn_global_load_lds((const unsigned*)((const char*)(gbase) + (voff)[_i]), (PG8_LAS unsigned*)(lds + (bufoff) + ldsw + _i * 8192), 16, 0, 0); } while (0)
; #define PG8_LDA(dst, b, h) do { _Pragma("unroll") for (int m = 0; m < 4; ++m) _Pragma("unroll") for (int k = 0; k < 2; ++k) dst[m][k] = *(const PG8_LAS bf16x8*)(lds + PG8_SA(b, h) + aoff + m * 2048 + k * 1024); } while (0)
; #define PG8_MMA(ai, bj, At, Bt) do { __builtin_amdgcn_s_setprio(1); _Pragma("unroll") for (int m = 0; m < 4; ++m) _Pragma("unroll") for (int n = 0; n < 2; ++n) _Pragma("unroll") for (int k = 0; k < 2; ++k) \
;         acc[ai][bj][m][n] = __builtin_amdgcn_mfma_f32_16x16x32_bf16(Bt[n][k], At[m][k], acc[ai][bj][m][n], 0, 0, 0); __builtin_amdgcn_s_setprio(0); } while (0)
; #define PG8_WAIT_V(n) asm volatile("s_waitcnt vmcnt(" #n ")" ::: "memory")
; #define PG8_WAIT_L(n) asm volatile("s_waitcnt lgkmcnt(" #n ")" ::: "memory")
; #define PG8_BAR __builtin_amdgcn_s_barrier()
; #define PG8_SCHED __builtin_amdgcn_sched_barrier(0)
; template <class Epi, class Sched, bool ALIGN_EPI = false, bool SP2 = false>
; __device__ __forceinline__ void gemm_phase(PG8_LAS unsigned char* lds, const Gemm g, const Sched& S, const Epi& E, int wave_s) {
;     ...
;         for (int t = 0; t < nt; t += 2) {
;             const bool last = (t == nt - 2);
;     ...
;             PG8_LDA(At, 1, 1); PG8_STAGE(PG8_SB(1, 0), b3, voffB); PG8_STAGE(PG8_SB(1, 1), b3 + hstep, voffB); PG8_STAGE(PG8_SA(1, 0), a3, voffA);
;             PG8_WAIT_V(8); PG8_WAIT_L(0); PG8_BAR; PG8_MMA(1, 0, At, B0); PG8_MMA(1, 1, At, B1); PG8_BAR; PG8_SCHED;
	s_add_i32 s0, s50, s19
	v_lshl_add_u64 v[198:199], v[198:199], 0, s[12:13]
	s_mov_b32 m0, s0
	ds_read_b128 v[182:185], v153 offset:49152
	ds_read_b128 v[186:189], v153 offset:50176
	ds_read_b128 v[190:193], v153 offset:51200
	ds_read_b128 v[194:197], v153 offset:52224
	ds_read_b128 v[202:205], v153 offset:53248
	ds_read_b128 v[208:211], v153 offset:54272
	ds_read_b128 v[212:215], v153 offset:55296
	ds_read_b128 v[216:219], v153 offset:56320
	global_load_lds_dwordx4 v[198:199], off
	s_add_i32 m0, s0, 0x2000
	s_add_u32 s0, s30, 0x80080
	v_lshl_add_u64 v[198:199], v[220:221], 0, s[12:13]
	s_addc_u32 s1, s31, 0
	s_add_i32 s30, s51, s19
	global_load_lds_dwordx4 v[198:199], off
	v_lshl_add_u64 v[198:199], s[0:1], 0, v[130:131]
	s_mov_b32 m0, s30
	s_nop 0
	global_load_lds_dwordx4 v[198:199], off
	v_lshl_add_u64 v[198:199], s[0:1], 0, v[134:135]
	s_add_i32 m0, s30, 0x2000
	s_nop 0
	global_load_lds_dwordx4 v[198:199], off
	v_lshl_add_u64 v[198:199], v[222:223], 0, s[12:13]
	s_mov_b32 m0, s40
	s_nop 0
	global_load_lds_dwordx4 v[198:199], off
	v_lshl_add_u64 v[198:199], v[224:225], 0, s[12:13]
	s_mov_b32 m0, s41
	s_nop 0
	global_load_lds_dwordx4 v[198:199], off
	s_waitcnt vmcnt(8)
	s_waitcnt lgkmcnt(0)
	s_barrier
	s_setprio 1
	s_waitcnt lgkmcnt(0)
	v_mfma_f32_16x16x32_bf16 v[60:63], v[144:147], v[182:185], v[60:63]
	v_mfma_f32_16x16x32_bf16 v[56:59], v[158:161], v[182:185], v[56:59]
	v_mfma_f32_16x16x32_bf16 v[44:47], v[144:147], v[190:193], v[44:47]
	v_mfma_f32_16x16x32_bf16 v[40:43], v[158:161], v[190:193], v[40:43]
	v_mfma_f32_16x16x32_bf16 v[28:31], v[144:147], v[202:205], v[28:31]
	v_mfma_f32_16x16x32_bf16 v[24:27], v[158:161], v[202:205], v[24:27]
	v_mfma_f32_16x16x32_bf16 v[12:15], v[144:147], v[212:215], v[12:15]
	v_mfma_f32_16x16x32_bf16 v[8:11], v[158:161], v[212:215], v[8:11]
	v_mfma_f32_16x16x32_bf16 v[60:63], v[154:157], v[186:189], v[60:63]
	v_mfma_f32_16x16x32_bf16 v[56:59], v[162:165], v[186:189], v[56:59]
	v_mfma_f32_16x16x32_bf16 v[44:47], v[154:157], v[194:197], v[44:47]
	v_mfma_f32_16x16x32_bf16 v[40:43], v[162:165], v[194:197], v[40:43]
	v_mfma_f32_16x16x32_bf16 v[28:31], v[154:157], v[208:211], v[28:31]
	v_mfma_f32_16x16x32_bf16 v[24:27], v[162:165], v[208:211], v[24:27]
	v_mfma_f32_16x16x32_bf16 v[12:15], v[154:157], v[216:219], v[12:15]
	v_mfma_f32_16x16x32_bf16 v[8:11], v[162:165], v[216:219], v[8:11]
	s_setprio 0
	s_setprio 1
	v_mfma_f32_16x16x32_bf16 v[52:55], v[166:169], v[182:185], v[52:55]
	v_mfma_f32_16x16x32_bf16 v[48:51], v[174:177], v[182:185], v[48:51]
	v_mfma_f32_16x16x32_bf16 v[36:39], v[166:169], v[190:193], v[36:39]
	v_mfma_f32_16x16x32_bf16 v[32:35], v[174:177], v[190:193], v[32:35]
	v_mfma_f32_16x16x32_bf16 v[20:23], v[166:169], v[202:205], v[20:23]
	v_mfma_f32_16x16x32_bf16 v[16:19], v[174:177], v[202:205], v[16:19]
	v_mfma_f32_16x16x32_bf16 v[4:7], v[166:169], v[212:215], v[4:7]
	v_mfma_f32_16x16x32_bf16 v[0:3], v[174:177], v[212:215], v[0:3]
	v_mfma_f32_16x16x32_bf16 v[52:55], v[170:173], v[186:189], v[52:55]
	v_mfma_f32_16x16x32_bf16 v[48:51], v[178:181], v[186:189], v[48:51]
	v_mfma_f32_16x16x32_bf16 v[36:39], v[170:173], v[194:197], v[36:39]
	v_mfma_f32_16x16x32_bf16 v[32:35], v[178:181], v[194:197], v[32:35]
	v_mfma_f32_16x16x32_bf16 v[20:23], v[170:173], v[208:211], v[20:23]
	v_mfma_f32_16x16x32_bf16 v[16:19], v[178:181], v[208:211], v[16:19]
	v_mfma_f32_16x16x32_bf16 v[4:7], v[170:173], v[216:219], v[4:7]
	v_mfma_f32_16x16x32_bf16 v[0:3], v[178:181], v[216:219], v[0:3]
	s_add_i32 s49, s49, 2
	s_add_u32 s28, s28, 0x100
	s_addc_u32 s29, s29, 0
	s_add_u32 s27, s27, 0x100
	s_addc_u32 s48, s48, 0
	s_cmp_gt_u32 s49, 29
	s_setprio 0
	s_barrier
	s_cbranch_scc0 .LBB0_1318
	s_and_b64 vcc, exec, s[14:15]
	s_cbranch_vccz .LBB0_1321
	s_barrier

; #define PG8_STAGE(bufoff, gbase, voff) do { _Pragma("unroll") for (int _i = 0; _i < 2; ++_i) \
;         __builtin_amdgcn_global_load_lds((const unsigned*)((const char*)(gbase) + (voff)[_i]), (PG8_LAS unsigned*)(lds + (bufoff) + ldsw + _i * 8192), 16, 0, 0); } while (0)
; #define PG8_LDA(dst, b, h) do { _Pragma("unroll") for (int m = 0; m < 4; ++m) _Pragma("unroll") for (int k = 0; k < 2; ++k) dst[m][k] = *(const PG8_LAS bf16x8*)(lds + PG8_SA(b, h) + aoff + m * 2048 + k * 1024); } while (0)
; #define PG8_LDB(dst, b, h) do { _Pragma("unroll") for (int n = 0; n < 2; ++n) _Pragma("unroll") for (int k = 0; k < 2; ++k) dst[n][k] = *(const PG8_LAS bf16x8*)(lds + PG8_SB(b, h) + boff + n * 2048 + k * 1024); } while (0)
; #define PG8_MMA(ai, bj, At, Bt) do { __builtin_amdgcn_s_setprio(1); _Pragma("unroll") for (int m = 0; m < 4; ++m) _Pragma("unroll") for (int n = 0; n < 2; ++n) _Pragma("unroll") for (int k = 0; k < 2; ++k) \
;         acc[ai][bj][m][n] = __builtin_amdgcn_mfma_f32_16x16x32_bf16(Bt[n][k], At[m][k], acc[ai][bj][m][n], 0, 0, 0); __builtin_amdgcn_s_setprio(0); } while (0)
; #define PG8_WAIT_V(n) asm volatile("s_waitcnt vmcnt(" #n ")" ::: "memory")
; #define PG8_WAIT_L(n) asm volatile("s_waitcnt lgkmcnt(" #n ")" ::: "memory")
; #define PG8_BAR __builtin_amdgcn_s_barrier()
; #define PG8_SCHED __builtin_amdgcn_sched_barrier(0)
; template <class Epi, class Sched, bool ALIGN_EPI = false, bool SP2 = false>
; __device__ __forceinline__ void gemm_phase(PG8_LAS unsigned char* lds, const Gemm g, const Sched& S, const Epi& E, int wave_s) {
;     ...
;         for (int t = 0; t < nt; t += 2) {
;             const bool last = (t == nt - 2);
;             const char* a1 = cA + (size_t)(t + 1) * kstep;
;             const char* a2 = last ? nA : cA + (size_t)(t + 2) * kstep; const char* b2 = last ? nB : cB + (size_t)(t + 2) * kstep;
;             const char* a3 = a2 + kstep; const char* b3 = b2 + kstep;
;             if (last && has_next) S.a_ready(nxt);
;             if constexpr (SP2) {
;             PG8_LDB(B0, 0, 0); PG8_LDB(B1, 0, 1); PG8_SCHED; PG8_LDA(At, 0, 0); PG8_STAGE(PG8_SA(1, 1), a1 + hstep, voffA);
;             PG8_WAIT_V(8); PG8_WAIT_L(0); PG8_BAR; PG8_MMA(0, 0, At, B0); PG8_MMA(0, 1, At, B1); PG8_BAR; PG8_SCHED;
;             PG8_LDA(At, 0, 1); PG8_STAGE(PG8_SB(0, 0), b2, voffB); PG8_STAGE(PG8_SB(0, 1), b2 + hstep, voffB); PG8_STAGE(PG8_SA(0, 0), a2, voffA);
.LBB0_1363:
	ds_read_b128 v[150:153], v147
	ds_read_b128 v[154:157], v147 offset:1024
	ds_read_b128 v[158:161], v147 offset:2048
	ds_read_b128 v[162:165], v147 offset:3072
	ds_read_b128 v[166:169], v148
	ds_read_b128 v[170:173], v148 offset:1024
	ds_read_b128 v[174:177], v148 offset:2048
	ds_read_b128 v[178:181], v148 offset:3072
	s_add_i32 s71, s36, 2
	s_add_u32 s0, s34, 0x80
	s_addc_u32 s1, s35, 0
	s_cmp_eq_u32 s50, s36
	s_cselect_b32 s36, s6, s0
	s_cselect_b32 s37, s7, s1
	s_cselect_b32 s1, s31, s3
	s_cselect_b32 s0, s30, s2
	v_lshl_add_u64 v[198:199], s[34:35], 0, v[136:137]
	s_add_i32 m0, s42, 0xc000
	ds_read_b128 v[182:185], v149
	ds_read_b128 v[186:189], v149 offset:1024
	ds_read_b128 v[190:193], v149 offset:2048
	ds_read_b128 v[194:197], v149 offset:3072
	ds_read_b128 v[202:205], v149 offset:4096
	ds_read_b128 v[208:211], v149 offset:5120
	ds_read_b128 v[212:215], v149 offset:6144
	ds_read_b128 v[216:219], v149 offset:7168
	global_load_lds_dwordx4 v[198:199], off
	v_lshl_add_u64 v[198:199], s[34:35], 0, v[138:139]
	s_add_i32 m0, s42, 0xe000
	s_nop 0
	global_load_lds_dwordx4 v[198:199], off
	s_waitcnt vmcnt(8)
	s_waitcnt lgkmcnt(0)
	s_barrier
	s_setprio 1
	s_waitcnt lgkmcnt(0)
	v_mfma_f32_16x16x32_bf16 v[120:123], v[150:153], v[182:185], v[120:123]
	v_mfma_f32_16x16x32_bf16 v[124:127], v[158:161], v[182:185], v[124:127]
	v_mfma_f32_16x16x32_bf16 v[108:111], v[150:153], v[190:193], v[108:111]
	v_mfma_f32_16x16x32_bf16 v[104:107], v[158:161], v[190:193], v[104:107]
	v_mfma_f32_16x16x32_bf16 v[92:95], v[150:153], v[202:205], v[92:95]
	v_mfma_f32_16x16x32_bf16 v[88:91], v[158:161], v[202:205], v[88:91]
	v_mfma_f32_16x16x32_bf16 v[76:79], v[150:153], v[212:215], v[76:79]
	v_mfma_f32_16x16x32_bf16 v[72:75], v[158:161], v[212:215], v[72:75]
	v_mfma_f32_16x16x32_bf16 v[120:123], v[154:157], v[186:189], v[120:123]
	v_mfma_f32_16x16x32_bf16 v[124:127], v[162:165], v[186:189], v[124:127]
	v_mfma_f32_16x16x32_bf16 v[108:111], v[154:157], v[194:197], v[108:111]
	v_mfma_f32_16x16x32_bf16 v[104:107], v[162:165], v[194:197], v[104:107]
	v_mfma_f32_16x16x32_bf16 v[92:95], v[154:157], v[208:211], v[92:95]
	v_mfma_f32_16x16x32_bf16 v[88:91], v[162:165], v[208:211], v[88:91]
	v_mfma_f32_16x16x32_bf16 v[76:79], v[154:157], v[216:219], v[76:79]
	v_mfma_f32_16x16x32_bf16 v[72:75], v[162:165], v[216:219], v[72:75]
	s_setprio 0
	s_setprio 1
	v_mfma_f32_16x16x32_bf16 v[116:119], v[166:169], v[182:185], v[116:119]
	v_mfma_f32_16x16x32_bf16 v[112:115], v[174:177], v[182:185], v[112:115]
	v_mfma_f32_16x16x32_bf16 v[100:103], v[166:169], v[190:193], v[100:103]
	v_mfma_f32_16x16x32_bf16 v[96:99], v[174:177], v[190:193], v[96:99]
	v_mfma_f32_16x16x32_bf16 v[84:87], v[166:169], v[202:205], v[84:87]
	v_mfma_f32_16x16x32_bf16 v[80:83], v[174:177], v[202:205], v[80:83]
	v_mfma_f32_16x16x32_bf16 v[68:71], v[166:169], v[212:215], v[68:71]
	v_mfma_f32_16x16x32_bf16 v[64:67], v[174:177], v[212:215], v[64:67]
	v_mfma_f32_16x16x32_bf16 v[116:119], v[170:173], v[186:189], v[116:119]
	v_mfma_f32_16x16x32_bf16 v[112:115], v[178:181], v[186:189], v[112:115]
	v_mfma_f32_16x16x32_bf16 v[100:103], v[170:173], v[194:197], v[100:103]
	v_mfma_f32_16x16x32_bf16 v[96:99], v[178:181], v[194:197], v[96:99]
	v_mfma_f32_16x16x32_bf16 v[84:87], v[170:173], v[208:211], v[84:87]
	v_mfma_f32_16x16x32_bf16 v[80:83], v[178:181], v[208:211], v[80:83]
	v_mfma_f32_16x16x32_bf16 v[68:71], v[170:173], v[216:219], v[68:71]
	v_mfma_f32_16x16x32_bf16 v[64:67], v[178:181], v[216:219], v[64:67]
	s_setprio 0
	s_barrier
	s_add_i32 s76, s53, s41
	v_lshl_add_u64 v[198:199], s[0:1], 0, v[130:131]
	s_mov_b32 m0, s76
	ds_read_b128 v[182:185], v149 offset:16384
	ds_read_b128 v[186:189], v149 offset:17408
	ds_read_b128 v[190:193], v149 offset:18432
	ds_read_b128 v[194:197], v149 offset:19456
	ds_read_b128 v[202:205], v149 offset:20480
	ds_read_b128 v[208:211], v149 offset:21504
	ds_read_b128 v[212:215], v149 offset:22528
	ds_read_b128 v[216:219], v149 offset:23552
	global_load_lds_dwordx4 v[198:199], off
	s_add_i32 m0, s76, 0x2000
	v_lshl_add_u64 v[220:221], s[0:1], 0, v[134:135]
	s_add_u32 s0, s0, s8
	s_addc_u32 s1, s1, s9
	s_add_i32 s76, s58, s41
	global_load_lds_dwordx4 v[220:221], off
	v_lshl_add_u64 v[222:223], s[0:1], 0, v[130:131]
	s_mov_b32 m0, s76
	v_lshl_add_u64 v[224:225], s[0:1], 0, v[134:135]
	global_load_lds_dwordx4 v[222:223], off
	s_add_i32 m0, s76, 0x2000
	v_lshl_add_u64 v[226:227], s[36:37], 0, v[128:129]
	global_load_lds_dwordx4 v[224:225], off
	s_mov_b32 m0, s42
	v_lshl_add_u64 v[228:229], s[36:37], 0, v[132:133]
	global_load_lds_dwordx4 v[226:227], off
	s_mov_b32 m0, s43
	s_nop 0
	global_load_lds_dwordx4 v[228:229], off
	s_waitcnt vmcnt(8)
	s_waitcnt lgkmcnt(0)
	s_barrier
; #define PG8_STAGE(bufoff, gbase, voff) do { _Pragma("unroll") for (int _i = 0; _i < 2; ++_i) \
;         __builtin_amdgcn_global_load_lds((const unsigned*)((const char*)(gbase) + (voff)[_i]), (PG8_LAS unsigned*)(lds + (bufoff) + ldsw + _i * 8192), 16, 0, 0); } while (0)
; #define PG8_LDA(dst, b, h) do { _Pragma("unroll") for (int m = 0; m < 4; ++m) _Pragma("unroll") for (int k = 0; k < 2; ++k) dst[m][k] = *(const PG8_LAS bf16x8*)(lds + PG8_SA(b, h) + aoff + m * 2048 + k * 1024); } while (0)
; #define PG8_LDB(dst, b, h) do { _Pragma("unroll") for (int n = 0; n < 2; ++n) _Pragma("unroll") for (int k = 0; k < 2; ++k) dst[n][k] = *(const PG8_LAS bf16x8*)(lds + PG8_SB(b, h) + boff + n * 2048 + k * 1024); } while (0)
; #define PG8_MMA(ai, bj, At, Bt) do { __builtin_amdgcn_s_setprio(1); _Pragma("unroll") for (int m = 0; m < 4; ++m) _Pragma("unroll") for (int n = 0; n < 2; ++n) _Pragma("unroll") for (int k = 0; k < 2; ++k) \
;         acc[ai][bj][m][n] = __builtin_amdgcn_mfma_f32_16x16x32_bf16(Bt[n][k], At[m][k], acc[ai][bj][m][n], 0, 0, 0); __builtin_amdgcn_s_setprio(0); } while (0)
; #define PG8_WAIT_V(n) asm volatile("s_waitcnt vmcnt(" #n ")" ::: "memory")
; #define PG8_WAIT_L(n) asm volatile("s_waitcnt lgkmcnt(" #n ")" ::: "memory")
; #define PG8_BAR __builtin_amdgcn_s_barrier()
; #define PG8_SCHED __builtin_amdgcn_sched_barrier(0)
; template <class Epi, class Sched, bool ALIGN_EPI = false, bool SP2 = false>
; __device__ __forceinline__ void gemm_phase(PG8_LAS unsigned char* lds, const Gemm g, const Sched& S, const Epi& E, int wave_s) {
;     ...
;             PG8_WAIT_V(8); PG8_WAIT_L(0); PG8_BAR; PG8_MMA(1, 0, At, B0); PG8_MMA(1, 1, At, B1); PG8_BAR; PG8_SCHED;
;             PG8_LDB(B0, 1, 0); PG8_LDB(B1, 1, 1); PG8_SCHED; PG8_LDA(At, 1, 0); PG8_STAGE(PG8_SA(0, 1), a2 + hstep, voffA);
;             PG8_WAIT_V(8); PG8_WAIT_L(0); PG8_BAR; PG8_MMA(0, 0, At, B0); PG8_MMA(0, 1, At, B1); PG8_BAR; PG8_SCHED;
	s_setprio 1
	s_waitcnt lgkmcnt(0)
	v_mfma_f32_16x16x32_bf16 v[60:63], v[150:153], v[182:185], v[60:63]
	v_mfma_f32_16x16x32_bf16 v[56:59], v[158:161], v[182:185], v[56:59]
	v_mfma_f32_16x16x32_bf16 v[44:47], v[150:153], v[190:193], v[44:47]
	v_mfma_f32_16x16x32_bf16 v[40:43], v[158:161], v[190:193], v[40:43]
	v_mfma_f32_16x16x32_bf16 v[28:31], v[150:153], v[202:205], v[28:31]
	v_mfma_f32_16x16x32_bf16 v[24:27], v[158:161], v[202:205], v[24:27]
	v_mfma_f32_16x16x32_bf16 v[12:15], v[150:153], v[212:215], v[12:15]
	v_mfma_f32_16x16x32_bf16 v[8:11], v[158:161], v[212:215], v[8:11]
	v_mfma_f32_16x16x32_bf16 v[60:63], v[154:157], v[186:189], v[60:63]
	v_mfma_f32_16x16x32_bf16 v[56:59], v[162:165], v[186:189], v[56:59]
	v_mfma_f32_16x16x32_bf16 v[44:47], v[154:157], v[194:197], v[44:47]
	v_mfma_f32_16x16x32_bf16 v[40:43], v[162:165], v[194:197], v[40:43]
	v_mfma_f32_16x16x32_bf16 v[28:31], v[154:157], v[208:211], v[28:31]
	v_mfma_f32_16x16x32_bf16 v[24:27], v[162:165], v[208:211], v[24:27]
	v_mfma_f32_16x16x32_bf16 v[12:15], v[154:157], v[216:219], v[12:15]
	v_mfma_f32_16x16x32_bf16 v[8:11], v[162:165], v[216:219], v[8:11]
	s_setprio 0
	s_setprio 1
	v_mfma_f32_16x16x32_bf16 v[52:55], v[166:169], v[182:185], v[52:55]
	v_mfma_f32_16x16x32_bf16 v[48:51], v[174:177], v[182:185], v[48:51]
	v_mfma_f32_16x16x32_bf16 v[36:39], v[166:169], v[190:193], v[36:39]
	v_mfma_f32_16x16x32_bf16 v[32:35], v[174:177], v[190:193], v[32:35]
	v_mfma_f32_16x16x32_bf16 v[20:23], v[166:169], v[202:205], v[20:23]
	v_mfma_f32_16x16x32_bf16 v[16:19], v[174:177], v[202:205], v[16:19]
	v_mfma_f32_16x16x32_bf16 v[4:7], v[166:169], v[212:215], v[4:7]
	v_mfma_f32_16x16x32_bf16 v[0:3], v[174:177], v[212:215], v[0:3]
	v_mfma_f32_16x16x32_bf16 v[52:55], v[170:173], v[186:189], v[52:55]
	v_mfma_f32_16x16x32_bf16 v[48:51], v[178:181], v[186:189], v[48:51]
	v_mfma_f32_16x16x32_bf16 v[36:39], v[170:173], v[194:197], v[36:39]
	v_mfma_f32_16x16x32_bf16 v[32:35], v[178:181], v[194:197], v[32:35]
	v_mfma_f32_16x16x32_bf16 v[20:23], v[170:173], v[208:211], v[20:23]
	v_mfma_f32_16x16x32_bf16 v[16:19], v[178:181], v[208:211], v[16:19]
	v_mfma_f32_16x16x32_bf16 v[4:7], v[170:173], v[216:219], v[4:7]
	v_mfma_f32_16x16x32_bf16 v[0:3], v[178:181], v[216:219], v[0:3]
	s_setprio 0
	s_barrier
	s_add_i32 s76, 0, 0x18000
	s_add_i32 s77, 0, 0x1c000
	v_add_u32_e32 v162, s76, v145
	v_add_u32_e32 v178, s77, v145
	ds_read_b128 v[150:153], v162
	ds_read_b128 v[154:157], v162 offset:1024
	ds_read_b128 v[158:161], v162 offset:2048
	ds_read_b128 v[162:165], v162 offset:3072
	ds_read_b128 v[166:169], v178
	ds_read_b128 v[170:173], v178 offset:1024
	ds_read_b128 v[174:177], v178 offset:2048
	ds_read_b128 v[178:181], v178 offset:3072
	s_add_u32 s0, s36, s8
	s_addc_u32 s1, s37, s9
	s_mov_b32 m0, s44
	v_lshl_add_u64 v[230:231], s[0:1], 0, v[128:129]
	ds_read_b128 v[182:185], v149 offset:32768
	ds_read_b128 v[186:189], v149 offset:33792
	ds_read_b128 v[190:193], v149 offset:34816
	ds_read_b128 v[194:197], v149 offset:35840
	ds_read_b128 v[202:205], v149 offset:36864
	ds_read_b128 v[208:211], v149 offset:37888
	ds_read_b128 v[212:215], v149 offset:38912
	ds_read_b128 v[216:219], v149 offset:39936
	global_load_lds_dwordx4 v[230:231], off
	v_lshl_add_u64 v[230:231], s[0:1], 0, v[132:133]
	s_mov_b32 m0, s45
	s_nop 0
	global_load_lds_dwordx4 v[230:231], off
	s_waitcnt vmcnt(8)
	s_waitcnt lgkmcnt(0)
	s_barrier
	s_setprio 1
	s_waitcnt lgkmcnt(0)
	v_mfma_f32_16x16x32_bf16 v[120:123], v[150:153], v[182:185], v[120:123]
	v_mfma_f32_16x16x32_bf16 v[124:127], v[158:161], v[182:185], v[124:127]
	v_mfma_f32_16x16x32_bf16 v[108:111], v[150:153], v[190:193], v[108:111]
	v_mfma_f32_16x16x32_bf16 v[104:107], v[158:161], v[190:193], v[104:107]
	v_mfma_f32_16x16x32_bf16 v[92:95], v[150:153], v[202:205], v[92:95]
	v_mfma_f32_16x16x32_bf16 v[88:91], v[158:161], v[202:205], v[88:91]
	v_mfma_f32_16x16x32_bf16 v[76:79], v[150:153], v[212:215], v[76:79]
	v_mfma_f32_16x16x32_bf16 v[72:75], v[158:161], v[212:215], v[72:75]
	v_mfma_f32_16x16x32_bf16 v[120:123], v[154:157], v[186:189], v[120:123]
	v_mfma_f32_16x16x32_bf16 v[124:127], v[162:165], v[186:189], v[124:127]
	v_mfma_f32_16x16x32_bf16 v[108:111], v[154:157], v[194:197], v[108:111]
	v_mfma_f32_16x16x32_bf16 v[104:107], v[162:165], v[194:197], v[104:107]
	v_mfma_f32_16x16x32_bf16 v[92:95], v[154:157], v[208:211], v[92:95]
	v_mfma_f32_16x16x32_bf16 v[88:91], v[162:165], v[208:211], v[88:91]
	v_mfma_f32_16x16x32_bf16 v[76:79], v[154:157], v[216:219], v[76:79]
	v_mfma_f32_16x16x32_bf16 v[72:75], v[162:165], v[216:219], v[72:75]
	s_setprio 0
	s_setprio 1
	v_mfma_f32_16x16x32_bf16 v[116:119], v[166:169], v[182:185], v[116:119]
	v_mfma_f32_16x16x32_bf16 v[112:115], v[174:177], v[182:185], v[112:115]
	v_mfma_f32_16x16x32_bf16 v[100:103], v[166:169], v[190:193], v[100:103]
	v_mfma_f32_16x16x32_bf16 v[96:99], v[174:177], v[190:193], v[96:99]
	v_mfma_f32_16x16x32_bf16 v[84:87], v[166:169], v[202:205], v[84:87]
	v_mfma_f32_16x16x32_bf16 v[80:83], v[174:177], v[202:205], v[80:83]
	v_mfma_f32_16x16x32_bf16 v[68:71], v[166:169], v[212:215], v[68:71]
	v_mfma_f32_16x16x32_bf16 v[64:67], v[174:177], v[212:215], v[64:67]
	v_mfma_f32_16x16x32_bf16 v[116:119], v[170:173], v[186:189], v[116:119]
	v_mfma_f32_16x16x32_bf16 v[112:115], v[178:181], v[186:189], v[112:115]
	v_mfma_f32_16x16x32_bf16 v[100:103], v[170:173], v[194:197], v[100:103]
	v_mfma_f32_16x16x32_bf16 v[96:99], v[178:181], v[194:197], v[96:99]
	v_mfma_f32_16x16x32_bf16 v[84:87], v[170:173], v[208:211], v[84:87]
	v_mfma_f32_16x16x32_bf16 v[80:83], v[178:181], v[208:211], v[80:83]
	v_mfma_f32_16x16x32_bf16 v[68:71], v[170:173], v[216:219], v[68:71]
	v_mfma_f32_16x16x32_bf16 v[64:67], v[178:181], v[216:219], v[64:67]
	s_setprio 0
	s_barrier
; #define PG8_STAGE(bufoff, gbase, voff) do { _Pragma("unroll") for (int _i = 0; _i < 2; ++_i) \
;         __builtin_amdgcn_global_load_lds((const unsigned*)((const char*)(gbase) + (voff)[_i]), (PG8_LAS unsigned*)(lds + (bufoff) + ldsw + _i * 8192), 16, 0, 0); } while (0)
; #define PG8_LDA(dst, b, h) do { _Pragma("unroll") for (int m = 0; m < 4; ++m) _Pragma("unroll") for (int k = 0; k < 2; ++k) dst[m][k] = *(const PG8_LAS bf16x8*)(lds + PG8_SA(b, h) + aoff + m * 2048 + k * 1024); } while (0)
; #define PG8_MMA(ai, bj, At, Bt) do { __builtin_amdgcn_s_setprio(1); _Pragma("unroll") for (int m = 0; m < 4; ++m) _Pragma("unroll") for (int n = 0; n < 2; ++n) _Pragma("unroll") for (int k = 0; k < 2; ++k) \
;         acc[ai][bj][m][n] = __builtin_amdgcn_mfma_f32_16x16x32_bf16(Bt[n][k], At[m][k], acc[ai][bj][m][n], 0, 0, 0); __builtin_amdgcn_s_setprio(0); } while (0)
; #define PG8_WAIT_V(n) asm volatile("s_waitcnt vmcnt(" #n ")" ::: "memory")
; #define PG8_WAIT_L(n) asm volatile("s_waitcnt lgkmcnt(" #n ")" ::: "memory")
; #define PG8_BAR __builtin_amdgcn_s_barrier()
; #define PG8_SCHED __builtin_amdgcn_sched_barrier(0)
; template <class Epi, class Sched, bool ALIGN_EPI = false, bool SP2 = false>
; __device__ __forceinline__ void gemm_phase(PG8_LAS unsigned char* lds, const Gemm g, const Sched& S, const Epi& E, int wave_s) {
;     ...
;         for (int t = 0; t < nt; t += 2) {
;             const bool last = (t == nt - 2);
;     ...
;             PG8_LDA(At, 1, 1); PG8_STAGE(PG8_SB(1, 0), b3, voffB); PG8_STAGE(PG8_SB(1, 1), b3 + hstep, voffB); PG8_STAGE(PG8_SA(1, 0), a3, voffA);
;             PG8_WAIT_V(8); PG8_WAIT_L(0); PG8_BAR; PG8_MMA(1, 0, At, B0); PG8_MMA(1, 1, At, B1); PG8_BAR; PG8_SCHED;
	s_add_i32 s0, s76, s41
	v_lshl_add_u64 v[198:199], v[198:199], 0, s[14:15]
	s_mov_b32 m0, s0
	ds_read_b128 v[182:185], v149 offset:49152
	ds_read_b128 v[186:189], v149 offset:50176
	ds_read_b128 v[190:193], v149 offset:51200
	ds_read_b128 v[194:197], v149 offset:52224
	ds_read_b128 v[202:205], v149 offset:53248
	ds_read_b128 v[208:211], v149 offset:54272
	ds_read_b128 v[212:215], v149 offset:55296
	ds_read_b128 v[216:219], v149 offset:56320
	global_load_lds_dwordx4 v[198:199], off
	v_lshl_add_u64 v[198:199], v[220:221], 0, s[14:15]
	s_add_i32 m0, s0, 0x2000
	s_add_i32 s0, s77, s41
	global_load_lds_dwordx4 v[198:199], off
	v_lshl_add_u64 v[198:199], v[222:223], 0, s[14:15]
	s_mov_b32 m0, s0
	s_nop 0
	global_load_lds_dwordx4 v[198:199], off
	v_lshl_add_u64 v[198:199], v[224:225], 0, s[14:15]
	s_add_i32 m0, s0, 0x2000
	s_nop 0
	global_load_lds_dwordx4 v[198:199], off
	v_lshl_add_u64 v[198:199], v[226:227], 0, s[14:15]
	s_mov_b32 m0, s47
	s_nop 0
	global_load_lds_dwordx4 v[198:199], off
	v_lshl_add_u64 v[198:199], v[228:229], 0, s[14:15]
	s_mov_b32 m0, s48
	s_nop 0
	global_load_lds_dwordx4 v[198:199], off
	s_waitcnt vmcnt(8)
	s_waitcnt lgkmcnt(0)
	s_barrier
	s_setprio 1
	s_waitcnt lgkmcnt(0)
	v_mfma_f32_16x16x32_bf16 v[60:63], v[150:153], v[182:185], v[60:63]
	v_mfma_f32_16x16x32_bf16 v[56:59], v[158:161], v[182:185], v[56:59]
	v_mfma_f32_16x16x32_bf16 v[44:47], v[150:153], v[190:193], v[44:47]
	v_mfma_f32_16x16x32_bf16 v[40:43], v[158:161], v[190:193], v[40:43]
	v_mfma_f32_16x16x32_bf16 v[28:31], v[150:153], v[202:205], v[28:31]
	v_mfma_f32_16x16x32_bf16 v[24:27], v[158:161], v[202:205], v[24:27]
	v_mfma_f32_16x16x32_bf16 v[12:15], v[150:153], v[212:215], v[12:15]
	v_mfma_f32_16x16x32_bf16 v[8:11], v[158:161], v[212:215], v[8:11]
	v_mfma_f32_16x16x32_bf16 v[60:63], v[154:157], v[186:189], v[60:63]
	v_mfma_f32_16x16x32_bf16 v[56:59], v[162:165], v[186:189], v[56:59]
	v_mfma_f32_16x16x32_bf16 v[44:47], v[154:157], v[194:197], v[44:47]
	v_mfma_f32_16x16x32_bf16 v[40:43], v[162:165], v[194:197], v[40:43]
	v_mfma_f32_16x16x32_bf16 v[28:31], v[154:157], v[208:211], v[28:31]
	v_mfma_f32_16x16x32_bf16 v[24:27], v[162:165], v[208:211], v[24:27]
	v_mfma_f32_16x16x32_bf16 v[12:15], v[154:157], v[216:219], v[12:15]
	v_mfma_f32_16x16x32_bf16 v[8:11], v[162:165], v[216:219], v[8:11]
	s_setprio 0
	s_setprio 1
	v_mfma_f32_16x16x32_bf16 v[52:55], v[166:169], v[182:185], v[52:55]
	v_mfma_f32_16x16x32_bf16 v[48:51], v[174:177], v[182:185], v[48:51]
	v_mfma_f32_16x16x32_bf16 v[36:39], v[166:169], v[190:193], v[36:39]
	v_mfma_f32_16x16x32_bf16 v[32:35], v[174:177], v[190:193], v[32:35]
	v_mfma_f32_16x16x32_bf16 v[20:23], v[166:169], v[202:205], v[20:23]
	v_mfma_f32_16x16x32_bf16 v[16:19], v[174:177], v[202:205], v[16:19]
	v_mfma_f32_16x16x32_bf16 v[4:7], v[166:169], v[212:215], v[4:7]
	v_mfma_f32_16x16x32_bf16 v[0:3], v[174:177], v[212:215], v[0:3]
	v_mfma_f32_16x16x32_bf16 v[52:55], v[170:173], v[186:189], v[52:55]
	v_mfma_f32_16x16x32_bf16 v[48:51], v[178:181], v[186:189], v[48:51]
	v_mfma_f32_16x16x32_bf16 v[36:39], v[170:173], v[194:197], v[36:39]
	v_mfma_f32_16x16x32_bf16 v[32:35], v[178:181], v[194:197], v[32:35]
	v_mfma_f32_16x16x32_bf16 v[20:23], v[170:173], v[208:211], v[20:23]
	v_mfma_f32_16x16x32_bf16 v[16:19], v[178:181], v[208:211], v[16:19]
	v_mfma_f32_16x16x32_bf16 v[4:7], v[170:173], v[216:219], v[4:7]
	v_mfma_f32_16x16x32_bf16 v[0:3], v[178:181], v[216:219], v[0:3]
	s_add_u32 s34, s34, 0x100
	s_addc_u32 s35, s35, 0
	s_add_u32 s2, s2, 0x100
	s_addc_u32 s3, s3, 0
	s_cmp_ge_i32 s71, s49
	s_mov_b32 s36, s71
	s_setprio 0
	s_barrier
	s_cbranch_scc0 .LBB0_1363

; #define PG8_STAGE(bufoff, gbase, voff) do { _Pragma("unroll") for (int _i = 0; _i < 2; ++_i) \
;         __builtin_amdgcn_global_load_lds((const unsigned*)((const char*)(gbase) + (voff)[_i]), (PG8_LAS unsigned*)(lds + (bufoff) + ldsw + _i * 8192), 16, 0, 0); } while (0)
; #define PG8_LDA(dst, b, h) do { _Pragma("unroll") for (int m = 0; m < 4; ++m) _Pragma("unroll") for (int k = 0; k < 2; ++k) dst[m][k] = *(const PG8_LAS bf16x8*)(lds + PG8_SA(b, h) + aoff + m * 2048 + k * 1024); } while (0)
; #define PG8_LDB(dst, b, h) do { _Pragma("unroll") for (int n = 0; n < 2; ++n) _Pragma("unroll") for (int k = 0; k < 2; ++k) dst[n][k] = *(const PG8_LAS bf16x8*)(lds + PG8_SB(b, h) + boff + n * 2048 + k * 1024); } while (0)
; #define PG8_MMA(ai, bj, At, Bt) do { __builtin_amdgcn_s_setprio(1); _Pragma("unroll") for (int m = 0; m < 4; ++m) _Pragma("unroll") for (int n = 0; n < 2; ++n) _Pragma("unroll") for (int k = 0; k < 2; ++k) \
;         acc[ai][bj][m][n] = __builtin_amdgcn_mfma_f32_16x16x32_bf16(Bt[n][k], At[m][k], acc[ai][bj][m][n], 0, 0, 0); __builtin_amdgcn_s_setprio(0); } while (0)
; #define PG8_WAIT_V(n) asm volatile("s_waitcnt vmcnt(" #n ")" ::: "memory")
; #define PG8_WAIT_L(n) asm volatile("s_waitcnt lgkmcnt(" #n ")" ::: "memory")
; #define PG8_BAR __builtin_amdgcn_s_barrier()
; #define PG8_SCHED __builtin_amdgcn_sched_barrier(0)
; template <class Epi, class Sched, bool ALIGN_EPI = false, bool SP2 = false>
; __device__ __forceinline__ void gemm_phase(PG8_LAS unsigned char* lds, const Gemm g, const Sched& S, const Epi& E, int wave_s) {
;     ...
;         for (int t = 0; t < nt; t += 2) {
;             const bool last = (t == nt - 2);
;             const char* a1 = cA + (size_t)(t + 1) * kstep;
;             const char* a2 = last ? nA : cA + (size_t)(t + 2) * kstep; const char* b2 = last ? nB : cB + (size_t)(t + 2) * kstep;
;             const char* a3 = a2 + kstep; const char* b3 = b2 + kstep;
;             if (last && has_next) S.a_ready(nxt);
;             if constexpr (SP2) {
;             PG8_LDB(B0, 0, 0); PG8_LDB(B1, 0, 1); PG8_SCHED; PG8_LDA(At, 0, 0); PG8_STAGE(PG8_SA(1, 1), a1 + hstep, voffA);
;             PG8_WAIT_V(8); PG8_WAIT_L(0); PG8_BAR; PG8_MMA(0, 0, At, B0); PG8_MMA(0, 1, At, B1); PG8_BAR; PG8_SCHED;
;             PG8_LDA(At, 0, 1); PG8_STAGE(PG8_SB(0, 0), b2, voffB); PG8_STAGE(PG8_SB(0, 1), b2 + hstep, voffB); PG8_STAGE(PG8_SA(0, 0), a2, voffA);
.LBB0_1498:
	ds_read_b128 v[56:59], v161
	ds_read_b128 v[60:63], v161 offset:1024
	ds_read_b128 v[168:171], v161 offset:2048
	ds_read_b128 v[172:175], v161 offset:3072
	ds_read_b128 v[176:179], v163
	ds_read_b128 v[180:183], v163 offset:1024
	ds_read_b128 v[184:187], v163 offset:2048
	ds_read_b128 v[188:191], v163 offset:3072
	s_add_u32 s34, s30, 0xfff80080
	s_addc_u32 s35, s31, -1
	s_cmp_eq_u32 s56, 28
	s_cselect_b32 s37, s23, s35
	s_cselect_b32 s36, s50, s34
	s_cselect_b32 s35, s21, s53
	s_cselect_b32 s34, s51, s52
	v_lshl_add_u64 v[154:155], s[30:31], 0, v[144:145]
	s_add_i32 m0, s29, 0xc000
	ds_read_b128 v[192:195], v167
	ds_read_b128 v[196:199], v167 offset:1024
	ds_read_b128 v[200:203], v167 offset:2048
	ds_read_b128 v[204:207], v167 offset:3072
	ds_read_b128 v[208:211], v167 offset:4096
	ds_read_b128 v[212:215], v167 offset:5120
	ds_read_b128 v[216:219], v167 offset:6144
	ds_read_b128 v[220:223], v167 offset:7168
	global_load_lds_dwordx4 v[154:155], off
	v_lshl_add_u64 v[154:155], s[30:31], 0, v[146:147]
	s_add_i32 m0, s29, 0xe000
	s_nop 0
	global_load_lds_dwordx4 v[154:155], off
	s_waitcnt vmcnt(8)
	s_waitcnt lgkmcnt(0)
	s_barrier
	s_setprio 1
	s_waitcnt lgkmcnt(0)
	v_mfma_f32_16x16x32_bf16 v[52:55], v[56:59], v[192:195], v[52:55]
	v_mfma_f32_16x16x32_bf16 v[48:51], v[168:171], v[192:195], v[48:51]
	v_mfma_f32_16x16x32_bf16 v[124:127], v[56:59], v[200:203], v[124:127]
	v_mfma_f32_16x16x32_bf16 v[120:123], v[168:171], v[200:203], v[120:123]
	v_mfma_f32_16x16x32_bf16 v[108:111], v[56:59], v[208:211], v[108:111]
	v_mfma_f32_16x16x32_bf16 v[104:107], v[168:171], v[208:211], v[104:107]
	v_mfma_f32_16x16x32_bf16 v[92:95], v[56:59], v[216:219], v[92:95]
	v_mfma_f32_16x16x32_bf16 v[88:91], v[168:171], v[216:219], v[88:91]
	v_mfma_f32_16x16x32_bf16 v[52:55], v[60:63], v[196:199], v[52:55]
	v_mfma_f32_16x16x32_bf16 v[48:51], v[172:175], v[196:199], v[48:51]
	v_mfma_f32_16x16x32_bf16 v[124:127], v[60:63], v[204:207], v[124:127]
	v_mfma_f32_16x16x32_bf16 v[120:123], v[172:175], v[204:207], v[120:123]
	v_mfma_f32_16x16x32_bf16 v[108:111], v[60:63], v[212:215], v[108:111]
	v_mfma_f32_16x16x32_bf16 v[104:107], v[172:175], v[212:215], v[104:107]
	v_mfma_f32_16x16x32_bf16 v[92:95], v[60:63], v[220:223], v[92:95]
	v_mfma_f32_16x16x32_bf16 v[88:91], v[172:175], v[220:223], v[88:91]
	s_setprio 0
	s_setprio 1
	v_mfma_f32_16x16x32_bf16 v[132:135], v[176:179], v[192:195], v[132:135]
	v_mfma_f32_16x16x32_bf16 v[128:131], v[184:187], v[192:195], v[128:131]
	v_mfma_f32_16x16x32_bf16 v[116:119], v[176:179], v[200:203], v[116:119]
	v_mfma_f32_16x16x32_bf16 v[112:115], v[184:187], v[200:203], v[112:115]
	v_mfma_f32_16x16x32_bf16 v[100:103], v[176:179], v[208:211], v[100:103]
	v_mfma_f32_16x16x32_bf16 v[96:99], v[184:187], v[208:211], v[96:99]
	v_mfma_f32_16x16x32_bf16 v[84:87], v[176:179], v[216:219], v[84:87]
	v_mfma_f32_16x16x32_bf16 v[80:83], v[184:187], v[216:219], v[80:83]
	v_mfma_f32_16x16x32_bf16 v[132:135], v[180:183], v[196:199], v[132:135]
	v_mfma_f32_16x16x32_bf16 v[128:131], v[188:191], v[196:199], v[128:131]
	v_mfma_f32_16x16x32_bf16 v[116:119], v[180:183], v[204:207], v[116:119]
	v_mfma_f32_16x16x32_bf16 v[112:115], v[188:191], v[204:207], v[112:115]
	v_mfma_f32_16x16x32_bf16 v[100:103], v[180:183], v[212:215], v[100:103]
	v_mfma_f32_16x16x32_bf16 v[96:99], v[188:191], v[212:215], v[96:99]
	v_mfma_f32_16x16x32_bf16 v[84:87], v[180:183], v[220:223], v[84:87]
	v_mfma_f32_16x16x32_bf16 v[80:83], v[188:191], v[220:223], v[80:83]
	s_setprio 0
	s_barrier
	s_add_i32 s57, s47, s39
	v_lshl_add_u64 v[154:155], s[34:35], 0, v[138:139]
	s_mov_b32 m0, s57
	ds_read_b128 v[192:195], v167 offset:16384
	ds_read_b128 v[196:199], v167 offset:17408
	ds_read_b128 v[200:203], v167 offset:18432
	ds_read_b128 v[204:207], v167 offset:19456
	ds_read_b128 v[208:211], v167 offset:20480
	ds_read_b128 v[212:215], v167 offset:21504
	ds_read_b128 v[216:219], v167 offset:22528
	ds_read_b128 v[220:223], v167 offset:23552
	global_load_lds_dwordx4 v[154:155], off
	s_add_i32 m0, s57, 0x2000
	s_add_u32 s58, s34, 0x80000
	v_lshl_add_u64 v[164:165], s[34:35], 0, v[142:143]
	s_addc_u32 s59, s35, 0
	s_add_i32 s57, s48, s39
	global_load_lds_dwordx4 v[164:165], off
	v_lshl_add_u64 v[224:225], s[58:59], 0, v[138:139]
	s_mov_b32 m0, s57
	v_lshl_add_u64 v[226:227], s[36:37], 0, v[140:141]
	global_load_lds_dwordx4 v[224:225], off
	v_lshl_add_u64 v[224:225], s[58:59], 0, v[142:143]
	s_add_i32 m0, s57, 0x2000
	s_nop 0
	global_load_lds_dwordx4 v[224:225], off
	v_lshl_add_u64 v[224:225], s[36:37], 0, v[136:137]
	s_mov_b32 m0, s29
	s_nop 0
	global_load_lds_dwordx4 v[224:225], off
	s_mov_b32 m0, s40
	s_nop 0
	global_load_lds_dwordx4 v[226:227], off
	s_waitcnt vmcnt(8)
	s_waitcnt lgkmcnt(0)
	s_barrier
; #define PG8_STAGE(bufoff, gbase, voff) do { _Pragma("unroll") for (int _i = 0; _i < 2; ++_i) \
;         __builtin_amdgcn_global_load_lds((const unsigned*)((const char*)(gbase) + (voff)[_i]), (PG8_LAS unsigned*)(lds + (bufoff) + ldsw + _i * 8192), 16, 0, 0); } while (0)
; #define PG8_LDA(dst, b, h) do { _Pragma("unroll") for (int m = 0; m < 4; ++m) _Pragma("unroll") for (int k = 0; k < 2; ++k) dst[m][k] = *(const PG8_LAS bf16x8*)(lds + PG8_SA(b, h) + aoff + m * 2048 + k * 1024); } while (0)
; #define PG8_LDB(dst, b, h) do { _Pragma("unroll") for (int n = 0; n < 2; ++n) _Pragma("unroll") for (int k = 0; k < 2; ++k) dst[n][k] = *(const PG8_LAS bf16x8*)(lds + PG8_SB(b, h) + boff + n * 2048 + k * 1024); } while (0)
; #define PG8_MMA(ai, bj, At, Bt) do { __builtin_amdgcn_s_setprio(1); _Pragma("unroll") for (int m = 0; m < 4; ++m) _Pragma("unroll") for (int n = 0; n < 2; ++n) _Pragma("unroll") for (int k = 0; k < 2; ++k) \
;         acc[ai][bj][m][n] = __builtin_amdgcn_mfma_f32_16x16x32_bf16(Bt[n][k], At[m][k], acc[ai][bj][m][n], 0, 0, 0); __builtin_amdgcn_s_setprio(0); } while (0)
; #define PG8_WAIT_V(n) asm volatile("s_waitcnt vmcnt(" #n ")" ::: "memory")
; #define PG8_WAIT_L(n) asm volatile("s_waitcnt lgkmcnt(" #n ")" ::: "memory")
; #define PG8_BAR __builtin_amdgcn_s_barrier()
; #define PG8_SCHED __builtin_amdgcn_sched_barrier(0)
; template <class Epi, class Sched, bool ALIGN_EPI = false, bool SP2 = false>
; __device__ __forceinline__ void gemm_phase(PG8_LAS unsigned char* lds, const Gemm g, const Sched& S, const Epi& E, int wave_s) {
;     ...
;             PG8_WAIT_V(8); PG8_WAIT_L(0); PG8_BAR; PG8_MMA(1, 0, At, B0); PG8_MMA(1, 1, At, B1); PG8_BAR; PG8_SCHED;
;             PG8_LDB(B0, 1, 0); PG8_LDB(B1, 1, 1); PG8_SCHED; PG8_LDA(At, 1, 0); PG8_STAGE(PG8_SA(0, 1), a2 + hstep, voffA);
;             PG8_WAIT_V(8); PG8_WAIT_L(0); PG8_BAR; PG8_MMA(0, 0, At, B0); PG8_MMA(0, 1, At, B1); PG8_BAR; PG8_SCHED;
	s_setprio 1
	s_waitcnt lgkmcnt(0)
	v_mfma_f32_16x16x32_bf16 v[76:79], v[56:59], v[192:195], v[76:79]
	v_mfma_f32_16x16x32_bf16 v[72:75], v[168:171], v[192:195], v[72:75]
	v_mfma_f32_16x16x32_bf16 v[44:47], v[56:59], v[200:203], v[44:47]
	v_mfma_f32_16x16x32_bf16 v[40:43], v[168:171], v[200:203], v[40:43]
	v_mfma_f32_16x16x32_bf16 v[28:31], v[56:59], v[208:211], v[28:31]
	v_mfma_f32_16x16x32_bf16 v[24:27], v[168:171], v[208:211], v[24:27]
	v_mfma_f32_16x16x32_bf16 v[12:15], v[56:59], v[216:219], v[12:15]
	v_mfma_f32_16x16x32_bf16 v[8:11], v[168:171], v[216:219], v[8:11]
	v_mfma_f32_16x16x32_bf16 v[76:79], v[60:63], v[196:199], v[76:79]
	v_mfma_f32_16x16x32_bf16 v[72:75], v[172:175], v[196:199], v[72:75]
	v_mfma_f32_16x16x32_bf16 v[44:47], v[60:63], v[204:207], v[44:47]
	v_mfma_f32_16x16x32_bf16 v[40:43], v[172:175], v[204:207], v[40:43]
	v_mfma_f32_16x16x32_bf16 v[28:31], v[60:63], v[212:215], v[28:31]
	v_mfma_f32_16x16x32_bf16 v[24:27], v[172:175], v[212:215], v[24:27]
	v_mfma_f32_16x16x32_bf16 v[12:15], v[60:63], v[220:223], v[12:15]
	v_mfma_f32_16x16x32_bf16 v[8:11], v[172:175], v[220:223], v[8:11]
	s_setprio 0
	s_setprio 1
	v_mfma_f32_16x16x32_bf16 v[36:39], v[176:179], v[200:203], v[36:39]
	v_mfma_f32_16x16x32_bf16 v[32:35], v[184:187], v[200:203], v[32:35]
	v_mfma_f32_16x16x32_bf16 v[20:23], v[176:179], v[208:211], v[20:23]
	v_mfma_f32_16x16x32_bf16 v[16:19], v[184:187], v[208:211], v[16:19]
	v_mfma_f32_16x16x32_bf16 v[4:7], v[176:179], v[216:219], v[4:7]
	v_mfma_f32_16x16x32_bf16 v[0:3], v[184:187], v[216:219], v[0:3]
	v_mfma_f32_16x16x32_bf16 v[56:59], v[176:179], v[192:195], v[68:71]
	v_mfma_f32_16x16x32_bf16 v[60:63], v[184:187], v[192:195], v[64:67]
	v_mfma_f32_16x16x32_bf16 v[36:39], v[180:183], v[204:207], v[36:39]
	v_mfma_f32_16x16x32_bf16 v[32:35], v[188:191], v[204:207], v[32:35]
	v_mfma_f32_16x16x32_bf16 v[20:23], v[180:183], v[212:215], v[20:23]
	v_mfma_f32_16x16x32_bf16 v[16:19], v[188:191], v[212:215], v[16:19]
	v_mfma_f32_16x16x32_bf16 v[4:7], v[180:183], v[220:223], v[4:7]
	v_mfma_f32_16x16x32_bf16 v[0:3], v[188:191], v[220:223], v[0:3]
	v_mfma_f32_16x16x32_bf16 v[56:59], v[180:183], v[196:199], v[56:59]
	v_mfma_f32_16x16x32_bf16 v[60:63], v[188:191], v[196:199], v[60:63]
	s_setprio 0
	s_barrier
	s_add_i32 s57, 0, 0x18000
	v_add_u32_e32 v152, s57, v157
	s_add_i32 s58, 0, 0x1c000
	ds_read_b128 v[64:67], v152
	ds_read_b128 v[68:71], v152 offset:1024
	ds_read_b128 v[168:171], v152 offset:2048
	ds_read_b128 v[172:175], v152 offset:3072
	v_add_u32_e32 v152, s58, v157
	ds_read_b128 v[176:179], v152
	ds_read_b128 v[180:183], v152 offset:1024
	ds_read_b128 v[184:187], v152 offset:2048
	ds_read_b128 v[188:191], v152 offset:3072
	s_add_u32 s36, s36, 0x80000
	s_addc_u32 s37, s37, 0
	s_mov_b32 m0, s41
	v_lshl_add_u64 v[228:229], s[36:37], 0, v[136:137]
	ds_read_b128 v[192:195], v167 offset:32768
	ds_read_b128 v[196:199], v167 offset:33792
	ds_read_b128 v[200:203], v167 offset:34816
	ds_read_b128 v[204:207], v167 offset:35840
	ds_read_b128 v[208:211], v167 offset:36864
	ds_read_b128 v[212:215], v167 offset:37888
	ds_read_b128 v[216:219], v167 offset:38912
	ds_read_b128 v[220:223], v167 offset:39936
	global_load_lds_dwordx4 v[228:229], off
	v_lshl_add_u64 v[228:229], s[36:37], 0, v[140:141]
	s_mov_b32 m0, s42
	s_nop 0
	global_load_lds_dwordx4 v[228:229], off
	s_waitcnt vmcnt(8)
	s_waitcnt lgkmcnt(0)
	s_barrier
	s_setprio 1
	s_waitcnt lgkmcnt(0)
	v_mfma_f32_16x16x32_bf16 v[52:55], v[64:67], v[192:195], v[52:55]
	v_mfma_f32_16x16x32_bf16 v[48:51], v[168:171], v[192:195], v[48:51]
	v_mfma_f32_16x16x32_bf16 v[124:127], v[64:67], v[200:203], v[124:127]
	v_mfma_f32_16x16x32_bf16 v[120:123], v[168:171], v[200:203], v[120:123]
	v_mfma_f32_16x16x32_bf16 v[108:111], v[64:67], v[208:211], v[108:111]
	v_mfma_f32_16x16x32_bf16 v[104:107], v[168:171], v[208:211], v[104:107]
	v_mfma_f32_16x16x32_bf16 v[92:95], v[64:67], v[216:219], v[92:95]
	v_mfma_f32_16x16x32_bf16 v[88:91], v[168:171], v[216:219], v[88:91]
	v_mfma_f32_16x16x32_bf16 v[52:55], v[68:71], v[196:199], v[52:55]
	v_mfma_f32_16x16x32_bf16 v[48:51], v[172:175], v[196:199], v[48:51]
	v_mfma_f32_16x16x32_bf16 v[124:127], v[68:71], v[204:207], v[124:127]
	v_mfma_f32_16x16x32_bf16 v[120:123], v[172:175], v[204:207], v[120:123]
	v_mfma_f32_16x16x32_bf16 v[108:111], v[68:71], v[212:215], v[108:111]
	v_mfma_f32_16x16x32_bf16 v[104:107], v[172:175], v[212:215], v[104:107]
	v_mfma_f32_16x16x32_bf16 v[92:95], v[68:71], v[220:223], v[92:95]
	v_mfma_f32_16x16x32_bf16 v[88:91], v[172:175], v[220:223], v[88:91]
	s_setprio 0
	s_setprio 1
	v_mfma_f32_16x16x32_bf16 v[132:135], v[176:179], v[192:195], v[132:135]
	v_mfma_f32_16x16x32_bf16 v[128:131], v[184:187], v[192:195], v[128:131]
	v_mfma_f32_16x16x32_bf16 v[116:119], v[176:179], v[200:203], v[116:119]
	v_mfma_f32_16x16x32_bf16 v[112:115], v[184:187], v[200:203], v[112:115]
	v_mfma_f32_16x16x32_bf16 v[100:103], v[176:179], v[208:211], v[100:103]
	v_mfma_f32_16x16x32_bf16 v[96:99], v[184:187], v[208:211], v[96:99]
	v_mfma_f32_16x16x32_bf16 v[84:87], v[176:179], v[216:219], v[84:87]
	v_mfma_f32_16x16x32_bf16 v[80:83], v[184:187], v[216:219], v[80:83]
	v_mfma_f32_16x16x32_bf16 v[132:135], v[180:183], v[196:199], v[132:135]
	v_mfma_f32_16x16x32_bf16 v[128:131], v[188:191], v[196:199], v[128:131]
	v_mfma_f32_16x16x32_bf16 v[116:119], v[180:183], v[204:207], v[116:119]
	v_mfma_f32_16x16x32_bf16 v[112:115], v[188:191], v[204:207], v[112:115]
	v_mfma_f32_16x16x32_bf16 v[100:103], v[180:183], v[212:215], v[100:103]
	v_mfma_f32_16x16x32_bf16 v[96:99], v[188:191], v[212:215], v[96:99]
	v_mfma_f32_16x16x32_bf16 v[84:87], v[180:183], v[220:223], v[84:87]
	v_mfma_f32_16x16x32_bf16 v[80:83], v[188:191], v[220:223], v[80:83]
	s_setprio 0
	s_barrier
; #define PG8_STAGE(bufoff, gbase, voff) do { _Pragma("unroll") for (int _i = 0; _i < 2; ++_i) \
;         __builtin_amdgcn_global_load_lds((const unsigned*)((const char*)(gbase) + (voff)[_i]), (PG8_LAS unsigned*)(lds + (bufoff) + ldsw + _i * 8192), 16, 0, 0); } while (0)
; #define PG8_LDA(dst, b, h) do { _Pragma("unroll") for (int m = 0; m < 4; ++m) _Pragma("unroll") for (int k = 0; k < 2; ++k) dst[m][k] = *(const PG8_LAS bf16x8*)(lds + PG8_SA(b, h) + aoff + m * 2048 + k * 1024); } while (0)
; #define PG8_MMA(ai, bj, At, Bt) do { __builtin_amdgcn_s_setprio(1); _Pragma("unroll") for (int m = 0; m < 4; ++m) _Pragma("unroll") for (int n = 0; n < 2; ++n) _Pragma("unroll") for (int k = 0; k < 2; ++k) \
;         acc[ai][bj][m][n] = __builtin_amdgcn_mfma_f32_16x16x32_bf16(Bt[n][k], At[m][k], acc[ai][bj][m][n], 0, 0, 0); __builtin_amdgcn_s_setprio(0); } while (0)
; #define PG8_WAIT_V(n) asm volatile("s_waitcnt vmcnt(" #n ")" ::: "memory")
; #define PG8_WAIT_L(n) asm volatile("s_waitcnt lgkmcnt(" #n ")" ::: "memory")
; #define PG8_BAR __builtin_amdgcn_s_barrier()
; #define PG8_SCHED __builtin_amdgcn_sched_barrier(0)
; template <class Epi, class Sched, bool ALIGN_EPI = false, bool SP2 = false>
; __device__ __forceinline__ void gemm_phase(PG8_LAS unsigned char* lds, const Gemm g, const Sched& S, const Epi& E, int wave_s) {
;     ...
;         for (int t = 0; t < nt; t += 2) {
;             const bool last = (t == nt - 2);
;     ...
;             PG8_LDA(At, 1, 1); PG8_STAGE(PG8_SB(1, 0), b3, voffB); PG8_STAGE(PG8_SB(1, 1), b3 + hstep, voffB); PG8_STAGE(PG8_SA(1, 0), a3, voffA);
;             PG8_WAIT_V(8); PG8_WAIT_L(0); PG8_BAR; PG8_MMA(1, 0, At, B0); PG8_MMA(1, 1, At, B1); PG8_BAR; PG8_SCHED;
	s_add_i32 s36, s57, s39
	v_lshl_add_u64 v[154:155], v[154:155], 0, s[6:7]
	s_mov_b32 m0, s36
	ds_read_b128 v[192:195], v167 offset:49152
	ds_read_b128 v[196:199], v167 offset:50176
	ds_read_b128 v[200:203], v167 offset:51200
	ds_read_b128 v[204:207], v167 offset:52224
	ds_read_b128 v[208:211], v167 offset:53248
	ds_read_b128 v[212:215], v167 offset:54272
	ds_read_b128 v[216:219], v167 offset:55296
	ds_read_b128 v[220:223], v167 offset:56320
	global_load_lds_dwordx4 v[154:155], off
	s_add_i32 m0, s36, 0x2000
	s_add_u32 s34, s34, 0x80080
	v_lshl_add_u64 v[154:155], v[164:165], 0, s[6:7]
	s_addc_u32 s35, s35, 0
	s_add_i32 s36, s58, s39
	global_load_lds_dwordx4 v[154:155], off
	v_lshl_add_u64 v[154:155], s[34:35], 0, v[138:139]
	s_mov_b32 m0, s36
	s_nop 0
	global_load_lds_dwordx4 v[154:155], off
	v_lshl_add_u64 v[154:155], s[34:35], 0, v[142:143]
	s_add_i32 m0, s36, 0x2000
	s_nop 0
	global_load_lds_dwordx4 v[154:155], off
	v_lshl_add_u64 v[154:155], v[224:225], 0, s[6:7]
	s_mov_b32 m0, s44
	s_nop 0
	global_load_lds_dwordx4 v[154:155], off
	v_lshl_add_u64 v[154:155], v[226:227], 0, s[6:7]
	s_mov_b32 m0, s45
	s_nop 0
	global_load_lds_dwordx4 v[154:155], off
	s_waitcnt vmcnt(8)
	s_waitcnt lgkmcnt(0)
	s_barrier
	s_setprio 1
	s_waitcnt lgkmcnt(0)
	v_mfma_f32_16x16x32_bf16 v[76:79], v[64:67], v[192:195], v[76:79]
	v_mfma_f32_16x16x32_bf16 v[72:75], v[168:171], v[192:195], v[72:75]
	v_mfma_f32_16x16x32_bf16 v[44:47], v[64:67], v[200:203], v[44:47]
	v_mfma_f32_16x16x32_bf16 v[40:43], v[168:171], v[200:203], v[40:43]
	v_mfma_f32_16x16x32_bf16 v[28:31], v[64:67], v[208:211], v[28:31]
	v_mfma_f32_16x16x32_bf16 v[24:27], v[168:171], v[208:211], v[24:27]
	v_mfma_f32_16x16x32_bf16 v[12:15], v[64:67], v[216:219], v[12:15]
	v_mfma_f32_16x16x32_bf16 v[8:11], v[168:171], v[216:219], v[8:11]
	v_mfma_f32_16x16x32_bf16 v[76:79], v[68:71], v[196:199], v[76:79]
	v_mfma_f32_16x16x32_bf16 v[72:75], v[172:175], v[196:199], v[72:75]
	v_mfma_f32_16x16x32_bf16 v[44:47], v[68:71], v[204:207], v[44:47]
	v_mfma_f32_16x16x32_bf16 v[40:43], v[172:175], v[204:207], v[40:43]
	v_mfma_f32_16x16x32_bf16 v[28:31], v[68:71], v[212:215], v[28:31]
	v_mfma_f32_16x16x32_bf16 v[24:27], v[172:175], v[212:215], v[24:27]
	v_mfma_f32_16x16x32_bf16 v[12:15], v[68:71], v[220:223], v[12:15]
	v_mfma_f32_16x16x32_bf16 v[8:11], v[172:175], v[220:223], v[8:11]
	s_setprio 0
	s_setprio 1
	v_mfma_f32_16x16x32_bf16 v[56:59], v[176:179], v[192:195], v[56:59]
	v_mfma_f32_16x16x32_bf16 v[68:71], v[180:183], v[196:199], v[56:59]
	v_mfma_f32_16x16x32_bf16 v[56:59], v[184:187], v[192:195], v[60:63]
	v_mfma_f32_16x16x32_bf16 v[36:39], v[176:179], v[200:203], v[36:39]
	v_mfma_f32_16x16x32_bf16 v[32:35], v[184:187], v[200:203], v[32:35]
	v_mfma_f32_16x16x32_bf16 v[20:23], v[176:179], v[208:211], v[20:23]
	v_mfma_f32_16x16x32_bf16 v[16:19], v[184:187], v[208:211], v[16:19]
	v_mfma_f32_16x16x32_bf16 v[4:7], v[176:179], v[216:219], v[4:7]
	v_mfma_f32_16x16x32_bf16 v[0:3], v[184:187], v[216:219], v[0:3]
	v_mfma_f32_16x16x32_bf16 v[64:67], v[188:191], v[196:199], v[56:59]
	v_mfma_f32_16x16x32_bf16 v[36:39], v[180:183], v[204:207], v[36:39]
	v_mfma_f32_16x16x32_bf16 v[32:35], v[188:191], v[204:207], v[32:35]
	v_mfma_f32_16x16x32_bf16 v[20:23], v[180:183], v[212:215], v[20:23]
	v_mfma_f32_16x16x32_bf16 v[16:19], v[188:191], v[212:215], v[16:19]
	v_mfma_f32_16x16x32_bf16 v[4:7], v[180:183], v[220:223], v[4:7]
	v_mfma_f32_16x16x32_bf16 v[0:3], v[188:191], v[220:223], v[0:3]
	s_add_i32 s56, s56, 2
	s_add_u32 s30, s30, 0x100
	s_addc_u32 s31, s31, 0
	s_add_u32 s52, s52, 0x100
	s_addc_u32 s53, s53, 0
	s_cmp_gt_u32 s56, 29
	s_setprio 0
	s_barrier
	s_cbranch_scc0 .LBB0_1498
	s_and_b64 vcc, exec, s[8:9]
	s_cbranch_vccz .LBB0_1501
	s_barrier
